# MMA segments: no-op lgkmcnt ladder and back-to-back setprio pair removed (on top of merge-epilogue load batching)
# speedup vs baseline: 1.0141x; 1.0065x over previous
; #define PG8_WAIT_V(n) asm volatile("s_waitcnt vmcnt(" #n ")" ::: "memory")
; template <class Epi, bool ALIGN_EPI, bool SP2, class Hook>
; __device__ __forceinline__ void gemm_phase(LAS unsigned char* lds, const Gemm g, const StaticOrder& S, const Epi& E, Acc& acc, const bool fresh, const Hook& H, const int wave_id) {
;     ...
;         if constexpr (SP2 && Epi::NSTORE > 0) {
;             const Src a1 = cA + kstep, a2 = cA + 2 * kstep, b2 = cB + 2 * kstep, a3 = a2 + kstep, b3 = b2 + kstep;
;             if constexpr (Epi::NSTORE == 16) PG8_TRIP_SP2(PG8_WAIT_V(24)); else PG8_TRIP_SP2(PG8_WAIT_V(16));
;             t0 = 2;
.LBB0_382:
	ds_read_b128 v[2:5], v150
	ds_read_b128 v[6:9], v150 offset:1024
	ds_read_b128 v[10:13], v150 offset:2048
	ds_read_b128 v[14:17], v150 offset:3072
	ds_read_b128 v[18:21], v151
	ds_read_b128 v[22:25], v151 offset:1024
	ds_read_b128 v[26:29], v151 offset:2048
	ds_read_b128 v[30:33], v151 offset:3072
	s_or_b32 s9, s68, 0x100
	s_or_b32 s8, s68, 0x180
	s_or_b32 s10, s69, 0x100
	s_or_b32 s11, s68, 0x40080
	s_mov_b32 m0, s45
	ds_read_b128 v[34:37], v149
	ds_read_b128 v[38:41], v149 offset:1024
	ds_read_b128 v[42:45], v149 offset:2048
	ds_read_b128 v[46:49], v149 offset:3072
	ds_read_b128 v[50:53], v149 offset:4096
	ds_read_b128 v[54:57], v149 offset:5120
	ds_read_b128 v[58:61], v149 offset:6144
	ds_read_b128 v[62:65], v149 offset:7168
	buffer_load_dwordx4 v144, s[0:3], s11 offen lds
	s_mov_b32 m0, s46
	s_nop 0
	buffer_load_dwordx4 v146, s[0:3], s11 offen lds
	s_waitcnt vmcnt(24)
	s_waitcnt lgkmcnt(0)
	s_barrier
	s_setprio 1
	v_mfma_f32_16x16x32_bf16 v[86:89], v[10:13], v[50:53], 0
	v_mfma_f32_16x16x32_bf16 v[92:95], v[14:17], v[54:57], v[86:89]
	v_mfma_f32_16x16x32_bf16 v[86:89], v[2:5], v[58:61], 0
	v_mfma_f32_16x16x32_bf16 v[66:69], v[2:5], v[34:37], 0
	v_mfma_f32_16x16x32_bf16 v[70:73], v[10:13], v[34:37], 0
	v_mfma_f32_16x16x32_bf16 v[74:77], v[2:5], v[42:45], 0
	v_mfma_f32_16x16x32_bf16 v[78:81], v[10:13], v[42:45], 0
	v_mfma_f32_16x16x32_bf16 v[82:85], v[2:5], v[50:53], 0
	v_mfma_f32_16x16x32_bf16 v[96:99], v[6:9], v[62:65], v[86:89]
	v_mfma_f32_16x16x32_bf16 v[86:89], v[10:13], v[58:61], 0
	v_mfma_f32_16x16x32_bf16 v[66:69], v[6:9], v[38:41], v[66:69]
	v_mfma_f32_16x16x32_bf16 v[70:73], v[14:17], v[38:41], v[70:73]
	v_mfma_f32_16x16x32_bf16 v[74:77], v[6:9], v[46:49], v[74:77]
	v_mfma_f32_16x16x32_bf16 v[78:81], v[14:17], v[46:49], v[78:81]
	v_mfma_f32_16x16x32_bf16 v[82:85], v[6:9], v[54:57], v[82:85]
	v_mfma_f32_16x16x32_bf16 v[104:107], v[14:17], v[62:65], v[86:89]
	v_mfma_f32_16x16x32_bf16 v[86:89], v[18:21], v[34:37], 0
	v_mfma_f32_16x16x32_bf16 v[34:37], v[26:29], v[34:37], 0
	v_mfma_f32_16x16x32_bf16 v[116:119], v[30:33], v[38:41], v[34:37]
	v_mfma_f32_16x16x32_bf16 v[34:37], v[18:21], v[42:45], 0
	v_mfma_f32_16x16x32_bf16 v[132:135], v[22:25], v[46:49], v[34:37]
	v_mfma_f32_16x16x32_bf16 v[34:37], v[26:29], v[42:45], 0
	v_mfma_f32_16x16x32_bf16 v[108:111], v[22:25], v[38:41], v[86:89]
	v_mfma_f32_16x16x32_bf16 v[40:43], v[30:33], v[46:49], v[34:37]
	v_mfma_f32_16x16x32_bf16 v[34:37], v[18:21], v[50:53], 0
	v_mfma_f32_16x16x32_bf16 v[44:47], v[22:25], v[54:57], v[34:37]
	v_mfma_f32_16x16x32_bf16 v[34:37], v[26:29], v[50:53], 0
	v_mfma_f32_16x16x32_bf16 v[48:51], v[30:33], v[54:57], v[34:37]
	v_mfma_f32_16x16x32_bf16 v[34:37], v[18:21], v[58:61], 0
	v_mfma_f32_16x16x32_bf16 v[52:55], v[22:25], v[62:65], v[34:37]
	v_mfma_f32_16x16x32_bf16 v[34:37], v[26:29], v[58:61], 0
	v_mfma_f32_16x16x32_bf16 v[60:63], v[30:33], v[62:65], v[34:37]
	s_setprio 0
	s_barrier
	s_mov_b32 m0, s92
	s_nop 3
	ds_read_b128 v[34:37], v149 offset:16384
	ds_read_b128 v[56:59], v149 offset:17408
	ds_read_b128 v[86:89], v149 offset:18432
	ds_read_b128 v[100:103], v149 offset:19456
	ds_read_b128 v[112:115], v149 offset:20480
	ds_read_b128 v[120:123], v149 offset:21504
	ds_read_b128 v[124:127], v149 offset:22528
	ds_read_b128 v[128:131], v149 offset:23552
	buffer_load_dwordx4 v145, s[4:7], s10 offen lds
	s_mov_b32 m0, s93
	s_nop 0
	buffer_load_dwordx4 v147, s[4:7], s10 offen lds
	s_or_b32 s10, s69, 0x40100
	s_mov_b32 m0, s94
	s_nop 0
	buffer_load_dwordx4 v145, s[4:7], s10 offen lds
	s_mov_b32 m0, s95
	s_nop 0
	buffer_load_dwordx4 v147, s[4:7], s10 offen lds
	s_mov_b32 m0, s44
	s_nop 0
	buffer_load_dwordx4 v144, s[0:3], s9 offen lds
	s_mov_b32 m0, s36
	s_nop 0
	buffer_load_dwordx4 v146, s[0:3], s9 offen lds
	s_waitcnt vmcnt(24)
	s_waitcnt lgkmcnt(0)
	s_barrier
	s_setprio 1
	v_mfma_f32_16x16x32_bf16 v[136:139], v[2:5], v[34:37], 0
	v_mfma_f32_16x16x32_bf16 v[154:157], v[2:5], v[86:89], 0
	v_mfma_f32_16x16x32_bf16 v[162:165], v[2:5], v[112:115], 0
	v_mfma_f32_16x16x32_bf16 v[2:5], v[2:5], v[124:127], 0
	v_mfma_f32_16x16x32_bf16 v[136:139], v[6:9], v[56:59], v[136:139]
	v_mfma_f32_16x16x32_bf16 v[140:143], v[10:13], v[34:37], 0
	v_mfma_f32_16x16x32_bf16 v[154:157], v[6:9], v[100:103], v[154:157]
	v_mfma_f32_16x16x32_bf16 v[158:161], v[10:13], v[86:89], 0
	v_mfma_f32_16x16x32_bf16 v[162:165], v[6:9], v[120:123], v[162:165]
	v_mfma_f32_16x16x32_bf16 v[166:169], v[10:13], v[112:115], 0
	v_mfma_f32_16x16x32_bf16 v[2:5], v[6:9], v[128:131], v[2:5]
	v_mfma_f32_16x16x32_bf16 v[6:9], v[10:13], v[124:127], 0
	v_mfma_f32_16x16x32_bf16 v[140:143], v[14:17], v[56:59], v[140:143]
	v_mfma_f32_16x16x32_bf16 v[158:161], v[14:17], v[100:103], v[158:161]
	v_mfma_f32_16x16x32_bf16 v[166:169], v[14:17], v[120:123], v[166:169]
	v_mfma_f32_16x16x32_bf16 v[170:173], v[14:17], v[128:131], v[6:9]
	v_mfma_f32_16x16x32_bf16 v[6:9], v[18:21], v[34:37], 0
	v_mfma_f32_16x16x32_bf16 v[174:177], v[22:25], v[56:59], v[6:9]
	v_mfma_f32_16x16x32_bf16 v[6:9], v[26:29], v[34:37], 0
	v_mfma_f32_16x16x32_bf16 v[178:181], v[30:33], v[56:59], v[6:9]
	v_mfma_f32_16x16x32_bf16 v[6:9], v[18:21], v[86:89], 0
	v_mfma_f32_16x16x32_bf16 v[182:185], v[22:25], v[100:103], v[6:9]
	v_mfma_f32_16x16x32_bf16 v[6:9], v[26:29], v[86:89], 0
	v_mfma_f32_16x16x32_bf16 v[186:189], v[30:33], v[100:103], v[6:9]
	v_mfma_f32_16x16x32_bf16 v[6:9], v[18:21], v[112:115], 0
	v_mfma_f32_16x16x32_bf16 v[190:193], v[22:25], v[120:123], v[6:9]
	v_mfma_f32_16x16x32_bf16 v[6:9], v[26:29], v[112:115], 0
	v_mfma_f32_16x16x32_bf16 v[212:215], v[30:33], v[120:123], v[6:9]
	v_mfma_f32_16x16x32_bf16 v[6:9], v[18:21], v[124:127], 0
	v_mfma_f32_16x16x32_bf16 v[20:23], v[22:25], v[128:131], v[6:9]
	v_mfma_f32_16x16x32_bf16 v[6:9], v[26:29], v[124:127], 0
	v_mfma_f32_16x16x32_bf16 v[216:219], v[30:33], v[128:131], v[6:9]
	s_setprio 0
	s_barrier
; #define PG8_WAIT_V(n) asm volatile("s_waitcnt vmcnt(" #n ")" ::: "memory")
; template <class Epi, bool ALIGN_EPI, bool SP2, class Hook>
; __device__ __forceinline__ void gemm_phase(LAS unsigned char* lds, const Gemm g, const StaticOrder& S, const Epi& E, Acc& acc, const bool fresh, const Hook& H, const int wave_id) {
;     ...
;         if constexpr (SP2 && Epi::NSTORE > 0) {
;             const Src a1 = cA + kstep, a2 = cA + 2 * kstep, b2 = cB + 2 * kstep, a3 = a2 + kstep, b3 = b2 + kstep;
;             if constexpr (Epi::NSTORE == 16) PG8_TRIP_SP2(PG8_WAIT_V(24)); else PG8_TRIP_SP2(PG8_WAIT_V(16));
;             t0 = 2;
	s_nop 4
	ds_read_b128 v[6:9], v152
	ds_read_b128 v[24:27], v152 offset:1024
	ds_read_b128 v[228:231], v152 offset:2048
	ds_read_b128 v[232:235], v152 offset:3072
	ds_read_b128 v[236:239], v153
	ds_read_b128 v[240:243], v153 offset:1024
	ds_read_b128 v[244:247], v153 offset:2048
	ds_read_b128 v[150:153], v153 offset:3072
	s_or_b32 s9, s68, 0x40100
	s_mov_b32 m0, s37
	ds_read_b128 v[10:13], v149 offset:32768
	ds_read_b128 v[14:17], v149 offset:33792
	ds_read_b128 v[32:35], v149 offset:34816
	ds_read_b128 v[194:197], v149 offset:35840
	ds_read_b128 v[208:211], v149 offset:36864
	ds_read_b128 v[200:203], v149 offset:37888
	ds_read_b128 v[204:207], v149 offset:38912
	ds_read_b128 v[220:223], v149 offset:39936
	buffer_load_dwordx4 v144, s[0:3], s9 offen lds
	s_mov_b32 m0, s38
	s_nop 0
	buffer_load_dwordx4 v146, s[0:3], s9 offen lds
	s_waitcnt vmcnt(8)
	s_waitcnt lgkmcnt(0)
	s_barrier
	s_setprio 1
	v_mfma_f32_16x16x32_bf16 v[28:31], v[6:9], v[10:13], v[66:69]
	v_mfma_f32_16x16x32_bf16 v[120:123], v[24:27], v[14:17], v[28:31]
	v_mfma_f32_16x16x32_bf16 v[28:31], v[228:231], v[10:13], v[70:73]
	v_mfma_f32_16x16x32_bf16 v[112:115], v[232:235], v[14:17], v[28:31]
	v_mfma_f32_16x16x32_bf16 v[28:31], v[6:9], v[32:35], v[74:77]
	v_mfma_f32_16x16x32_bf16 v[100:103], v[24:27], v[194:197], v[28:31]
	v_mfma_f32_16x16x32_bf16 v[28:31], v[228:231], v[32:35], v[78:81]
	v_mfma_f32_16x16x32_bf16 v[88:91], v[232:235], v[194:197], v[28:31]
	v_mfma_f32_16x16x32_bf16 v[28:31], v[6:9], v[208:211], v[82:85]
	v_mfma_f32_16x16x32_bf16 v[68:71], v[24:27], v[200:203], v[28:31]
	v_mfma_f32_16x16x32_bf16 v[28:31], v[228:231], v[208:211], v[92:95]
	v_mfma_f32_16x16x32_bf16 v[56:59], v[232:235], v[200:203], v[28:31]
	v_mfma_f32_16x16x32_bf16 v[28:31], v[6:9], v[204:207], v[96:99]
	v_mfma_f32_16x16x32_bf16 v[36:39], v[24:27], v[220:223], v[28:31]
	v_mfma_f32_16x16x32_bf16 v[28:31], v[228:231], v[204:207], v[104:107]
	v_mfma_f32_16x16x32_bf16 v[28:31], v[232:235], v[220:223], v[28:31]
	v_mfma_f32_16x16x32_bf16 v[64:67], v[236:239], v[10:13], v[108:111]
	v_mfma_f32_16x16x32_bf16 v[10:13], v[244:247], v[10:13], v[116:119]
	v_mfma_f32_16x16x32_bf16 v[124:127], v[150:153], v[14:17], v[10:13]
	v_mfma_f32_16x16x32_bf16 v[10:13], v[236:239], v[32:35], v[132:135]
	v_mfma_f32_16x16x32_bf16 v[116:119], v[240:243], v[194:197], v[10:13]
	v_mfma_f32_16x16x32_bf16 v[10:13], v[244:247], v[32:35], v[40:43]
	v_mfma_f32_16x16x32_bf16 v[108:111], v[150:153], v[194:197], v[10:13]
	v_mfma_f32_16x16x32_bf16 v[10:13], v[236:239], v[208:211], v[44:47]
	v_mfma_f32_16x16x32_bf16 v[92:95], v[240:243], v[200:203], v[10:13]
	v_mfma_f32_16x16x32_bf16 v[10:13], v[244:247], v[208:211], v[48:51]
	v_mfma_f32_16x16x32_bf16 v[80:83], v[150:153], v[200:203], v[10:13]
	v_mfma_f32_16x16x32_bf16 v[10:13], v[236:239], v[204:207], v[52:55]
	v_mfma_f32_16x16x32_bf16 v[128:131], v[240:243], v[14:17], v[64:67]
	v_mfma_f32_16x16x32_bf16 v[64:67], v[240:243], v[220:223], v[10:13]
	v_mfma_f32_16x16x32_bf16 v[10:13], v[244:247], v[204:207], v[60:63]
	v_mfma_f32_16x16x32_bf16 v[48:51], v[150:153], v[220:223], v[10:13]
	s_setprio 0
	s_barrier
	s_mov_b32 m0, s39
	s_or_b32 s9, s69, 0x180
	ds_read_b128 v[44:47], v149 offset:49152
	ds_read_b128 v[52:55], v149 offset:50176
	ds_read_b128 v[76:79], v149 offset:51200
	ds_read_b128 v[132:135], v149 offset:52224
	ds_read_b128 v[194:197], v149 offset:53248
	ds_read_b128 v[200:203], v149 offset:54272
	ds_read_b128 v[204:207], v149 offset:55296
	ds_read_b128 v[208:211], v149 offset:56320
	buffer_load_dwordx4 v145, s[4:7], s9 offen lds
	s_mov_b32 m0, s40
	s_nop 0
	buffer_load_dwordx4 v147, s[4:7], s9 offen lds
	s_or_b32 s9, s69, 0x40180
	s_mov_b32 m0, s43
	s_nop 0
	buffer_load_dwordx4 v145, s[4:7], s9 offen lds
	s_mov_b32 m0, s42
	s_nop 0
	buffer_load_dwordx4 v147, s[4:7], s9 offen lds
	s_mov_b32 m0, s41
	s_nop 0
	buffer_load_dwordx4 v144, s[0:3], s8 offen lds
	s_mov_b32 m0, s33
	s_nop 0
	buffer_load_dwordx4 v146, s[0:3], s8 offen lds
	s_waitcnt vmcnt(8)
	s_waitcnt lgkmcnt(0)
	s_barrier
	s_setprio 1
	v_mfma_f32_16x16x32_bf16 v[10:13], v[6:9], v[44:47], v[136:139]
	v_mfma_f32_16x16x32_bf16 v[72:75], v[24:27], v[52:55], v[10:13]
	v_mfma_f32_16x16x32_bf16 v[10:13], v[228:231], v[44:47], v[140:143]
	v_mfma_f32_16x16x32_bf16 v[60:63], v[232:235], v[52:55], v[10:13]
	v_mfma_f32_16x16x32_bf16 v[10:13], v[6:9], v[76:79], v[154:157]
	v_mfma_f32_16x16x32_bf16 v[40:43], v[24:27], v[132:135], v[10:13]
	v_mfma_f32_16x16x32_bf16 v[10:13], v[228:231], v[76:79], v[158:161]
	v_mfma_f32_16x16x32_bf16 v[32:35], v[232:235], v[132:135], v[10:13]
	v_mfma_f32_16x16x32_bf16 v[10:13], v[6:9], v[194:197], v[162:165]
	v_mfma_f32_16x16x32_bf16 v[16:19], v[24:27], v[200:203], v[10:13]
	v_mfma_f32_16x16x32_bf16 v[10:13], v[228:231], v[194:197], v[166:169]
	v_mfma_f32_16x16x32_bf16 v[2:5], v[6:9], v[204:207], v[2:5]
	v_mfma_f32_16x16x32_bf16 v[12:15], v[232:235], v[200:203], v[10:13]
	v_mfma_f32_16x16x32_bf16 v[8:11], v[24:27], v[208:211], v[2:5]
	v_mfma_f32_16x16x32_bf16 v[2:5], v[228:231], v[204:207], v[170:173]
	v_mfma_f32_16x16x32_bf16 v[4:7], v[232:235], v[208:211], v[2:5]
	v_mfma_f32_16x16x32_bf16 v[24:27], v[236:239], v[44:47], v[174:177]
	v_mfma_f32_16x16x32_bf16 v[96:99], v[240:243], v[52:55], v[24:27]
	v_mfma_f32_16x16x32_bf16 v[24:27], v[244:247], v[44:47], v[178:181]
	v_mfma_f32_16x16x32_bf16 v[104:107], v[150:153], v[52:55], v[24:27]
	v_mfma_f32_16x16x32_bf16 v[24:27], v[236:239], v[76:79], v[182:185]
	v_mfma_f32_16x16x32_bf16 v[84:87], v[240:243], v[132:135], v[24:27]
	v_mfma_f32_16x16x32_bf16 v[24:27], v[244:247], v[76:79], v[186:189]
	v_mfma_f32_16x16x32_bf16 v[76:79], v[150:153], v[132:135], v[24:27]
	v_mfma_f32_16x16x32_bf16 v[24:27], v[236:239], v[194:197], v[190:193]
	v_mfma_f32_16x16x32_bf16 v[52:55], v[240:243], v[200:203], v[24:27]
	v_mfma_f32_16x16x32_bf16 v[24:27], v[244:247], v[194:197], v[212:215]
	v_mfma_f32_16x16x32_bf16 v[20:23], v[236:239], v[204:207], v[20:23]
	v_mfma_f32_16x16x32_bf16 v[44:47], v[150:153], v[200:203], v[24:27]
	v_mfma_f32_16x16x32_bf16 v[24:27], v[240:243], v[208:211], v[20:23]
	v_mfma_f32_16x16x32_bf16 v[20:23], v[244:247], v[204:207], v[216:219]
	v_mfma_f32_16x16x32_bf16 v[20:23], v[150:153], v[208:211], v[20:23]
	s_setprio 0
	s_barrier
	s_mov_b64 s[8:9], 0
	v_mov_b64_e32 v[234:235], v[198:199]
	v_mov_b64_e32 v[236:237], v[226:227]
	v_mov_b32_e32 v198, v0
	v_mov_b32_e32 v226, v225
	v_mov_b64_e32 v[244:245], 0x100
	v_mov_b64_e32 v[246:247], 0xff

; #define PG8_WAIT_V(n) asm volatile("s_waitcnt vmcnt(" #n ")" ::: "memory")
; template <class Epi, bool ALIGN_EPI, bool SP2, class Hook>
; __device__ __forceinline__ void gemm_phase(LAS unsigned char* lds, const Gemm g, const StaticOrder& S, const Epi& E, Acc& acc, const bool fresh, const Hook& H, const int wave_id) {
;     ...
;         for (int t = t0; t < nt; t += 2) {
;             const bool last = (t == nt - 2);
;             const Src a1 = cA + (size_t)(t + 1) * kstep;
;             const Src a2 = last ? nA : cA + (size_t)(t + 2) * kstep, b2 = last ? nB : cB + (size_t)(t + 2) * kstep;
;             const Src a3 = a2 + kstep, b3 = b2 + kstep;
;             if (last && has_next) H(nxt);
;             if constexpr (SP2) {
;             PG8_TRIP_SP2(PG8_WAIT_V(8));
.LBB0_391:
	v_add_u32_e32 v150, 0x10000, v148
	v_add_u32_e32 v151, 0x14000, v148
	ds_read_b128 v[132:135], v150
	ds_read_b128 v[136:139], v150 offset:1024
	ds_read_b128 v[140:143], v150 offset:2048
	ds_read_b128 v[152:155], v150 offset:3072
	ds_read_b128 v[156:159], v151
	ds_read_b128 v[160:163], v151 offset:1024
	ds_read_b128 v[164:167], v151 offset:2048
	ds_read_b128 v[168:171], v151 offset:3072
	s_add_i32 s12, s56, 0xfffc0080
	s_cmp_eq_u32 s29, 12
	s_cselect_b32 s60, s68, s12
	s_cselect_b32 s13, s5, s77
	s_cselect_b32 s12, s4, s76
	s_cselect_b32 s15, s7, s55
	s_cselect_b32 s14, s6, s54
	s_cselect_b32 s58, s69, s57
	s_cselect_b32 s16, s0, s8
	s_cselect_b32 s17, s1, s9
	s_cselect_b32 s18, s2, s10
	s_cselect_b32 s19, s3, s11
	s_or_b32 s59, s60, 0x80
	s_mov_b32 m0, s45
	ds_read_b128 v[172:175], v149
	ds_read_b128 v[176:179], v149 offset:1024
	ds_read_b128 v[180:183], v149 offset:2048
	ds_read_b128 v[184:187], v149 offset:3072
	ds_read_b128 v[188:191], v149 offset:4096
	ds_read_b128 v[212:215], v149 offset:5120
	ds_read_b128 v[216:219], v149 offset:6144
	ds_read_b128 v[228:231], v149 offset:7168
	buffer_load_dwordx4 v144, s[8:11], s56 offen lds
	s_mov_b32 m0, s46
	s_nop 0
	buffer_load_dwordx4 v146, s[8:11], s56 offen lds
	s_waitcnt vmcnt(8)
	s_waitcnt lgkmcnt(0)
	s_barrier
	s_setprio 1
	v_mfma_f32_16x16x32_bf16 v[120:123], v[132:135], v[172:175], v[120:123]
	v_mfma_f32_16x16x32_bf16 v[112:115], v[140:143], v[172:175], v[112:115]
	v_mfma_f32_16x16x32_bf16 v[100:103], v[132:135], v[180:183], v[100:103]
	v_mfma_f32_16x16x32_bf16 v[88:91], v[140:143], v[180:183], v[88:91]
	v_mfma_f32_16x16x32_bf16 v[68:71], v[132:135], v[188:191], v[68:71]
	v_mfma_f32_16x16x32_bf16 v[56:59], v[140:143], v[188:191], v[56:59]
	v_mfma_f32_16x16x32_bf16 v[36:39], v[132:135], v[216:219], v[36:39]
	v_mfma_f32_16x16x32_bf16 v[28:31], v[140:143], v[216:219], v[28:31]
	v_mfma_f32_16x16x32_bf16 v[120:123], v[136:139], v[176:179], v[120:123]
	v_mfma_f32_16x16x32_bf16 v[112:115], v[152:155], v[176:179], v[112:115]
	v_mfma_f32_16x16x32_bf16 v[100:103], v[136:139], v[184:187], v[100:103]
	v_mfma_f32_16x16x32_bf16 v[88:91], v[152:155], v[184:187], v[88:91]
	v_mfma_f32_16x16x32_bf16 v[68:71], v[136:139], v[212:215], v[68:71]
	v_mfma_f32_16x16x32_bf16 v[56:59], v[152:155], v[212:215], v[56:59]
	v_mfma_f32_16x16x32_bf16 v[36:39], v[136:139], v[228:231], v[36:39]
	v_mfma_f32_16x16x32_bf16 v[28:31], v[152:155], v[228:231], v[28:31]
	v_mfma_f32_16x16x32_bf16 v[128:131], v[156:159], v[172:175], v[128:131]
	v_mfma_f32_16x16x32_bf16 v[124:127], v[164:167], v[172:175], v[124:127]
	v_mfma_f32_16x16x32_bf16 v[116:119], v[156:159], v[180:183], v[116:119]
	v_mfma_f32_16x16x32_bf16 v[108:111], v[164:167], v[180:183], v[108:111]
	v_mfma_f32_16x16x32_bf16 v[92:95], v[156:159], v[188:191], v[92:95]
	v_mfma_f32_16x16x32_bf16 v[80:83], v[164:167], v[188:191], v[80:83]
	v_mfma_f32_16x16x32_bf16 v[64:67], v[156:159], v[216:219], v[64:67]
	v_mfma_f32_16x16x32_bf16 v[48:51], v[164:167], v[216:219], v[48:51]
	v_mfma_f32_16x16x32_bf16 v[128:131], v[160:163], v[176:179], v[128:131]
	v_mfma_f32_16x16x32_bf16 v[124:127], v[168:171], v[176:179], v[124:127]
	v_mfma_f32_16x16x32_bf16 v[116:119], v[160:163], v[184:187], v[116:119]
	v_mfma_f32_16x16x32_bf16 v[108:111], v[168:171], v[184:187], v[108:111]
	v_mfma_f32_16x16x32_bf16 v[92:95], v[160:163], v[212:215], v[92:95]
	v_mfma_f32_16x16x32_bf16 v[80:83], v[168:171], v[212:215], v[80:83]
	v_mfma_f32_16x16x32_bf16 v[64:67], v[160:163], v[228:231], v[64:67]
	v_mfma_f32_16x16x32_bf16 v[48:51], v[168:171], v[228:231], v[48:51]
	s_setprio 0
	s_barrier
	s_mov_b32 m0, s92
	ds_read_b128 v[172:175], v149 offset:16384
	ds_read_b128 v[176:179], v149 offset:17408
	ds_read_b128 v[180:183], v149 offset:18432
	ds_read_b128 v[184:187], v149 offset:19456
	ds_read_b128 v[188:191], v149 offset:20480
	ds_read_b128 v[212:215], v149 offset:21504
	ds_read_b128 v[216:219], v149 offset:22528
	ds_read_b128 v[228:231], v149 offset:23552
	buffer_load_dwordx4 v145, s[12:15], s58 offen lds
	s_mov_b32 m0, s93
	s_add_i32 s61, s58, 0x40000
	buffer_load_dwordx4 v147, s[12:15], s58 offen lds
	s_mov_b32 m0, s94
	s_nop 0
	buffer_load_dwordx4 v145, s[12:15], s61 offen lds
	s_mov_b32 m0, s95
	s_nop 0
	buffer_load_dwordx4 v147, s[12:15], s61 offen lds
	s_mov_b32 m0, s44
	s_nop 0
	buffer_load_dwordx4 v144, s[16:19], s60 offen lds
	s_mov_b32 m0, s36
	s_nop 0
	buffer_load_dwordx4 v146, s[16:19], s60 offen lds
	s_waitcnt vmcnt(8)
	s_waitcnt lgkmcnt(0)
	s_barrier
	s_setprio 1
	v_mfma_f32_16x16x32_bf16 v[72:75], v[132:135], v[172:175], v[72:75]
	v_mfma_f32_16x16x32_bf16 v[60:63], v[140:143], v[172:175], v[60:63]
	v_mfma_f32_16x16x32_bf16 v[40:43], v[132:135], v[180:183], v[40:43]
	v_mfma_f32_16x16x32_bf16 v[32:35], v[140:143], v[180:183], v[32:35]
	v_mfma_f32_16x16x32_bf16 v[16:19], v[132:135], v[188:191], v[16:19]
	v_mfma_f32_16x16x32_bf16 v[12:15], v[140:143], v[188:191], v[12:15]
	v_mfma_f32_16x16x32_bf16 v[8:11], v[132:135], v[216:219], v[8:11]
	v_mfma_f32_16x16x32_bf16 v[2:5], v[140:143], v[216:219], v[4:7]
	v_mfma_f32_16x16x32_bf16 v[72:75], v[136:139], v[176:179], v[72:75]
	v_mfma_f32_16x16x32_bf16 v[60:63], v[152:155], v[176:179], v[60:63]
	v_mfma_f32_16x16x32_bf16 v[40:43], v[136:139], v[184:187], v[40:43]
	v_mfma_f32_16x16x32_bf16 v[32:35], v[152:155], v[184:187], v[32:35]
	v_mfma_f32_16x16x32_bf16 v[16:19], v[136:139], v[212:215], v[16:19]
	v_mfma_f32_16x16x32_bf16 v[12:15], v[152:155], v[212:215], v[12:15]
	v_mfma_f32_16x16x32_bf16 v[8:11], v[136:139], v[228:231], v[8:11]
	v_mfma_f32_16x16x32_bf16 v[2:5], v[152:155], v[228:231], v[2:5]
	v_mfma_f32_16x16x32_bf16 v[96:99], v[156:159], v[172:175], v[96:99]
	v_mfma_f32_16x16x32_bf16 v[104:107], v[164:167], v[172:175], v[104:107]
	v_mfma_f32_16x16x32_bf16 v[84:87], v[156:159], v[180:183], v[84:87]
	v_mfma_f32_16x16x32_bf16 v[76:79], v[164:167], v[180:183], v[76:79]
	v_mfma_f32_16x16x32_bf16 v[52:55], v[156:159], v[188:191], v[52:55]
	v_mfma_f32_16x16x32_bf16 v[44:47], v[164:167], v[188:191], v[44:47]
	v_mfma_f32_16x16x32_bf16 v[24:27], v[156:159], v[216:219], v[24:27]
	v_mfma_f32_16x16x32_bf16 v[20:23], v[164:167], v[216:219], v[20:23]
	v_mfma_f32_16x16x32_bf16 v[96:99], v[160:163], v[176:179], v[96:99]
	v_mfma_f32_16x16x32_bf16 v[104:107], v[168:171], v[176:179], v[104:107]
	v_mfma_f32_16x16x32_bf16 v[84:87], v[160:163], v[184:187], v[84:87]
	v_mfma_f32_16x16x32_bf16 v[76:79], v[168:171], v[184:187], v[76:79]
	v_mfma_f32_16x16x32_bf16 v[52:55], v[160:163], v[212:215], v[52:55]
	v_mfma_f32_16x16x32_bf16 v[44:47], v[168:171], v[212:215], v[44:47]
	v_mfma_f32_16x16x32_bf16 v[24:27], v[160:163], v[228:231], v[24:27]
	v_mfma_f32_16x16x32_bf16 v[20:23], v[168:171], v[228:231], v[20:23]
	s_setprio 0
	s_barrier
; #define PG8_WAIT_V(n) asm volatile("s_waitcnt vmcnt(" #n ")" ::: "memory")
; template <class Epi, bool ALIGN_EPI, bool SP2, class Hook>
; __device__ __forceinline__ void gemm_phase(LAS unsigned char* lds, const Gemm g, const StaticOrder& S, const Epi& E, Acc& acc, const bool fresh, const Hook& H, const int wave_id) {
;     ...
;         for (int t = t0; t < nt; t += 2) {
;             const bool last = (t == nt - 2);
;             const Src a1 = cA + (size_t)(t + 1) * kstep;
;             const Src a2 = last ? nA : cA + (size_t)(t + 2) * kstep, b2 = last ? nB : cB + (size_t)(t + 2) * kstep;
;             const Src a3 = a2 + kstep, b3 = b2 + kstep;
;             if (last && has_next) H(nxt);
;             if constexpr (SP2) {
;             PG8_TRIP_SP2(PG8_WAIT_V(8));
	v_add_u32_e32 v152, 0x18000, v148
	v_add_u32_e32 v153, 0x1c000, v148
	ds_read_b128 v[132:135], v152
	ds_read_b128 v[136:139], v152 offset:1024
	ds_read_b128 v[140:143], v152 offset:2048
	ds_read_b128 v[154:157], v152 offset:3072
	ds_read_b128 v[158:161], v153
	ds_read_b128 v[162:165], v153 offset:1024
	ds_read_b128 v[166:169], v153 offset:2048
	ds_read_b128 v[170:173], v153 offset:3072
	s_add_i32 s60, s60, 0x40000
	s_mov_b32 m0, s37
	ds_read_b128 v[174:177], v149 offset:32768
	ds_read_b128 v[178:181], v149 offset:33792
	ds_read_b128 v[182:185], v149 offset:34816
	ds_read_b128 v[186:189], v149 offset:35840
	ds_read_b128 v[190:193], v149 offset:36864
	ds_read_b128 v[212:215], v149 offset:37888
	ds_read_b128 v[216:219], v149 offset:38912
	ds_read_b128 v[228:231], v149 offset:39936
	buffer_load_dwordx4 v144, s[16:19], s60 offen lds
	s_mov_b32 m0, s38
	s_nop 0
	buffer_load_dwordx4 v146, s[16:19], s60 offen lds
	s_waitcnt vmcnt(8)
	s_waitcnt lgkmcnt(0)
	s_barrier
	s_setprio 1
	v_mfma_f32_16x16x32_bf16 v[120:123], v[132:135], v[174:177], v[120:123]
	v_mfma_f32_16x16x32_bf16 v[112:115], v[140:143], v[174:177], v[112:115]
	v_mfma_f32_16x16x32_bf16 v[100:103], v[132:135], v[182:185], v[100:103]
	v_mfma_f32_16x16x32_bf16 v[88:91], v[140:143], v[182:185], v[88:91]
	v_mfma_f32_16x16x32_bf16 v[68:71], v[132:135], v[190:193], v[68:71]
	v_mfma_f32_16x16x32_bf16 v[56:59], v[140:143], v[190:193], v[56:59]
	v_mfma_f32_16x16x32_bf16 v[36:39], v[132:135], v[216:219], v[36:39]
	v_mfma_f32_16x16x32_bf16 v[28:31], v[140:143], v[216:219], v[28:31]
	v_mfma_f32_16x16x32_bf16 v[120:123], v[136:139], v[178:181], v[120:123]
	v_mfma_f32_16x16x32_bf16 v[112:115], v[154:157], v[178:181], v[112:115]
	v_mfma_f32_16x16x32_bf16 v[100:103], v[136:139], v[186:189], v[100:103]
	v_mfma_f32_16x16x32_bf16 v[88:91], v[154:157], v[186:189], v[88:91]
	v_mfma_f32_16x16x32_bf16 v[68:71], v[136:139], v[212:215], v[68:71]
	v_mfma_f32_16x16x32_bf16 v[56:59], v[154:157], v[212:215], v[56:59]
	v_mfma_f32_16x16x32_bf16 v[36:39], v[136:139], v[228:231], v[36:39]
	v_mfma_f32_16x16x32_bf16 v[28:31], v[154:157], v[228:231], v[28:31]
	v_mfma_f32_16x16x32_bf16 v[128:131], v[158:161], v[174:177], v[128:131]
	v_mfma_f32_16x16x32_bf16 v[124:127], v[166:169], v[174:177], v[124:127]
	v_mfma_f32_16x16x32_bf16 v[116:119], v[158:161], v[182:185], v[116:119]
	v_mfma_f32_16x16x32_bf16 v[108:111], v[166:169], v[182:185], v[108:111]
	v_mfma_f32_16x16x32_bf16 v[92:95], v[158:161], v[190:193], v[92:95]
	v_mfma_f32_16x16x32_bf16 v[80:83], v[166:169], v[190:193], v[80:83]
	v_mfma_f32_16x16x32_bf16 v[64:67], v[158:161], v[216:219], v[64:67]
	v_mfma_f32_16x16x32_bf16 v[48:51], v[166:169], v[216:219], v[48:51]
	v_mfma_f32_16x16x32_bf16 v[128:131], v[162:165], v[178:181], v[128:131]
	v_mfma_f32_16x16x32_bf16 v[124:127], v[170:173], v[178:181], v[124:127]
	v_mfma_f32_16x16x32_bf16 v[116:119], v[162:165], v[186:189], v[116:119]
	v_mfma_f32_16x16x32_bf16 v[108:111], v[170:173], v[186:189], v[108:111]
	v_mfma_f32_16x16x32_bf16 v[92:95], v[162:165], v[212:215], v[92:95]
	v_mfma_f32_16x16x32_bf16 v[80:83], v[170:173], v[212:215], v[80:83]
	v_mfma_f32_16x16x32_bf16 v[64:67], v[162:165], v[228:231], v[64:67]
	v_mfma_f32_16x16x32_bf16 v[48:51], v[170:173], v[228:231], v[48:51]
	s_setprio 0
	s_barrier
	s_mov_b32 m0, s39
	s_or_b32 s60, s58, 0x80
	ds_read_b128 v[174:177], v149 offset:49152
	ds_read_b128 v[178:181], v149 offset:50176
	ds_read_b128 v[182:185], v149 offset:51200
	ds_read_b128 v[186:189], v149 offset:52224
	ds_read_b128 v[190:193], v149 offset:53248
	ds_read_b128 v[212:215], v149 offset:54272
	ds_read_b128 v[216:219], v149 offset:55296
	ds_read_b128 v[228:231], v149 offset:56320
	buffer_load_dwordx4 v145, s[12:15], s60 offen lds
	s_mov_b32 m0, s40
	s_add_i32 s58, s58, 0x40080
	buffer_load_dwordx4 v147, s[12:15], s60 offen lds
	s_mov_b32 m0, s43
	s_nop 0
	buffer_load_dwordx4 v145, s[12:15], s58 offen lds
	s_mov_b32 m0, s42
	s_nop 0
	buffer_load_dwordx4 v147, s[12:15], s58 offen lds
	s_mov_b32 m0, s41
	s_nop 0
	buffer_load_dwordx4 v144, s[16:19], s59 offen lds
	s_mov_b32 m0, s33
	s_nop 0
	buffer_load_dwordx4 v146, s[16:19], s59 offen lds
	s_waitcnt vmcnt(8)
	s_waitcnt lgkmcnt(0)
	s_barrier
	s_setprio 1
	v_mfma_f32_16x16x32_bf16 v[72:75], v[132:135], v[174:177], v[72:75]
	v_mfma_f32_16x16x32_bf16 v[60:63], v[140:143], v[174:177], v[60:63]
	v_mfma_f32_16x16x32_bf16 v[40:43], v[132:135], v[182:185], v[40:43]
	v_mfma_f32_16x16x32_bf16 v[32:35], v[140:143], v[182:185], v[32:35]
	v_mfma_f32_16x16x32_bf16 v[16:19], v[132:135], v[190:193], v[16:19]
	v_mfma_f32_16x16x32_bf16 v[12:15], v[140:143], v[190:193], v[12:15]
	v_mfma_f32_16x16x32_bf16 v[6:9], v[132:135], v[216:219], v[8:11]
	v_mfma_f32_16x16x32_bf16 v[2:5], v[140:143], v[216:219], v[2:5]
	v_mfma_f32_16x16x32_bf16 v[72:75], v[136:139], v[178:181], v[72:75]
	v_mfma_f32_16x16x32_bf16 v[60:63], v[154:157], v[178:181], v[60:63]
	v_mfma_f32_16x16x32_bf16 v[40:43], v[136:139], v[186:189], v[40:43]
	v_mfma_f32_16x16x32_bf16 v[32:35], v[154:157], v[186:189], v[32:35]
	v_mfma_f32_16x16x32_bf16 v[16:19], v[136:139], v[212:215], v[16:19]
	v_mfma_f32_16x16x32_bf16 v[12:15], v[154:157], v[212:215], v[12:15]
	v_mfma_f32_16x16x32_bf16 v[8:11], v[136:139], v[228:231], v[6:9]
	v_mfma_f32_16x16x32_bf16 v[4:7], v[154:157], v[228:231], v[2:5]
	v_mfma_f32_16x16x32_bf16 v[96:99], v[158:161], v[174:177], v[96:99]
	v_mfma_f32_16x16x32_bf16 v[104:107], v[166:169], v[174:177], v[104:107]
	v_mfma_f32_16x16x32_bf16 v[84:87], v[158:161], v[182:185], v[84:87]
	v_mfma_f32_16x16x32_bf16 v[76:79], v[166:169], v[182:185], v[76:79]
	v_mfma_f32_16x16x32_bf16 v[52:55], v[158:161], v[190:193], v[52:55]
	v_mfma_f32_16x16x32_bf16 v[44:47], v[166:169], v[190:193], v[44:47]
	v_mfma_f32_16x16x32_bf16 v[24:27], v[158:161], v[216:219], v[24:27]
	v_mfma_f32_16x16x32_bf16 v[20:23], v[166:169], v[216:219], v[20:23]
	v_mfma_f32_16x16x32_bf16 v[96:99], v[162:165], v[178:181], v[96:99]
	v_mfma_f32_16x16x32_bf16 v[104:107], v[170:173], v[178:181], v[104:107]
	v_mfma_f32_16x16x32_bf16 v[84:87], v[162:165], v[186:189], v[84:87]
	v_mfma_f32_16x16x32_bf16 v[76:79], v[170:173], v[186:189], v[76:79]
	v_mfma_f32_16x16x32_bf16 v[52:55], v[162:165], v[212:215], v[52:55]
	v_mfma_f32_16x16x32_bf16 v[44:47], v[170:173], v[212:215], v[44:47]
	v_mfma_f32_16x16x32_bf16 v[24:27], v[162:165], v[228:231], v[24:27]
	v_mfma_f32_16x16x32_bf16 v[20:23], v[170:173], v[228:231], v[20:23]
	s_setprio 0
	s_barrier
	s_add_i32 s29, s29, 2
	s_addk_i32 s56, 0x100
	s_addk_i32 s57, 0x100
	s_cmp_gt_u32 s29, 13
	s_cbranch_scc0 .LBB0_391
	v_readlane_b32 s8, v251, 45
	v_readlane_b32 s9, v251, 46
	s_and_b64 vcc, exec, s[8:9]
	s_cbranch_vccz .LBB0_394
	s_barrier

; #define PG8_WAIT_V(n) asm volatile("s_waitcnt vmcnt(" #n ")" ::: "memory")
; template <class Epi, bool ALIGN_EPI, bool SP2, class Hook>
; __device__ __forceinline__ void gemm_phase(LAS unsigned char* lds, const Gemm g, const StaticOrder& S, const Epi& E, Acc& acc, const bool fresh, const Hook& H, const int wave_id) {
;     ...
;         for (int t = t0; t < nt; t += 2) {
;             const bool last = (t == nt - 2);
;             const Src a1 = cA + (size_t)(t + 1) * kstep;
;             const Src a2 = last ? nA : cA + (size_t)(t + 2) * kstep, b2 = last ? nB : cB + (size_t)(t + 2) * kstep;
;             const Src a3 = a2 + kstep, b3 = b2 + kstep;
;             if (last && has_next) H(nxt);
;             if constexpr (SP2) {
;             PG8_TRIP_SP2(PG8_WAIT_V(8));
.LBB0_702:
	v_add_u32_e32 v70, 0x10000, v216
	v_add_u32_e32 v118, 0x14000, v216
	ds_read_b128 v[34:37], v70
	ds_read_b128 v[46:49], v70 offset:1024
	ds_read_b128 v[58:61], v70 offset:2048
	ds_read_b128 v[70:73], v70 offset:3072
	ds_read_b128 v[82:85], v118
	ds_read_b128 v[94:97], v118 offset:1024
	ds_read_b128 v[106:109], v118 offset:2048
	ds_read_b128 v[118:121], v118 offset:3072
	s_add_i32 s12, s55, 0xfffe0080
	s_cmp_eq_u32 s57, 4
	s_cselect_b32 s60, s53, s12
	s_cselect_b32 s13, s29, s77
	s_cselect_b32 s12, s28, s76
	s_cselect_b32 s15, s31, s35
	s_cselect_b32 s14, s30, s34
	s_cselect_b32 s58, s54, s56
	s_cselect_b32 s16, s2, s8
	s_cselect_b32 s17, s3, s9
	s_cselect_b32 s18, s26, s10
	s_cselect_b32 s19, s27, s11
	s_or_b32 s59, s60, 0x80
	s_mov_b32 m0, s45
	s_waitcnt vmcnt(14)
	ds_read_b128 v[130:133], v217
	ds_read_b128 v[142:145], v217 offset:1024
	ds_read_b128 v[154:157], v217 offset:2048
	ds_read_b128 v[166:169], v217 offset:3072
	ds_read_b128 v[174:177], v217 offset:4096
	ds_read_b128 v[182:185], v217 offset:5120
	ds_read_b128 v[186:189], v217 offset:6144
	ds_read_b128 v[190:193], v217 offset:7168
	buffer_load_dwordx4 v0, s[8:11], s55 offen lds
	s_mov_b32 m0, s46
	s_nop 0
	buffer_load_dwordx4 v214, s[8:11], s55 offen lds
	s_waitcnt vmcnt(8)
	s_waitcnt lgkmcnt(0)
	s_barrier
	s_setprio 1
	v_mfma_f32_16x16x32_bf16 v[178:181], v[34:37], v[130:133], v[178:181]
	v_mfma_f32_16x16x32_bf16 v[170:173], v[58:61], v[130:133], v[170:173]
	v_mfma_f32_16x16x32_bf16 v[150:153], v[34:37], v[154:157], v[150:153]
	v_mfma_f32_16x16x32_bf16 v[146:149], v[58:61], v[154:157], v[146:149]
	v_mfma_f32_16x16x32_bf16 v[126:129], v[34:37], v[174:177], v[126:129]
	v_mfma_f32_16x16x32_bf16 v[122:125], v[58:61], v[174:177], v[122:125]
	v_mfma_f32_16x16x32_bf16 v[102:105], v[34:37], v[186:189], v[102:105]
	v_mfma_f32_16x16x32_bf16 v[98:101], v[58:61], v[186:189], v[98:101]
	v_mfma_f32_16x16x32_bf16 v[178:181], v[46:49], v[142:145], v[178:181]
	v_mfma_f32_16x16x32_bf16 v[170:173], v[70:73], v[142:145], v[170:173]
	v_mfma_f32_16x16x32_bf16 v[150:153], v[46:49], v[166:169], v[150:153]
	v_mfma_f32_16x16x32_bf16 v[146:149], v[70:73], v[166:169], v[146:149]
	v_mfma_f32_16x16x32_bf16 v[126:129], v[46:49], v[182:185], v[126:129]
	v_mfma_f32_16x16x32_bf16 v[122:125], v[70:73], v[182:185], v[122:125]
	v_mfma_f32_16x16x32_bf16 v[102:105], v[46:49], v[190:193], v[102:105]
	v_mfma_f32_16x16x32_bf16 v[98:101], v[70:73], v[190:193], v[98:101]
	v_mfma_f32_16x16x32_bf16 v[162:165], v[82:85], v[130:133], v[162:165]
	v_mfma_f32_16x16x32_bf16 v[138:141], v[82:85], v[154:157], v[138:141]
	v_mfma_f32_16x16x32_bf16 v[134:137], v[106:109], v[154:157], v[134:137]
	v_mfma_f32_16x16x32_bf16 v[114:117], v[82:85], v[174:177], v[114:117]
	v_mfma_f32_16x16x32_bf16 v[110:113], v[106:109], v[174:177], v[110:113]
	v_mfma_f32_16x16x32_bf16 v[90:93], v[82:85], v[186:189], v[90:93]
	v_mfma_f32_16x16x32_bf16 v[86:89], v[106:109], v[186:189], v[86:89]
	v_mfma_f32_16x16x32_bf16 v[162:165], v[94:97], v[142:145], v[162:165]
	v_mfma_f32_16x16x32_bf16 v[130:133], v[106:109], v[130:133], v[158:161]
	v_mfma_f32_16x16x32_bf16 v[138:141], v[94:97], v[166:169], v[138:141]
	v_mfma_f32_16x16x32_bf16 v[134:137], v[118:121], v[166:169], v[134:137]
	v_mfma_f32_16x16x32_bf16 v[114:117], v[94:97], v[182:185], v[114:117]
	v_mfma_f32_16x16x32_bf16 v[110:113], v[118:121], v[182:185], v[110:113]
	v_mfma_f32_16x16x32_bf16 v[90:93], v[94:97], v[190:193], v[90:93]
	v_mfma_f32_16x16x32_bf16 v[86:89], v[118:121], v[190:193], v[86:89]
	v_mfma_f32_16x16x32_bf16 v[130:133], v[118:121], v[142:145], v[130:133]
	s_setprio 0
	s_barrier
	s_mov_b32 m0, s92
	ds_read_b128 v[142:145], v217 offset:16384
	ds_read_b128 v[154:157], v217 offset:17408
	ds_read_b128 v[158:161], v217 offset:18432
	ds_read_b128 v[166:169], v217 offset:19456
	ds_read_b128 v[174:177], v217 offset:20480
	ds_read_b128 v[182:185], v217 offset:21504
	ds_read_b128 v[186:189], v217 offset:22528
	ds_read_b128 v[190:193], v217 offset:23552
	buffer_load_dwordx4 v199, s[12:15], s58 offen lds
	s_mov_b32 m0, s93
	s_add_i32 s61, s58, 0x20000
	buffer_load_dwordx4 v215, s[12:15], s58 offen lds
	s_mov_b32 m0, s94
	s_nop 0
	buffer_load_dwordx4 v199, s[12:15], s61 offen lds
	s_mov_b32 m0, s95
	s_nop 0
	buffer_load_dwordx4 v215, s[12:15], s61 offen lds
	s_mov_b32 m0, s44
	s_nop 0
	buffer_load_dwordx4 v0, s[16:19], s60 offen lds
	s_mov_b32 m0, s36
	s_nop 0
	buffer_load_dwordx4 v214, s[16:19], s60 offen lds
	s_waitcnt vmcnt(8)
	s_waitcnt lgkmcnt(0)
	s_barrier
	s_setprio 1
	v_mfma_f32_16x16x32_bf16 v[78:81], v[34:37], v[142:145], v[78:81]
	v_mfma_f32_16x16x32_bf16 v[74:77], v[58:61], v[142:145], v[74:77]
	v_mfma_f32_16x16x32_bf16 v[54:57], v[34:37], v[158:161], v[54:57]
	v_mfma_f32_16x16x32_bf16 v[50:53], v[58:61], v[158:161], v[50:53]
	v_mfma_f32_16x16x32_bf16 v[30:33], v[34:37], v[174:177], v[30:33]
	v_mfma_f32_16x16x32_bf16 v[26:29], v[58:61], v[174:177], v[26:29]
	v_mfma_f32_16x16x32_bf16 v[14:17], v[34:37], v[186:189], v[14:17]
	v_mfma_f32_16x16x32_bf16 v[10:13], v[58:61], v[186:189], v[10:13]
	v_mfma_f32_16x16x32_bf16 v[78:81], v[46:49], v[154:157], v[78:81]
	v_mfma_f32_16x16x32_bf16 v[74:77], v[70:73], v[154:157], v[74:77]
	v_mfma_f32_16x16x32_bf16 v[54:57], v[46:49], v[166:169], v[54:57]
	v_mfma_f32_16x16x32_bf16 v[50:53], v[70:73], v[166:169], v[50:53]
	v_mfma_f32_16x16x32_bf16 v[30:33], v[46:49], v[182:185], v[30:33]
	v_mfma_f32_16x16x32_bf16 v[26:29], v[70:73], v[182:185], v[26:29]
	v_mfma_f32_16x16x32_bf16 v[14:17], v[46:49], v[190:193], v[14:17]
	v_mfma_f32_16x16x32_bf16 v[10:13], v[70:73], v[190:193], v[10:13]
	v_mfma_f32_16x16x32_bf16 v[42:45], v[82:85], v[158:161], v[42:45]
	v_mfma_f32_16x16x32_bf16 v[38:41], v[106:109], v[158:161], v[38:41]
	v_mfma_f32_16x16x32_bf16 v[22:25], v[82:85], v[174:177], v[22:25]
	v_mfma_f32_16x16x32_bf16 v[18:21], v[106:109], v[174:177], v[18:21]
	v_mfma_f32_16x16x32_bf16 v[6:9], v[82:85], v[186:189], v[6:9]
	v_mfma_f32_16x16x32_bf16 v[2:5], v[106:109], v[186:189], v[2:5]
	v_mfma_f32_16x16x32_bf16 v[34:37], v[82:85], v[142:145], v[66:69]
	v_mfma_f32_16x16x32_bf16 v[46:49], v[106:109], v[142:145], v[62:65]
	v_mfma_f32_16x16x32_bf16 v[42:45], v[94:97], v[166:169], v[42:45]
	v_mfma_f32_16x16x32_bf16 v[38:41], v[118:121], v[166:169], v[38:41]
	v_mfma_f32_16x16x32_bf16 v[22:25], v[94:97], v[182:185], v[22:25]
	v_mfma_f32_16x16x32_bf16 v[18:21], v[118:121], v[182:185], v[18:21]
	v_mfma_f32_16x16x32_bf16 v[6:9], v[94:97], v[190:193], v[6:9]
	v_mfma_f32_16x16x32_bf16 v[2:5], v[118:121], v[190:193], v[2:5]
	v_mfma_f32_16x16x32_bf16 v[34:37], v[94:97], v[154:157], v[34:37]
	v_mfma_f32_16x16x32_bf16 v[46:49], v[118:121], v[154:157], v[46:49]
	s_setprio 0
	s_barrier
; #define PG8_WAIT_V(n) asm volatile("s_waitcnt vmcnt(" #n ")" ::: "memory")
; template <class Epi, bool ALIGN_EPI, bool SP2, class Hook>
; __device__ __forceinline__ void gemm_phase(LAS unsigned char* lds, const Gemm g, const StaticOrder& S, const Epi& E, Acc& acc, const bool fresh, const Hook& H, const int wave_id) {
;     ...
;         for (int t = t0; t < nt; t += 2) {
;             const bool last = (t == nt - 2);
;             const Src a1 = cA + (size_t)(t + 1) * kstep;
;             const Src a2 = last ? nA : cA + (size_t)(t + 2) * kstep, b2 = last ? nB : cB + (size_t)(t + 2) * kstep;
;             const Src a3 = a2 + kstep, b3 = b2 + kstep;
;             if (last && has_next) H(nxt);
;             if constexpr (SP2) {
;             PG8_TRIP_SP2(PG8_WAIT_V(8));
	v_add_u32_e32 v70, 0x18000, v216
	v_add_u32_e32 v118, 0x1c000, v216
	ds_read_b128 v[58:61], v70
	ds_read_b128 v[62:65], v70 offset:1024
	ds_read_b128 v[66:69], v70 offset:2048
	ds_read_b128 v[70:73], v70 offset:3072
	ds_read_b128 v[82:85], v118
	ds_read_b128 v[94:97], v118 offset:1024
	ds_read_b128 v[106:109], v118 offset:2048
	ds_read_b128 v[118:121], v118 offset:3072
	s_add_i32 s60, s60, 0x20000
	s_mov_b32 m0, s37
	ds_read_b128 v[142:145], v217 offset:32768
	ds_read_b128 v[154:157], v217 offset:33792
	ds_read_b128 v[166:169], v217 offset:34816
	ds_read_b128 v[174:177], v217 offset:35840
	ds_read_b128 v[182:185], v217 offset:36864
	ds_read_b128 v[186:189], v217 offset:37888
	ds_read_b128 v[190:193], v217 offset:38912
	ds_read_b128 v[194:197], v217 offset:39936
	buffer_load_dwordx4 v0, s[16:19], s60 offen lds
	s_mov_b32 m0, s38
	s_nop 0
	buffer_load_dwordx4 v214, s[16:19], s60 offen lds
	s_waitcnt vmcnt(8)
	s_waitcnt lgkmcnt(0)
	s_barrier
	s_setprio 1
	v_mfma_f32_16x16x32_bf16 v[158:161], v[58:61], v[142:145], v[178:181]
	v_mfma_f32_16x16x32_bf16 v[178:181], v[62:65], v[154:157], v[158:161]
	v_mfma_f32_16x16x32_bf16 v[158:161], v[66:69], v[142:145], v[170:173]
	v_mfma_f32_16x16x32_bf16 v[150:153], v[58:61], v[166:169], v[150:153]
	v_mfma_f32_16x16x32_bf16 v[146:149], v[66:69], v[166:169], v[146:149]
	v_mfma_f32_16x16x32_bf16 v[126:129], v[58:61], v[182:185], v[126:129]
	v_mfma_f32_16x16x32_bf16 v[122:125], v[66:69], v[182:185], v[122:125]
	v_mfma_f32_16x16x32_bf16 v[102:105], v[58:61], v[190:193], v[102:105]
	v_mfma_f32_16x16x32_bf16 v[98:101], v[66:69], v[190:193], v[98:101]
	v_mfma_f32_16x16x32_bf16 v[170:173], v[70:73], v[154:157], v[158:161]
	v_mfma_f32_16x16x32_bf16 v[150:153], v[62:65], v[174:177], v[150:153]
	v_mfma_f32_16x16x32_bf16 v[146:149], v[70:73], v[174:177], v[146:149]
	v_mfma_f32_16x16x32_bf16 v[126:129], v[62:65], v[186:189], v[126:129]
	v_mfma_f32_16x16x32_bf16 v[122:125], v[70:73], v[186:189], v[122:125]
	v_mfma_f32_16x16x32_bf16 v[102:105], v[62:65], v[194:197], v[102:105]
	v_mfma_f32_16x16x32_bf16 v[98:101], v[70:73], v[194:197], v[98:101]
	v_mfma_f32_16x16x32_bf16 v[158:161], v[82:85], v[142:145], v[162:165]
	v_mfma_f32_16x16x32_bf16 v[130:133], v[106:109], v[142:145], v[130:133]
	v_mfma_f32_16x16x32_bf16 v[162:165], v[94:97], v[154:157], v[158:161]
	v_mfma_f32_16x16x32_bf16 v[158:161], v[118:121], v[154:157], v[130:133]
	v_mfma_f32_16x16x32_bf16 v[130:133], v[82:85], v[166:169], v[138:141]
	v_mfma_f32_16x16x32_bf16 v[138:141], v[94:97], v[174:177], v[130:133]
	v_mfma_f32_16x16x32_bf16 v[130:133], v[106:109], v[166:169], v[134:137]
	v_mfma_f32_16x16x32_bf16 v[114:117], v[82:85], v[182:185], v[114:117]
	v_mfma_f32_16x16x32_bf16 v[110:113], v[106:109], v[182:185], v[110:113]
	v_mfma_f32_16x16x32_bf16 v[90:93], v[82:85], v[190:193], v[90:93]
	v_mfma_f32_16x16x32_bf16 v[86:89], v[106:109], v[190:193], v[86:89]
	v_mfma_f32_16x16x32_bf16 v[134:137], v[118:121], v[174:177], v[130:133]
	v_mfma_f32_16x16x32_bf16 v[114:117], v[94:97], v[186:189], v[114:117]
	v_mfma_f32_16x16x32_bf16 v[110:113], v[118:121], v[186:189], v[110:113]
	v_mfma_f32_16x16x32_bf16 v[90:93], v[94:97], v[194:197], v[90:93]
	v_mfma_f32_16x16x32_bf16 v[86:89], v[118:121], v[194:197], v[86:89]
	s_setprio 0
	s_barrier
	s_mov_b32 m0, s39
	s_or_b32 s60, s58, 0x80
	ds_read_b128 v[130:133], v217 offset:49152
	ds_read_b128 v[142:145], v217 offset:50176
	ds_read_b128 v[154:157], v217 offset:51200
	ds_read_b128 v[166:169], v217 offset:52224
	ds_read_b128 v[174:177], v217 offset:53248
	ds_read_b128 v[182:185], v217 offset:54272
	ds_read_b128 v[186:189], v217 offset:55296
	ds_read_b128 v[190:193], v217 offset:56320
	buffer_load_dwordx4 v199, s[12:15], s60 offen lds
	s_mov_b32 m0, s40
	s_add_i32 s58, s58, 0x20080
	buffer_load_dwordx4 v215, s[12:15], s60 offen lds
	s_mov_b32 m0, s43
	s_nop 0
	buffer_load_dwordx4 v199, s[12:15], s58 offen lds
	s_mov_b32 m0, s42
	s_nop 0
	buffer_load_dwordx4 v215, s[12:15], s58 offen lds
	s_mov_b32 m0, s41
	s_nop 0
	buffer_load_dwordx4 v0, s[16:19], s59 offen lds
	s_mov_b32 m0, s33
	s_nop 0
	buffer_load_dwordx4 v214, s[16:19], s59 offen lds
	s_waitcnt vmcnt(8)
	s_waitcnt lgkmcnt(0)
	s_barrier
	s_setprio 1
	v_mfma_f32_16x16x32_bf16 v[78:81], v[58:61], v[130:133], v[78:81]
	v_mfma_f32_16x16x32_bf16 v[74:77], v[66:69], v[130:133], v[74:77]
	v_mfma_f32_16x16x32_bf16 v[54:57], v[58:61], v[154:157], v[54:57]
	v_mfma_f32_16x16x32_bf16 v[50:53], v[66:69], v[154:157], v[50:53]
	v_mfma_f32_16x16x32_bf16 v[30:33], v[58:61], v[174:177], v[30:33]
	v_mfma_f32_16x16x32_bf16 v[26:29], v[66:69], v[174:177], v[26:29]
	v_mfma_f32_16x16x32_bf16 v[14:17], v[58:61], v[186:189], v[14:17]
	v_mfma_f32_16x16x32_bf16 v[10:13], v[66:69], v[186:189], v[10:13]
	v_mfma_f32_16x16x32_bf16 v[78:81], v[62:65], v[142:145], v[78:81]
	v_mfma_f32_16x16x32_bf16 v[74:77], v[70:73], v[142:145], v[74:77]
	v_mfma_f32_16x16x32_bf16 v[54:57], v[62:65], v[166:169], v[54:57]
	v_mfma_f32_16x16x32_bf16 v[50:53], v[70:73], v[166:169], v[50:53]
	v_mfma_f32_16x16x32_bf16 v[30:33], v[62:65], v[182:185], v[30:33]
	v_mfma_f32_16x16x32_bf16 v[26:29], v[70:73], v[182:185], v[26:29]
	v_mfma_f32_16x16x32_bf16 v[14:17], v[62:65], v[190:193], v[14:17]
	v_mfma_f32_16x16x32_bf16 v[10:13], v[70:73], v[190:193], v[10:13]
	v_mfma_f32_16x16x32_bf16 v[34:37], v[82:85], v[130:133], v[34:37]
	v_mfma_f32_16x16x32_bf16 v[66:69], v[94:97], v[142:145], v[34:37]
	v_mfma_f32_16x16x32_bf16 v[34:37], v[106:109], v[130:133], v[46:49]
	v_mfma_f32_16x16x32_bf16 v[62:65], v[118:121], v[142:145], v[34:37]
	v_mfma_f32_16x16x32_bf16 v[34:37], v[82:85], v[154:157], v[42:45]
	v_mfma_f32_16x16x32_bf16 v[42:45], v[94:97], v[166:169], v[34:37]
	v_mfma_f32_16x16x32_bf16 v[34:37], v[106:109], v[154:157], v[38:41]
	v_mfma_f32_16x16x32_bf16 v[22:25], v[82:85], v[174:177], v[22:25]
	v_mfma_f32_16x16x32_bf16 v[18:21], v[106:109], v[174:177], v[18:21]
	v_mfma_f32_16x16x32_bf16 v[6:9], v[82:85], v[186:189], v[6:9]
	v_mfma_f32_16x16x32_bf16 v[2:5], v[106:109], v[186:189], v[2:5]
	v_mfma_f32_16x16x32_bf16 v[38:41], v[118:121], v[166:169], v[34:37]
	v_mfma_f32_16x16x32_bf16 v[22:25], v[94:97], v[182:185], v[22:25]
	v_mfma_f32_16x16x32_bf16 v[18:21], v[118:121], v[182:185], v[18:21]
	v_mfma_f32_16x16x32_bf16 v[6:9], v[94:97], v[190:193], v[6:9]
	v_mfma_f32_16x16x32_bf16 v[2:5], v[118:121], v[190:193], v[2:5]
	s_setprio 0
	s_barrier
	s_add_i32 s57, s57, 2
	s_addk_i32 s55, 0x100
	s_addk_i32 s56, 0x100
	s_cmp_gt_u32 s57, 5
	s_cbranch_scc0 .LBB0_702
	v_readlane_b32 s8, v251, 45
	v_readlane_b32 s9, v251, 46
	s_and_b64 vcc, exec, s[8:9]
	s_cbranch_vccz .LBB0_705
	s_barrier

; #define PG8_WAIT_V(n) asm volatile("s_waitcnt vmcnt(" #n ")" ::: "memory")
; template <class Epi, bool ALIGN_EPI, bool SP2, class Hook>
; __device__ __forceinline__ void gemm_phase(LAS unsigned char* lds, const Gemm g, const StaticOrder& S, const Epi& E, Acc& acc, const bool fresh, const Hook& H, const int wave_id) {
;     ...
;         for (int t = t0; t < nt; t += 2) {
;             const bool last = (t == nt - 2);
;             const Src a1 = cA + (size_t)(t + 1) * kstep;
;             const Src a2 = last ? nA : cA + (size_t)(t + 2) * kstep, b2 = last ? nB : cB + (size_t)(t + 2) * kstep;
;             const Src a3 = a2 + kstep, b3 = b2 + kstep;
;             if (last && has_next) H(nxt);
;             if constexpr (SP2) {
;             PG8_TRIP_SP2(PG8_WAIT_V(8));
.LBB0_779:
	v_add_u32_e32 v0, 0x10000, v230
	s_waitcnt vmcnt(0)
	ds_read_b128 v[130:133], v0
	ds_read_b128 v[134:137], v0 offset:1024
	ds_read_b128 v[138:141], v0 offset:2048
	ds_read_b128 v[142:145], v0 offset:3072
	v_add_u32_e32 v0, 0x14000, v230
	ds_read_b128 v[146:149], v0
	ds_read_b128 v[150:153], v0 offset:1024
	ds_read_b128 v[154:157], v0 offset:2048
	ds_read_b128 v[158:161], v0 offset:3072
	s_add_i32 s12, s2, 0xfffe0080
	s_cmp_eq_u32 s63, 4
	s_cselect_b32 s66, s60, s12
	s_cselect_b32 s13, s53, s77
	s_cselect_b32 s12, s52, s76
	s_cselect_b32 s15, s55, s7
	s_cselect_b32 s14, s54, s6
	s_cselect_b32 s64, s61, s3
	s_cselect_b32 s16, s34, s8
	s_cselect_b32 s17, s35, s9
	s_cselect_b32 s18, s50, s10
	s_cselect_b32 s19, s51, s11
	s_or_b32 s65, s66, 0x80
	s_mov_b32 m0, s45
	ds_read_b128 v[162:165], v231
	ds_read_b128 v[166:169], v231 offset:1024
	ds_read_b128 v[170:173], v231 offset:2048
	ds_read_b128 v[174:177], v231 offset:3072
	ds_read_b128 v[178:181], v231 offset:4096
	ds_read_b128 v[182:185], v231 offset:5120
	ds_read_b128 v[186:189], v231 offset:6144
	ds_read_b128 v[190:193], v231 offset:7168
	buffer_load_dwordx4 v199, s[8:11], s2 offen lds
	s_mov_b32 m0, s46
	s_nop 0
	buffer_load_dwordx4 v228, s[8:11], s2 offen lds
	s_waitcnt vmcnt(8)
	s_waitcnt lgkmcnt(0)
	s_barrier
	s_setprio 1
	v_mfma_f32_16x16x32_bf16 v[126:129], v[130:133], v[162:165], v[126:129]
	v_mfma_f32_16x16x32_bf16 v[122:125], v[138:141], v[162:165], v[122:125]
	v_mfma_f32_16x16x32_bf16 v[118:121], v[130:133], v[170:173], v[118:121]
	v_mfma_f32_16x16x32_bf16 v[114:117], v[138:141], v[170:173], v[114:117]
	v_mfma_f32_16x16x32_bf16 v[110:113], v[130:133], v[178:181], v[110:113]
	v_mfma_f32_16x16x32_bf16 v[106:109], v[138:141], v[178:181], v[106:109]
	v_mfma_f32_16x16x32_bf16 v[102:105], v[130:133], v[186:189], v[102:105]
	v_mfma_f32_16x16x32_bf16 v[98:101], v[138:141], v[186:189], v[98:101]
	v_mfma_f32_16x16x32_bf16 v[126:129], v[134:137], v[166:169], v[126:129]
	v_mfma_f32_16x16x32_bf16 v[122:125], v[142:145], v[166:169], v[122:125]
	v_mfma_f32_16x16x32_bf16 v[118:121], v[134:137], v[174:177], v[118:121]
	v_mfma_f32_16x16x32_bf16 v[114:117], v[142:145], v[174:177], v[114:117]
	v_mfma_f32_16x16x32_bf16 v[110:113], v[134:137], v[182:185], v[110:113]
	v_mfma_f32_16x16x32_bf16 v[106:109], v[142:145], v[182:185], v[106:109]
	v_mfma_f32_16x16x32_bf16 v[102:105], v[134:137], v[190:193], v[102:105]
	v_mfma_f32_16x16x32_bf16 v[98:101], v[142:145], v[190:193], v[98:101]
	v_mfma_f32_16x16x32_bf16 v[94:97], v[146:149], v[162:165], v[94:97]
	v_mfma_f32_16x16x32_bf16 v[90:93], v[154:157], v[162:165], v[90:93]
	v_mfma_f32_16x16x32_bf16 v[86:89], v[146:149], v[170:173], v[86:89]
	v_mfma_f32_16x16x32_bf16 v[82:85], v[154:157], v[170:173], v[82:85]
	v_mfma_f32_16x16x32_bf16 v[78:81], v[146:149], v[178:181], v[78:81]
	v_mfma_f32_16x16x32_bf16 v[74:77], v[154:157], v[178:181], v[74:77]
	v_mfma_f32_16x16x32_bf16 v[70:73], v[146:149], v[186:189], v[70:73]
	v_mfma_f32_16x16x32_bf16 v[66:69], v[154:157], v[186:189], v[66:69]
	v_mfma_f32_16x16x32_bf16 v[94:97], v[150:153], v[166:169], v[94:97]
	v_mfma_f32_16x16x32_bf16 v[90:93], v[158:161], v[166:169], v[90:93]
	v_mfma_f32_16x16x32_bf16 v[86:89], v[150:153], v[174:177], v[86:89]
	v_mfma_f32_16x16x32_bf16 v[82:85], v[158:161], v[174:177], v[82:85]
	v_mfma_f32_16x16x32_bf16 v[78:81], v[150:153], v[182:185], v[78:81]
	v_mfma_f32_16x16x32_bf16 v[74:77], v[158:161], v[182:185], v[74:77]
	v_mfma_f32_16x16x32_bf16 v[70:73], v[150:153], v[190:193], v[70:73]
	v_mfma_f32_16x16x32_bf16 v[66:69], v[158:161], v[190:193], v[66:69]
	s_setprio 0
	s_barrier
	s_mov_b32 m0, s92
	ds_read_b128 v[162:165], v231 offset:16384
	ds_read_b128 v[166:169], v231 offset:17408
	ds_read_b128 v[170:173], v231 offset:18432
	ds_read_b128 v[174:177], v231 offset:19456
	ds_read_b128 v[178:181], v231 offset:20480
	ds_read_b128 v[182:185], v231 offset:21504
	ds_read_b128 v[186:189], v231 offset:22528
	ds_read_b128 v[190:193], v231 offset:23552
	buffer_load_dwordx4 v227, s[12:15], s64 offen lds
	s_mov_b32 m0, s93
	s_add_i32 s67, s64, 0x20000
	buffer_load_dwordx4 v229, s[12:15], s64 offen lds
	s_mov_b32 m0, s94
	s_nop 0
	buffer_load_dwordx4 v227, s[12:15], s67 offen lds
	s_mov_b32 m0, s95
	s_nop 0
	buffer_load_dwordx4 v229, s[12:15], s67 offen lds
	s_mov_b32 m0, s44
	s_nop 0
	buffer_load_dwordx4 v199, s[16:19], s66 offen lds
	s_mov_b32 m0, s36
	s_nop 0
	buffer_load_dwordx4 v228, s[16:19], s66 offen lds
	s_waitcnt vmcnt(8)
	s_waitcnt lgkmcnt(0)
	s_barrier
	s_setprio 1
	v_mfma_f32_16x16x32_bf16 v[62:65], v[130:133], v[162:165], v[62:65]
	v_mfma_f32_16x16x32_bf16 v[58:61], v[138:141], v[162:165], v[58:61]
	v_mfma_f32_16x16x32_bf16 v[54:57], v[130:133], v[170:173], v[54:57]
	v_mfma_f32_16x16x32_bf16 v[50:53], v[138:141], v[170:173], v[50:53]
	v_mfma_f32_16x16x32_bf16 v[46:49], v[130:133], v[178:181], v[46:49]
	v_mfma_f32_16x16x32_bf16 v[42:45], v[138:141], v[178:181], v[42:45]
	v_mfma_f32_16x16x32_bf16 v[38:41], v[130:133], v[186:189], v[38:41]
	v_mfma_f32_16x16x32_bf16 v[34:37], v[138:141], v[186:189], v[34:37]
	v_mfma_f32_16x16x32_bf16 v[62:65], v[134:137], v[166:169], v[62:65]
	v_mfma_f32_16x16x32_bf16 v[58:61], v[142:145], v[166:169], v[58:61]
	v_mfma_f32_16x16x32_bf16 v[54:57], v[134:137], v[174:177], v[54:57]
	v_mfma_f32_16x16x32_bf16 v[50:53], v[142:145], v[174:177], v[50:53]
	v_mfma_f32_16x16x32_bf16 v[46:49], v[134:137], v[182:185], v[46:49]
	v_mfma_f32_16x16x32_bf16 v[42:45], v[142:145], v[182:185], v[42:45]
	v_mfma_f32_16x16x32_bf16 v[38:41], v[134:137], v[190:193], v[38:41]
	v_mfma_f32_16x16x32_bf16 v[34:37], v[142:145], v[190:193], v[34:37]
	v_mfma_f32_16x16x32_bf16 v[30:33], v[146:149], v[162:165], v[30:33]
	v_mfma_f32_16x16x32_bf16 v[26:29], v[154:157], v[162:165], v[26:29]
	v_mfma_f32_16x16x32_bf16 v[22:25], v[146:149], v[170:173], v[22:25]
	v_mfma_f32_16x16x32_bf16 v[18:21], v[154:157], v[170:173], v[18:21]
	v_mfma_f32_16x16x32_bf16 v[14:17], v[146:149], v[178:181], v[14:17]
	v_mfma_f32_16x16x32_bf16 v[10:13], v[154:157], v[178:181], v[10:13]
	v_mfma_f32_16x16x32_bf16 v[6:9], v[146:149], v[186:189], v[6:9]
	v_mfma_f32_16x16x32_bf16 v[2:5], v[154:157], v[186:189], v[2:5]
	v_mfma_f32_16x16x32_bf16 v[30:33], v[150:153], v[166:169], v[30:33]
	v_mfma_f32_16x16x32_bf16 v[26:29], v[158:161], v[166:169], v[26:29]
	v_mfma_f32_16x16x32_bf16 v[22:25], v[150:153], v[174:177], v[22:25]
	v_mfma_f32_16x16x32_bf16 v[18:21], v[158:161], v[174:177], v[18:21]
	v_mfma_f32_16x16x32_bf16 v[14:17], v[150:153], v[182:185], v[14:17]
	v_mfma_f32_16x16x32_bf16 v[10:13], v[158:161], v[182:185], v[10:13]
	v_mfma_f32_16x16x32_bf16 v[6:9], v[150:153], v[190:193], v[6:9]
	v_mfma_f32_16x16x32_bf16 v[2:5], v[158:161], v[190:193], v[2:5]
	s_setprio 0
	s_barrier
; #define PG8_WAIT_V(n) asm volatile("s_waitcnt vmcnt(" #n ")" ::: "memory")
; template <class Epi, bool ALIGN_EPI, bool SP2, class Hook>
; __device__ __forceinline__ void gemm_phase(LAS unsigned char* lds, const Gemm g, const StaticOrder& S, const Epi& E, Acc& acc, const bool fresh, const Hook& H, const int wave_id) {
;     ...
;         for (int t = t0; t < nt; t += 2) {
;             const bool last = (t == nt - 2);
;             const Src a1 = cA + (size_t)(t + 1) * kstep;
;             const Src a2 = last ? nA : cA + (size_t)(t + 2) * kstep, b2 = last ? nB : cB + (size_t)(t + 2) * kstep;
;             const Src a3 = a2 + kstep, b3 = b2 + kstep;
;             if (last && has_next) H(nxt);
;             if constexpr (SP2) {
;             PG8_TRIP_SP2(PG8_WAIT_V(8));
	v_add_u32_e32 v0, 0x18000, v230
	ds_read_b128 v[130:133], v0
	ds_read_b128 v[134:137], v0 offset:1024
	ds_read_b128 v[138:141], v0 offset:2048
	ds_read_b128 v[142:145], v0 offset:3072
	v_add_u32_e32 v0, 0x1c000, v230
	ds_read_b128 v[146:149], v0
	ds_read_b128 v[150:153], v0 offset:1024
	ds_read_b128 v[154:157], v0 offset:2048
	ds_read_b128 v[158:161], v0 offset:3072
	s_add_i32 s66, s66, 0x20000
	s_mov_b32 m0, s37
	ds_read_b128 v[162:165], v231 offset:32768
	ds_read_b128 v[166:169], v231 offset:33792
	ds_read_b128 v[170:173], v231 offset:34816
	ds_read_b128 v[174:177], v231 offset:35840
	ds_read_b128 v[178:181], v231 offset:36864
	ds_read_b128 v[182:185], v231 offset:37888
	ds_read_b128 v[186:189], v231 offset:38912
	ds_read_b128 v[190:193], v231 offset:39936
	buffer_load_dwordx4 v199, s[16:19], s66 offen lds
	s_mov_b32 m0, s38
	s_nop 0
	buffer_load_dwordx4 v228, s[16:19], s66 offen lds
	s_waitcnt vmcnt(8)
	s_waitcnt lgkmcnt(0)
	s_barrier
	s_setprio 1
	v_mfma_f32_16x16x32_bf16 v[126:129], v[130:133], v[162:165], v[126:129]
	v_mfma_f32_16x16x32_bf16 v[122:125], v[138:141], v[162:165], v[122:125]
	v_mfma_f32_16x16x32_bf16 v[118:121], v[130:133], v[170:173], v[118:121]
	v_mfma_f32_16x16x32_bf16 v[114:117], v[138:141], v[170:173], v[114:117]
	v_mfma_f32_16x16x32_bf16 v[110:113], v[130:133], v[178:181], v[110:113]
	v_mfma_f32_16x16x32_bf16 v[106:109], v[138:141], v[178:181], v[106:109]
	v_mfma_f32_16x16x32_bf16 v[102:105], v[130:133], v[186:189], v[102:105]
	v_mfma_f32_16x16x32_bf16 v[98:101], v[138:141], v[186:189], v[98:101]
	v_mfma_f32_16x16x32_bf16 v[126:129], v[134:137], v[166:169], v[126:129]
	v_mfma_f32_16x16x32_bf16 v[122:125], v[142:145], v[166:169], v[122:125]
	v_mfma_f32_16x16x32_bf16 v[118:121], v[134:137], v[174:177], v[118:121]
	v_mfma_f32_16x16x32_bf16 v[114:117], v[142:145], v[174:177], v[114:117]
	v_mfma_f32_16x16x32_bf16 v[110:113], v[134:137], v[182:185], v[110:113]
	v_mfma_f32_16x16x32_bf16 v[106:109], v[142:145], v[182:185], v[106:109]
	v_mfma_f32_16x16x32_bf16 v[102:105], v[134:137], v[190:193], v[102:105]
	v_mfma_f32_16x16x32_bf16 v[98:101], v[142:145], v[190:193], v[98:101]
	v_mfma_f32_16x16x32_bf16 v[94:97], v[146:149], v[162:165], v[94:97]
	v_mfma_f32_16x16x32_bf16 v[90:93], v[154:157], v[162:165], v[90:93]
	v_mfma_f32_16x16x32_bf16 v[86:89], v[146:149], v[170:173], v[86:89]
	v_mfma_f32_16x16x32_bf16 v[82:85], v[154:157], v[170:173], v[82:85]
	v_mfma_f32_16x16x32_bf16 v[78:81], v[146:149], v[178:181], v[78:81]
	v_mfma_f32_16x16x32_bf16 v[74:77], v[154:157], v[178:181], v[74:77]
	v_mfma_f32_16x16x32_bf16 v[70:73], v[146:149], v[186:189], v[70:73]
	v_mfma_f32_16x16x32_bf16 v[66:69], v[154:157], v[186:189], v[66:69]
	v_mfma_f32_16x16x32_bf16 v[94:97], v[150:153], v[166:169], v[94:97]
	v_mfma_f32_16x16x32_bf16 v[90:93], v[158:161], v[166:169], v[90:93]
	v_mfma_f32_16x16x32_bf16 v[86:89], v[150:153], v[174:177], v[86:89]
	v_mfma_f32_16x16x32_bf16 v[82:85], v[158:161], v[174:177], v[82:85]
	v_mfma_f32_16x16x32_bf16 v[78:81], v[150:153], v[182:185], v[78:81]
	v_mfma_f32_16x16x32_bf16 v[74:77], v[158:161], v[182:185], v[74:77]
	v_mfma_f32_16x16x32_bf16 v[70:73], v[150:153], v[190:193], v[70:73]
	v_mfma_f32_16x16x32_bf16 v[66:69], v[158:161], v[190:193], v[66:69]
	s_setprio 0
	s_barrier
	s_mov_b32 m0, s39
	s_or_b32 s66, s64, 0x80
	ds_read_b128 v[162:165], v231 offset:49152
	ds_read_b128 v[166:169], v231 offset:50176
	ds_read_b128 v[170:173], v231 offset:51200
	ds_read_b128 v[174:177], v231 offset:52224
	ds_read_b128 v[178:181], v231 offset:53248
	ds_read_b128 v[182:185], v231 offset:54272
	ds_read_b128 v[186:189], v231 offset:55296
	ds_read_b128 v[190:193], v231 offset:56320
	buffer_load_dwordx4 v227, s[12:15], s66 offen lds
	s_mov_b32 m0, s40
	s_add_i32 s64, s64, 0x20080
	buffer_load_dwordx4 v229, s[12:15], s66 offen lds
	s_mov_b32 m0, s43
	s_nop 0
	buffer_load_dwordx4 v227, s[12:15], s64 offen lds
	s_mov_b32 m0, s42
	s_nop 0
	buffer_load_dwordx4 v229, s[12:15], s64 offen lds
	s_mov_b32 m0, s41
	s_nop 0
	buffer_load_dwordx4 v199, s[16:19], s65 offen lds
	s_mov_b32 m0, s33
	s_nop 0
	buffer_load_dwordx4 v228, s[16:19], s65 offen lds
	s_waitcnt vmcnt(8)
	s_waitcnt lgkmcnt(0)
	s_barrier
	s_setprio 1
	v_mfma_f32_16x16x32_bf16 v[62:65], v[130:133], v[162:165], v[62:65]
	v_mfma_f32_16x16x32_bf16 v[58:61], v[138:141], v[162:165], v[58:61]
	v_mfma_f32_16x16x32_bf16 v[54:57], v[130:133], v[170:173], v[54:57]
	v_mfma_f32_16x16x32_bf16 v[50:53], v[138:141], v[170:173], v[50:53]
	v_mfma_f32_16x16x32_bf16 v[46:49], v[130:133], v[178:181], v[46:49]
	v_mfma_f32_16x16x32_bf16 v[42:45], v[138:141], v[178:181], v[42:45]
	v_mfma_f32_16x16x32_bf16 v[38:41], v[130:133], v[186:189], v[38:41]
	v_mfma_f32_16x16x32_bf16 v[34:37], v[138:141], v[186:189], v[34:37]
	v_mfma_f32_16x16x32_bf16 v[62:65], v[134:137], v[166:169], v[62:65]
	v_mfma_f32_16x16x32_bf16 v[58:61], v[142:145], v[166:169], v[58:61]
	v_mfma_f32_16x16x32_bf16 v[54:57], v[134:137], v[174:177], v[54:57]
	v_mfma_f32_16x16x32_bf16 v[50:53], v[142:145], v[174:177], v[50:53]
	v_mfma_f32_16x16x32_bf16 v[46:49], v[134:137], v[182:185], v[46:49]
	v_mfma_f32_16x16x32_bf16 v[42:45], v[142:145], v[182:185], v[42:45]
	v_mfma_f32_16x16x32_bf16 v[38:41], v[134:137], v[190:193], v[38:41]
	v_mfma_f32_16x16x32_bf16 v[34:37], v[142:145], v[190:193], v[34:37]
	v_mfma_f32_16x16x32_bf16 v[30:33], v[146:149], v[162:165], v[30:33]
	v_mfma_f32_16x16x32_bf16 v[26:29], v[154:157], v[162:165], v[26:29]
	v_mfma_f32_16x16x32_bf16 v[22:25], v[146:149], v[170:173], v[22:25]
	v_mfma_f32_16x16x32_bf16 v[18:21], v[154:157], v[170:173], v[18:21]
	v_mfma_f32_16x16x32_bf16 v[14:17], v[146:149], v[178:181], v[14:17]
	v_mfma_f32_16x16x32_bf16 v[10:13], v[154:157], v[178:181], v[10:13]
	v_mfma_f32_16x16x32_bf16 v[6:9], v[146:149], v[186:189], v[6:9]
	v_mfma_f32_16x16x32_bf16 v[2:5], v[154:157], v[186:189], v[2:5]
	v_mfma_f32_16x16x32_bf16 v[30:33], v[150:153], v[166:169], v[30:33]
	v_mfma_f32_16x16x32_bf16 v[26:29], v[158:161], v[166:169], v[26:29]
	v_mfma_f32_16x16x32_bf16 v[22:25], v[150:153], v[174:177], v[22:25]
	v_mfma_f32_16x16x32_bf16 v[18:21], v[158:161], v[174:177], v[18:21]
	v_mfma_f32_16x16x32_bf16 v[14:17], v[150:153], v[182:185], v[14:17]
	v_mfma_f32_16x16x32_bf16 v[10:13], v[158:161], v[182:185], v[10:13]
	v_mfma_f32_16x16x32_bf16 v[6:9], v[150:153], v[190:193], v[6:9]
	v_mfma_f32_16x16x32_bf16 v[2:5], v[158:161], v[190:193], v[2:5]
	s_setprio 0
	s_barrier
	s_add_i32 s63, s63, 2
	s_addk_i32 s2, 0x100
	s_addk_i32 s3, 0x100
	s_cmp_gt_u32 s63, 5
	s_cbranch_scc0 .LBB0_779
	v_readlane_b32 s2, v251, 45
	v_readlane_b32 s3, v251, 46
	s_and_b64 vcc, exec, s[2:3]
	s_cbranch_vccz .LBB0_782
	s_barrier

; #define PG8_WAIT_V(n) asm volatile("s_waitcnt vmcnt(" #n ")" ::: "memory")
; template <class Epi, bool ALIGN_EPI, bool SP2, class Hook>
; __device__ __forceinline__ void gemm_phase(LAS unsigned char* lds, const Gemm g, const StaticOrder& S, const Epi& E, Acc& acc, const bool fresh, const Hook& H, const int wave_id) {
;     ...
;         for (int t = t0; t < nt; t += 2) {
;             const bool last = (t == nt - 2);
;             const Src a1 = cA + (size_t)(t + 1) * kstep;
;             const Src a2 = last ? nA : cA + (size_t)(t + 2) * kstep, b2 = last ? nB : cB + (size_t)(t + 2) * kstep;
;             const Src a3 = a2 + kstep, b3 = b2 + kstep;
;             if (last && has_next) H(nxt);
;             if constexpr (SP2) {
;             PG8_TRIP_SP2(PG8_WAIT_V(8));
.LBB0_903:
	v_add_u32_e32 v70, 0x10000, v216
	v_add_u32_e32 v118, 0x14000, v216
	ds_read_b128 v[34:37], v70
	ds_read_b128 v[46:49], v70 offset:1024
	ds_read_b128 v[58:61], v70 offset:2048
	ds_read_b128 v[70:73], v70 offset:3072
	ds_read_b128 v[82:85], v118
	ds_read_b128 v[94:97], v118 offset:1024
	ds_read_b128 v[106:109], v118 offset:2048
	ds_read_b128 v[118:121], v118 offset:3072
	s_add_i32 s12, s55, 0xfffe0080
	s_cmp_eq_u32 s57, 4
	s_cselect_b32 s60, s53, s12
	s_cselect_b32 s13, s29, s77
	s_cselect_b32 s12, s28, s76
	s_cselect_b32 s15, s31, s35
	s_cselect_b32 s14, s30, s34
	s_cselect_b32 s58, s54, s56
	s_cselect_b32 s16, s2, s8
	s_cselect_b32 s17, s3, s9
	s_cselect_b32 s18, s26, s10
	s_cselect_b32 s19, s27, s11
	s_or_b32 s59, s60, 0x80
	s_mov_b32 m0, s45
	ds_read_b128 v[130:133], v217
	ds_read_b128 v[142:145], v217 offset:1024
	ds_read_b128 v[154:157], v217 offset:2048
	ds_read_b128 v[166:169], v217 offset:3072
	ds_read_b128 v[174:177], v217 offset:4096
	ds_read_b128 v[182:185], v217 offset:5120
	ds_read_b128 v[186:189], v217 offset:6144
	ds_read_b128 v[190:193], v217 offset:7168
	buffer_load_dwordx4 v0, s[8:11], s55 offen lds
	s_mov_b32 m0, s46
	s_nop 0
	buffer_load_dwordx4 v214, s[8:11], s55 offen lds
	s_waitcnt vmcnt(8)
	s_waitcnt lgkmcnt(0)
	s_barrier
	s_setprio 1
	v_mfma_f32_16x16x32_bf16 v[178:181], v[34:37], v[130:133], v[178:181]
	v_mfma_f32_16x16x32_bf16 v[170:173], v[58:61], v[130:133], v[170:173]
	v_mfma_f32_16x16x32_bf16 v[150:153], v[34:37], v[154:157], v[150:153]
	v_mfma_f32_16x16x32_bf16 v[146:149], v[58:61], v[154:157], v[146:149]
	v_mfma_f32_16x16x32_bf16 v[126:129], v[34:37], v[174:177], v[126:129]
	v_mfma_f32_16x16x32_bf16 v[122:125], v[58:61], v[174:177], v[122:125]
	v_mfma_f32_16x16x32_bf16 v[102:105], v[34:37], v[186:189], v[102:105]
	v_mfma_f32_16x16x32_bf16 v[98:101], v[58:61], v[186:189], v[98:101]
	v_mfma_f32_16x16x32_bf16 v[178:181], v[46:49], v[142:145], v[178:181]
	v_mfma_f32_16x16x32_bf16 v[170:173], v[70:73], v[142:145], v[170:173]
	v_mfma_f32_16x16x32_bf16 v[150:153], v[46:49], v[166:169], v[150:153]
	v_mfma_f32_16x16x32_bf16 v[146:149], v[70:73], v[166:169], v[146:149]
	v_mfma_f32_16x16x32_bf16 v[126:129], v[46:49], v[182:185], v[126:129]
	v_mfma_f32_16x16x32_bf16 v[122:125], v[70:73], v[182:185], v[122:125]
	v_mfma_f32_16x16x32_bf16 v[102:105], v[46:49], v[190:193], v[102:105]
	v_mfma_f32_16x16x32_bf16 v[98:101], v[70:73], v[190:193], v[98:101]
	v_mfma_f32_16x16x32_bf16 v[162:165], v[82:85], v[130:133], v[162:165]
	v_mfma_f32_16x16x32_bf16 v[138:141], v[82:85], v[154:157], v[138:141]
	v_mfma_f32_16x16x32_bf16 v[134:137], v[106:109], v[154:157], v[134:137]
	v_mfma_f32_16x16x32_bf16 v[114:117], v[82:85], v[174:177], v[114:117]
	v_mfma_f32_16x16x32_bf16 v[110:113], v[106:109], v[174:177], v[110:113]
	v_mfma_f32_16x16x32_bf16 v[90:93], v[82:85], v[186:189], v[90:93]
	v_mfma_f32_16x16x32_bf16 v[86:89], v[106:109], v[186:189], v[86:89]
	v_mfma_f32_16x16x32_bf16 v[162:165], v[94:97], v[142:145], v[162:165]
	v_mfma_f32_16x16x32_bf16 v[130:133], v[106:109], v[130:133], v[158:161]
	v_mfma_f32_16x16x32_bf16 v[138:141], v[94:97], v[166:169], v[138:141]
	v_mfma_f32_16x16x32_bf16 v[134:137], v[118:121], v[166:169], v[134:137]
	v_mfma_f32_16x16x32_bf16 v[114:117], v[94:97], v[182:185], v[114:117]
	v_mfma_f32_16x16x32_bf16 v[110:113], v[118:121], v[182:185], v[110:113]
	v_mfma_f32_16x16x32_bf16 v[90:93], v[94:97], v[190:193], v[90:93]
	v_mfma_f32_16x16x32_bf16 v[86:89], v[118:121], v[190:193], v[86:89]
	v_mfma_f32_16x16x32_bf16 v[130:133], v[118:121], v[142:145], v[130:133]
	s_setprio 0
	s_barrier
	s_mov_b32 m0, s92
	ds_read_b128 v[142:145], v217 offset:16384
	ds_read_b128 v[154:157], v217 offset:17408
	ds_read_b128 v[158:161], v217 offset:18432
	ds_read_b128 v[166:169], v217 offset:19456
	ds_read_b128 v[174:177], v217 offset:20480
	ds_read_b128 v[182:185], v217 offset:21504
	ds_read_b128 v[186:189], v217 offset:22528
	ds_read_b128 v[190:193], v217 offset:23552
	buffer_load_dwordx4 v199, s[12:15], s58 offen lds
	s_mov_b32 m0, s93
	s_add_i32 s61, s58, 0x20000
	buffer_load_dwordx4 v215, s[12:15], s58 offen lds
	s_mov_b32 m0, s94
	s_nop 0
	buffer_load_dwordx4 v199, s[12:15], s61 offen lds
	s_mov_b32 m0, s95
	s_nop 0
	buffer_load_dwordx4 v215, s[12:15], s61 offen lds
	s_mov_b32 m0, s44
	s_nop 0
	buffer_load_dwordx4 v0, s[16:19], s60 offen lds
	s_mov_b32 m0, s36
	s_nop 0
	buffer_load_dwordx4 v214, s[16:19], s60 offen lds
	s_waitcnt vmcnt(8)
	s_waitcnt lgkmcnt(0)
	s_barrier
	s_setprio 1
	v_mfma_f32_16x16x32_bf16 v[78:81], v[34:37], v[142:145], v[78:81]
	v_mfma_f32_16x16x32_bf16 v[74:77], v[58:61], v[142:145], v[74:77]
	v_mfma_f32_16x16x32_bf16 v[54:57], v[34:37], v[158:161], v[54:57]
	v_mfma_f32_16x16x32_bf16 v[50:53], v[58:61], v[158:161], v[50:53]
	v_mfma_f32_16x16x32_bf16 v[30:33], v[34:37], v[174:177], v[30:33]
	v_mfma_f32_16x16x32_bf16 v[26:29], v[58:61], v[174:177], v[26:29]
	v_mfma_f32_16x16x32_bf16 v[14:17], v[34:37], v[186:189], v[14:17]
	v_mfma_f32_16x16x32_bf16 v[10:13], v[58:61], v[186:189], v[10:13]
	v_mfma_f32_16x16x32_bf16 v[78:81], v[46:49], v[154:157], v[78:81]
	v_mfma_f32_16x16x32_bf16 v[74:77], v[70:73], v[154:157], v[74:77]
	v_mfma_f32_16x16x32_bf16 v[54:57], v[46:49], v[166:169], v[54:57]
	v_mfma_f32_16x16x32_bf16 v[50:53], v[70:73], v[166:169], v[50:53]
	v_mfma_f32_16x16x32_bf16 v[30:33], v[46:49], v[182:185], v[30:33]
	v_mfma_f32_16x16x32_bf16 v[26:29], v[70:73], v[182:185], v[26:29]
	v_mfma_f32_16x16x32_bf16 v[14:17], v[46:49], v[190:193], v[14:17]
	v_mfma_f32_16x16x32_bf16 v[10:13], v[70:73], v[190:193], v[10:13]
	v_mfma_f32_16x16x32_bf16 v[42:45], v[82:85], v[158:161], v[42:45]
	v_mfma_f32_16x16x32_bf16 v[38:41], v[106:109], v[158:161], v[38:41]
	v_mfma_f32_16x16x32_bf16 v[22:25], v[82:85], v[174:177], v[22:25]
	v_mfma_f32_16x16x32_bf16 v[18:21], v[106:109], v[174:177], v[18:21]
	v_mfma_f32_16x16x32_bf16 v[6:9], v[82:85], v[186:189], v[6:9]
	v_mfma_f32_16x16x32_bf16 v[2:5], v[106:109], v[186:189], v[2:5]
	v_mfma_f32_16x16x32_bf16 v[34:37], v[82:85], v[142:145], v[66:69]
	v_mfma_f32_16x16x32_bf16 v[46:49], v[106:109], v[142:145], v[62:65]
	v_mfma_f32_16x16x32_bf16 v[42:45], v[94:97], v[166:169], v[42:45]
	v_mfma_f32_16x16x32_bf16 v[38:41], v[118:121], v[166:169], v[38:41]
	v_mfma_f32_16x16x32_bf16 v[22:25], v[94:97], v[182:185], v[22:25]
	v_mfma_f32_16x16x32_bf16 v[18:21], v[118:121], v[182:185], v[18:21]
	v_mfma_f32_16x16x32_bf16 v[6:9], v[94:97], v[190:193], v[6:9]
	v_mfma_f32_16x16x32_bf16 v[2:5], v[118:121], v[190:193], v[2:5]
	v_mfma_f32_16x16x32_bf16 v[34:37], v[94:97], v[154:157], v[34:37]
	v_mfma_f32_16x16x32_bf16 v[46:49], v[118:121], v[154:157], v[46:49]
	s_setprio 0
	s_barrier
; #define PG8_WAIT_V(n) asm volatile("s_waitcnt vmcnt(" #n ")" ::: "memory")
; template <class Epi, bool ALIGN_EPI, bool SP2, class Hook>
; __device__ __forceinline__ void gemm_phase(LAS unsigned char* lds, const Gemm g, const StaticOrder& S, const Epi& E, Acc& acc, const bool fresh, const Hook& H, const int wave_id) {
;     ...
;         for (int t = t0; t < nt; t += 2) {
;             const bool last = (t == nt - 2);
;             const Src a1 = cA + (size_t)(t + 1) * kstep;
;             const Src a2 = last ? nA : cA + (size_t)(t + 2) * kstep, b2 = last ? nB : cB + (size_t)(t + 2) * kstep;
;             const Src a3 = a2 + kstep, b3 = b2 + kstep;
;             if (last && has_next) H(nxt);
;             if constexpr (SP2) {
;             PG8_TRIP_SP2(PG8_WAIT_V(8));
	v_add_u32_e32 v70, 0x18000, v216
	v_add_u32_e32 v118, 0x1c000, v216
	ds_read_b128 v[58:61], v70
	ds_read_b128 v[62:65], v70 offset:1024
	ds_read_b128 v[66:69], v70 offset:2048
	ds_read_b128 v[70:73], v70 offset:3072
	ds_read_b128 v[82:85], v118
	ds_read_b128 v[94:97], v118 offset:1024
	ds_read_b128 v[106:109], v118 offset:2048
	ds_read_b128 v[118:121], v118 offset:3072
	s_add_i32 s60, s60, 0x20000
	s_mov_b32 m0, s37
	ds_read_b128 v[142:145], v217 offset:32768
	ds_read_b128 v[154:157], v217 offset:33792
	ds_read_b128 v[166:169], v217 offset:34816
	ds_read_b128 v[174:177], v217 offset:35840
	ds_read_b128 v[182:185], v217 offset:36864
	ds_read_b128 v[186:189], v217 offset:37888
	ds_read_b128 v[190:193], v217 offset:38912
	ds_read_b128 v[194:197], v217 offset:39936
	buffer_load_dwordx4 v0, s[16:19], s60 offen lds
	s_mov_b32 m0, s38
	s_nop 0
	buffer_load_dwordx4 v214, s[16:19], s60 offen lds
	s_waitcnt vmcnt(8)
	s_waitcnt lgkmcnt(0)
	s_barrier
	s_setprio 1
	v_mfma_f32_16x16x32_bf16 v[158:161], v[58:61], v[142:145], v[178:181]
	v_mfma_f32_16x16x32_bf16 v[178:181], v[62:65], v[154:157], v[158:161]
	v_mfma_f32_16x16x32_bf16 v[158:161], v[66:69], v[142:145], v[170:173]
	v_mfma_f32_16x16x32_bf16 v[150:153], v[58:61], v[166:169], v[150:153]
	v_mfma_f32_16x16x32_bf16 v[146:149], v[66:69], v[166:169], v[146:149]
	v_mfma_f32_16x16x32_bf16 v[126:129], v[58:61], v[182:185], v[126:129]
	v_mfma_f32_16x16x32_bf16 v[122:125], v[66:69], v[182:185], v[122:125]
	v_mfma_f32_16x16x32_bf16 v[102:105], v[58:61], v[190:193], v[102:105]
	v_mfma_f32_16x16x32_bf16 v[98:101], v[66:69], v[190:193], v[98:101]
	v_mfma_f32_16x16x32_bf16 v[170:173], v[70:73], v[154:157], v[158:161]
	v_mfma_f32_16x16x32_bf16 v[150:153], v[62:65], v[174:177], v[150:153]
	v_mfma_f32_16x16x32_bf16 v[146:149], v[70:73], v[174:177], v[146:149]
	v_mfma_f32_16x16x32_bf16 v[126:129], v[62:65], v[186:189], v[126:129]
	v_mfma_f32_16x16x32_bf16 v[122:125], v[70:73], v[186:189], v[122:125]
	v_mfma_f32_16x16x32_bf16 v[102:105], v[62:65], v[194:197], v[102:105]
	v_mfma_f32_16x16x32_bf16 v[98:101], v[70:73], v[194:197], v[98:101]
	v_mfma_f32_16x16x32_bf16 v[158:161], v[82:85], v[142:145], v[162:165]
	v_mfma_f32_16x16x32_bf16 v[130:133], v[106:109], v[142:145], v[130:133]
	v_mfma_f32_16x16x32_bf16 v[162:165], v[94:97], v[154:157], v[158:161]
	v_mfma_f32_16x16x32_bf16 v[158:161], v[118:121], v[154:157], v[130:133]
	v_mfma_f32_16x16x32_bf16 v[130:133], v[82:85], v[166:169], v[138:141]
	v_mfma_f32_16x16x32_bf16 v[138:141], v[94:97], v[174:177], v[130:133]
	v_mfma_f32_16x16x32_bf16 v[130:133], v[106:109], v[166:169], v[134:137]
	v_mfma_f32_16x16x32_bf16 v[114:117], v[82:85], v[182:185], v[114:117]
	v_mfma_f32_16x16x32_bf16 v[110:113], v[106:109], v[182:185], v[110:113]
	v_mfma_f32_16x16x32_bf16 v[90:93], v[82:85], v[190:193], v[90:93]
	v_mfma_f32_16x16x32_bf16 v[86:89], v[106:109], v[190:193], v[86:89]
	v_mfma_f32_16x16x32_bf16 v[134:137], v[118:121], v[174:177], v[130:133]
	v_mfma_f32_16x16x32_bf16 v[114:117], v[94:97], v[186:189], v[114:117]
	v_mfma_f32_16x16x32_bf16 v[110:113], v[118:121], v[186:189], v[110:113]
	v_mfma_f32_16x16x32_bf16 v[90:93], v[94:97], v[194:197], v[90:93]
	v_mfma_f32_16x16x32_bf16 v[86:89], v[118:121], v[194:197], v[86:89]
	s_setprio 0
	s_barrier
	s_mov_b32 m0, s39
	s_or_b32 s60, s58, 0x80
	ds_read_b128 v[130:133], v217 offset:49152
	ds_read_b128 v[142:145], v217 offset:50176
	ds_read_b128 v[154:157], v217 offset:51200
	ds_read_b128 v[166:169], v217 offset:52224
	ds_read_b128 v[174:177], v217 offset:53248
	ds_read_b128 v[182:185], v217 offset:54272
	ds_read_b128 v[186:189], v217 offset:55296
	ds_read_b128 v[190:193], v217 offset:56320
	buffer_load_dwordx4 v199, s[12:15], s60 offen lds
	s_mov_b32 m0, s40
	s_add_i32 s58, s58, 0x20080
	buffer_load_dwordx4 v215, s[12:15], s60 offen lds
	s_mov_b32 m0, s43
	s_nop 0
	buffer_load_dwordx4 v199, s[12:15], s58 offen lds
	s_mov_b32 m0, s42
	s_nop 0
	buffer_load_dwordx4 v215, s[12:15], s58 offen lds
	s_mov_b32 m0, s41
	s_nop 0
	buffer_load_dwordx4 v0, s[16:19], s59 offen lds
	s_mov_b32 m0, s33
	s_nop 0
	buffer_load_dwordx4 v214, s[16:19], s59 offen lds
	s_waitcnt vmcnt(8)
	s_waitcnt lgkmcnt(0)
	s_barrier
	s_setprio 1
	v_mfma_f32_16x16x32_bf16 v[78:81], v[58:61], v[130:133], v[78:81]
	v_mfma_f32_16x16x32_bf16 v[74:77], v[66:69], v[130:133], v[74:77]
	v_mfma_f32_16x16x32_bf16 v[54:57], v[58:61], v[154:157], v[54:57]
	v_mfma_f32_16x16x32_bf16 v[50:53], v[66:69], v[154:157], v[50:53]
	v_mfma_f32_16x16x32_bf16 v[30:33], v[58:61], v[174:177], v[30:33]
	v_mfma_f32_16x16x32_bf16 v[26:29], v[66:69], v[174:177], v[26:29]
	v_mfma_f32_16x16x32_bf16 v[14:17], v[58:61], v[186:189], v[14:17]
	v_mfma_f32_16x16x32_bf16 v[10:13], v[66:69], v[186:189], v[10:13]
	v_mfma_f32_16x16x32_bf16 v[78:81], v[62:65], v[142:145], v[78:81]
	v_mfma_f32_16x16x32_bf16 v[74:77], v[70:73], v[142:145], v[74:77]
	v_mfma_f32_16x16x32_bf16 v[54:57], v[62:65], v[166:169], v[54:57]
	v_mfma_f32_16x16x32_bf16 v[50:53], v[70:73], v[166:169], v[50:53]
	v_mfma_f32_16x16x32_bf16 v[30:33], v[62:65], v[182:185], v[30:33]
	v_mfma_f32_16x16x32_bf16 v[26:29], v[70:73], v[182:185], v[26:29]
	v_mfma_f32_16x16x32_bf16 v[14:17], v[62:65], v[190:193], v[14:17]
	v_mfma_f32_16x16x32_bf16 v[10:13], v[70:73], v[190:193], v[10:13]
	v_mfma_f32_16x16x32_bf16 v[34:37], v[82:85], v[130:133], v[34:37]
	v_mfma_f32_16x16x32_bf16 v[66:69], v[94:97], v[142:145], v[34:37]
	v_mfma_f32_16x16x32_bf16 v[34:37], v[106:109], v[130:133], v[46:49]
	v_mfma_f32_16x16x32_bf16 v[62:65], v[118:121], v[142:145], v[34:37]
	v_mfma_f32_16x16x32_bf16 v[34:37], v[82:85], v[154:157], v[42:45]
	v_mfma_f32_16x16x32_bf16 v[42:45], v[94:97], v[166:169], v[34:37]
	v_mfma_f32_16x16x32_bf16 v[34:37], v[106:109], v[154:157], v[38:41]
	v_mfma_f32_16x16x32_bf16 v[22:25], v[82:85], v[174:177], v[22:25]
	v_mfma_f32_16x16x32_bf16 v[18:21], v[106:109], v[174:177], v[18:21]
	v_mfma_f32_16x16x32_bf16 v[6:9], v[82:85], v[186:189], v[6:9]
	v_mfma_f32_16x16x32_bf16 v[2:5], v[106:109], v[186:189], v[2:5]
	v_mfma_f32_16x16x32_bf16 v[38:41], v[118:121], v[166:169], v[34:37]
	v_mfma_f32_16x16x32_bf16 v[22:25], v[94:97], v[182:185], v[22:25]
	v_mfma_f32_16x16x32_bf16 v[18:21], v[118:121], v[182:185], v[18:21]
	v_mfma_f32_16x16x32_bf16 v[6:9], v[94:97], v[190:193], v[6:9]
	v_mfma_f32_16x16x32_bf16 v[2:5], v[118:121], v[190:193], v[2:5]
	s_setprio 0
	s_barrier
	s_add_i32 s57, s57, 2
	s_addk_i32 s55, 0x100
	s_addk_i32 s56, 0x100
	s_cmp_gt_u32 s57, 5
	s_cbranch_scc0 .LBB0_903
	v_readlane_b32 s8, v251, 45
	v_readlane_b32 s9, v251, 46
	s_and_b64 vcc, exec, s[8:9]
	s_cbranch_vccz .LBB0_906
	s_barrier

; #define PG8_WAIT_V(n) asm volatile("s_waitcnt vmcnt(" #n ")" ::: "memory")
; template <class Epi, bool ALIGN_EPI, bool SP2, class Hook>
; __device__ __forceinline__ void gemm_phase(LAS unsigned char* lds, const Gemm g, const StaticOrder& S, const Epi& E, Acc& acc, const bool fresh, const Hook& H, const int wave_id) {
;     ...
;         for (int t = t0; t < nt; t += 2) {
;             const bool last = (t == nt - 2);
;             const Src a1 = cA + (size_t)(t + 1) * kstep;
;             const Src a2 = last ? nA : cA + (size_t)(t + 2) * kstep, b2 = last ? nB : cB + (size_t)(t + 2) * kstep;
;             const Src a3 = a2 + kstep, b3 = b2 + kstep;
;             if (last && has_next) H(nxt);
;             if constexpr (SP2) {
;             PG8_TRIP_SP2(PG8_WAIT_V(8));
.LBB0_1029:
.LBB0_1030:
	v_add_u32_e32 v0, 0x10000, v230
	s_waitcnt vmcnt(0)
	ds_read_b128 v[130:133], v0
	ds_read_b128 v[134:137], v0 offset:1024
	ds_read_b128 v[138:141], v0 offset:2048
	ds_read_b128 v[142:145], v0 offset:3072
	v_add_u32_e32 v0, 0x14000, v230
	ds_read_b128 v[146:149], v0
	ds_read_b128 v[150:153], v0 offset:1024
	ds_read_b128 v[154:157], v0 offset:2048
	ds_read_b128 v[158:161], v0 offset:3072
	s_lshl_b32 s55, s20, 7
	s_add_i32 s18, s73, s55
	s_and_b64 s[12:13], s[16:17], exec
	s_cselect_b32 s13, s31, s9
	s_cselect_b32 s12, s30, s8
	s_cselect_b32 s15, s35, s11
	s_cselect_b32 s14, s34, s10
	s_cselect_b32 s56, s68, s18
	s_add_i32 s21, s74, s55
	s_and_b64 s[16:17], s[16:17], exec
	s_cselect_b32 s54, s69, s21
	s_cselect_b32 s17, s51, s77
	s_cselect_b32 s16, s50, s76
	s_cselect_b32 s19, s53, s7
	s_cselect_b32 s18, s52, s6
	s_or_b32 s21, s56, 0x80
	s_or_b32 s57, s54, 0x80
	s_add_i32 s55, s55, s75
	s_mov_b32 m0, s45
	ds_read_b128 v[162:165], v231
	ds_read_b128 v[166:169], v231 offset:1024
	ds_read_b128 v[170:173], v231 offset:2048
	ds_read_b128 v[174:177], v231 offset:3072
	ds_read_b128 v[178:181], v231 offset:4096
	ds_read_b128 v[182:185], v231 offset:5120
	ds_read_b128 v[186:189], v231 offset:6144
	ds_read_b128 v[190:193], v231 offset:7168
	buffer_load_dwordx4 v199, s[8:11], s55 offen lds
	s_mov_b32 m0, s46
	s_nop 0
	buffer_load_dwordx4 v228, s[8:11], s55 offen lds
	s_waitcnt vmcnt(8)
	s_waitcnt lgkmcnt(0)
	s_barrier
	s_setprio 1
	v_mfma_f32_16x16x32_bf16 v[126:129], v[130:133], v[162:165], v[126:129]
	v_mfma_f32_16x16x32_bf16 v[122:125], v[138:141], v[162:165], v[122:125]
	v_mfma_f32_16x16x32_bf16 v[118:121], v[130:133], v[170:173], v[118:121]
	v_mfma_f32_16x16x32_bf16 v[114:117], v[138:141], v[170:173], v[114:117]
	v_mfma_f32_16x16x32_bf16 v[110:113], v[130:133], v[178:181], v[110:113]
	v_mfma_f32_16x16x32_bf16 v[106:109], v[138:141], v[178:181], v[106:109]
	v_mfma_f32_16x16x32_bf16 v[102:105], v[130:133], v[186:189], v[102:105]
	v_mfma_f32_16x16x32_bf16 v[98:101], v[138:141], v[186:189], v[98:101]
	v_mfma_f32_16x16x32_bf16 v[126:129], v[134:137], v[166:169], v[126:129]
	v_mfma_f32_16x16x32_bf16 v[122:125], v[142:145], v[166:169], v[122:125]
	v_mfma_f32_16x16x32_bf16 v[118:121], v[134:137], v[174:177], v[118:121]
	v_mfma_f32_16x16x32_bf16 v[114:117], v[142:145], v[174:177], v[114:117]
	v_mfma_f32_16x16x32_bf16 v[110:113], v[134:137], v[182:185], v[110:113]
	v_mfma_f32_16x16x32_bf16 v[106:109], v[142:145], v[182:185], v[106:109]
	v_mfma_f32_16x16x32_bf16 v[102:105], v[134:137], v[190:193], v[102:105]
	v_mfma_f32_16x16x32_bf16 v[98:101], v[142:145], v[190:193], v[98:101]
	v_mfma_f32_16x16x32_bf16 v[94:97], v[146:149], v[162:165], v[94:97]
	v_mfma_f32_16x16x32_bf16 v[90:93], v[154:157], v[162:165], v[90:93]
	v_mfma_f32_16x16x32_bf16 v[86:89], v[146:149], v[170:173], v[86:89]
	v_mfma_f32_16x16x32_bf16 v[82:85], v[154:157], v[170:173], v[82:85]
	v_mfma_f32_16x16x32_bf16 v[78:81], v[146:149], v[178:181], v[78:81]
	v_mfma_f32_16x16x32_bf16 v[74:77], v[154:157], v[178:181], v[74:77]
	v_mfma_f32_16x16x32_bf16 v[70:73], v[146:149], v[186:189], v[70:73]
	v_mfma_f32_16x16x32_bf16 v[66:69], v[154:157], v[186:189], v[66:69]
	v_mfma_f32_16x16x32_bf16 v[94:97], v[150:153], v[166:169], v[94:97]
	v_mfma_f32_16x16x32_bf16 v[90:93], v[158:161], v[166:169], v[90:93]
	v_mfma_f32_16x16x32_bf16 v[86:89], v[150:153], v[174:177], v[86:89]
	v_mfma_f32_16x16x32_bf16 v[82:85], v[158:161], v[174:177], v[82:85]
	v_mfma_f32_16x16x32_bf16 v[78:81], v[150:153], v[182:185], v[78:81]
	v_mfma_f32_16x16x32_bf16 v[74:77], v[158:161], v[182:185], v[74:77]
	v_mfma_f32_16x16x32_bf16 v[70:73], v[150:153], v[190:193], v[70:73]
	v_mfma_f32_16x16x32_bf16 v[66:69], v[158:161], v[190:193], v[66:69]
	s_setprio 0
	s_barrier
	s_mov_b32 m0, s92
	ds_read_b128 v[162:165], v231 offset:16384
	ds_read_b128 v[166:169], v231 offset:17408
	ds_read_b128 v[170:173], v231 offset:18432
	ds_read_b128 v[174:177], v231 offset:19456
	ds_read_b128 v[178:181], v231 offset:20480
	ds_read_b128 v[182:185], v231 offset:21504
	ds_read_b128 v[186:189], v231 offset:22528
	ds_read_b128 v[190:193], v231 offset:23552
	buffer_load_dwordx4 v227, s[16:19], s54 offen lds
	s_mov_b32 m0, s93
	s_add_i32 s55, s54, 0x20000
	buffer_load_dwordx4 v229, s[16:19], s54 offen lds
	s_mov_b32 m0, s94
	s_nop 0
	buffer_load_dwordx4 v227, s[16:19], s55 offen lds
	s_mov_b32 m0, s95
	s_nop 0
	buffer_load_dwordx4 v229, s[16:19], s55 offen lds
	s_mov_b32 m0, s44
	s_nop 0
	buffer_load_dwordx4 v199, s[12:15], s56 offen lds
	s_mov_b32 m0, s36
	s_nop 0
	buffer_load_dwordx4 v228, s[12:15], s56 offen lds
	s_waitcnt vmcnt(8)
	s_waitcnt lgkmcnt(0)
	s_barrier
; #define PG8_WAIT_V(n) asm volatile("s_waitcnt vmcnt(" #n ")" ::: "memory")
; template <class Epi, bool ALIGN_EPI, bool SP2, class Hook>
; __device__ __forceinline__ void gemm_phase(LAS unsigned char* lds, const Gemm g, const StaticOrder& S, const Epi& E, Acc& acc, const bool fresh, const Hook& H, const int wave_id) {
;     ...
;         for (int t = t0; t < nt; t += 2) {
;             const bool last = (t == nt - 2);
;             const Src a1 = cA + (size_t)(t + 1) * kstep;
;             const Src a2 = last ? nA : cA + (size_t)(t + 2) * kstep, b2 = last ? nB : cB + (size_t)(t + 2) * kstep;
;             const Src a3 = a2 + kstep, b3 = b2 + kstep;
;             if (last && has_next) H(nxt);
;             if constexpr (SP2) {
;             PG8_TRIP_SP2(PG8_WAIT_V(8));
	s_setprio 1
	v_mfma_f32_16x16x32_bf16 v[62:65], v[130:133], v[162:165], v[62:65]
	v_mfma_f32_16x16x32_bf16 v[58:61], v[138:141], v[162:165], v[58:61]
	v_mfma_f32_16x16x32_bf16 v[54:57], v[130:133], v[170:173], v[54:57]
	v_mfma_f32_16x16x32_bf16 v[50:53], v[138:141], v[170:173], v[50:53]
	v_mfma_f32_16x16x32_bf16 v[46:49], v[130:133], v[178:181], v[46:49]
	v_mfma_f32_16x16x32_bf16 v[42:45], v[138:141], v[178:181], v[42:45]
	v_mfma_f32_16x16x32_bf16 v[38:41], v[130:133], v[186:189], v[38:41]
	v_mfma_f32_16x16x32_bf16 v[34:37], v[138:141], v[186:189], v[34:37]
	v_mfma_f32_16x16x32_bf16 v[62:65], v[134:137], v[166:169], v[62:65]
	v_mfma_f32_16x16x32_bf16 v[58:61], v[142:145], v[166:169], v[58:61]
	v_mfma_f32_16x16x32_bf16 v[54:57], v[134:137], v[174:177], v[54:57]
	v_mfma_f32_16x16x32_bf16 v[50:53], v[142:145], v[174:177], v[50:53]
	v_mfma_f32_16x16x32_bf16 v[46:49], v[134:137], v[182:185], v[46:49]
	v_mfma_f32_16x16x32_bf16 v[42:45], v[142:145], v[182:185], v[42:45]
	v_mfma_f32_16x16x32_bf16 v[38:41], v[134:137], v[190:193], v[38:41]
	v_mfma_f32_16x16x32_bf16 v[34:37], v[142:145], v[190:193], v[34:37]
	v_mfma_f32_16x16x32_bf16 v[30:33], v[146:149], v[162:165], v[30:33]
	v_mfma_f32_16x16x32_bf16 v[26:29], v[154:157], v[162:165], v[26:29]
	v_mfma_f32_16x16x32_bf16 v[22:25], v[146:149], v[170:173], v[22:25]
	v_mfma_f32_16x16x32_bf16 v[18:21], v[154:157], v[170:173], v[18:21]
	v_mfma_f32_16x16x32_bf16 v[14:17], v[146:149], v[178:181], v[14:17]
	v_mfma_f32_16x16x32_bf16 v[10:13], v[154:157], v[178:181], v[10:13]
	v_mfma_f32_16x16x32_bf16 v[6:9], v[146:149], v[186:189], v[6:9]
	v_mfma_f32_16x16x32_bf16 v[2:5], v[154:157], v[186:189], v[2:5]
	v_mfma_f32_16x16x32_bf16 v[30:33], v[150:153], v[166:169], v[30:33]
	v_mfma_f32_16x16x32_bf16 v[26:29], v[158:161], v[166:169], v[26:29]
	v_mfma_f32_16x16x32_bf16 v[22:25], v[150:153], v[174:177], v[22:25]
	v_mfma_f32_16x16x32_bf16 v[18:21], v[158:161], v[174:177], v[18:21]
	v_mfma_f32_16x16x32_bf16 v[14:17], v[150:153], v[182:185], v[14:17]
	v_mfma_f32_16x16x32_bf16 v[10:13], v[158:161], v[182:185], v[10:13]
	v_mfma_f32_16x16x32_bf16 v[6:9], v[150:153], v[190:193], v[6:9]
	v_mfma_f32_16x16x32_bf16 v[2:5], v[158:161], v[190:193], v[2:5]
	s_setprio 0
	s_barrier
	v_add_u32_e32 v0, 0x18000, v230
	ds_read_b128 v[130:133], v0
	ds_read_b128 v[134:137], v0 offset:1024
	ds_read_b128 v[138:141], v0 offset:2048
	ds_read_b128 v[142:145], v0 offset:3072
	v_add_u32_e32 v0, 0x1c000, v230
	ds_read_b128 v[146:149], v0
	ds_read_b128 v[150:153], v0 offset:1024
	ds_read_b128 v[154:157], v0 offset:2048
	ds_read_b128 v[158:161], v0 offset:3072
	s_add_i32 s56, s56, 0x20000
	s_mov_b32 m0, s37
	ds_read_b128 v[162:165], v231 offset:32768
	ds_read_b128 v[166:169], v231 offset:33792
	ds_read_b128 v[170:173], v231 offset:34816
	ds_read_b128 v[174:177], v231 offset:35840
	ds_read_b128 v[178:181], v231 offset:36864
	ds_read_b128 v[182:185], v231 offset:37888
	ds_read_b128 v[186:189], v231 offset:38912
	ds_read_b128 v[190:193], v231 offset:39936
	buffer_load_dwordx4 v199, s[12:15], s56 offen lds
	s_mov_b32 m0, s38
	s_nop 0
	buffer_load_dwordx4 v228, s[12:15], s56 offen lds
	s_waitcnt vmcnt(8)
	s_waitcnt lgkmcnt(0)
	s_barrier
	s_setprio 1
	v_mfma_f32_16x16x32_bf16 v[126:129], v[130:133], v[162:165], v[126:129]
	v_mfma_f32_16x16x32_bf16 v[122:125], v[138:141], v[162:165], v[122:125]
	v_mfma_f32_16x16x32_bf16 v[118:121], v[130:133], v[170:173], v[118:121]
	v_mfma_f32_16x16x32_bf16 v[114:117], v[138:141], v[170:173], v[114:117]
	v_mfma_f32_16x16x32_bf16 v[110:113], v[130:133], v[178:181], v[110:113]
	v_mfma_f32_16x16x32_bf16 v[106:109], v[138:141], v[178:181], v[106:109]
	v_mfma_f32_16x16x32_bf16 v[102:105], v[130:133], v[186:189], v[102:105]
	v_mfma_f32_16x16x32_bf16 v[98:101], v[138:141], v[186:189], v[98:101]
	v_mfma_f32_16x16x32_bf16 v[126:129], v[134:137], v[166:169], v[126:129]
	v_mfma_f32_16x16x32_bf16 v[122:125], v[142:145], v[166:169], v[122:125]
	v_mfma_f32_16x16x32_bf16 v[118:121], v[134:137], v[174:177], v[118:121]
	v_mfma_f32_16x16x32_bf16 v[114:117], v[142:145], v[174:177], v[114:117]
	v_mfma_f32_16x16x32_bf16 v[110:113], v[134:137], v[182:185], v[110:113]
	v_mfma_f32_16x16x32_bf16 v[106:109], v[142:145], v[182:185], v[106:109]
	v_mfma_f32_16x16x32_bf16 v[102:105], v[134:137], v[190:193], v[102:105]
	v_mfma_f32_16x16x32_bf16 v[98:101], v[142:145], v[190:193], v[98:101]
	v_mfma_f32_16x16x32_bf16 v[94:97], v[146:149], v[162:165], v[94:97]
	v_mfma_f32_16x16x32_bf16 v[90:93], v[154:157], v[162:165], v[90:93]
	v_mfma_f32_16x16x32_bf16 v[86:89], v[146:149], v[170:173], v[86:89]
	v_mfma_f32_16x16x32_bf16 v[82:85], v[154:157], v[170:173], v[82:85]
	v_mfma_f32_16x16x32_bf16 v[78:81], v[146:149], v[178:181], v[78:81]
	v_mfma_f32_16x16x32_bf16 v[74:77], v[154:157], v[178:181], v[74:77]
	v_mfma_f32_16x16x32_bf16 v[70:73], v[146:149], v[186:189], v[70:73]
	v_mfma_f32_16x16x32_bf16 v[66:69], v[154:157], v[186:189], v[66:69]
	v_mfma_f32_16x16x32_bf16 v[94:97], v[150:153], v[166:169], v[94:97]
	v_mfma_f32_16x16x32_bf16 v[90:93], v[158:161], v[166:169], v[90:93]
	v_mfma_f32_16x16x32_bf16 v[86:89], v[150:153], v[174:177], v[86:89]
	v_mfma_f32_16x16x32_bf16 v[82:85], v[158:161], v[174:177], v[82:85]
	v_mfma_f32_16x16x32_bf16 v[78:81], v[150:153], v[182:185], v[78:81]
	v_mfma_f32_16x16x32_bf16 v[74:77], v[158:161], v[182:185], v[74:77]
	v_mfma_f32_16x16x32_bf16 v[70:73], v[150:153], v[190:193], v[70:73]
	v_mfma_f32_16x16x32_bf16 v[66:69], v[158:161], v[190:193], v[66:69]
	s_setprio 0
	s_barrier
; #define PG8_WAIT_V(n) asm volatile("s_waitcnt vmcnt(" #n ")" ::: "memory")
; template <class Epi, bool ALIGN_EPI, bool SP2, class Hook>
; __device__ __forceinline__ void gemm_phase(LAS unsigned char* lds, const Gemm g, const StaticOrder& S, const Epi& E, Acc& acc, const bool fresh, const Hook& H, const int wave_id) {
;     ...
;         for (int t = t0; t < nt; t += 2) {
;             const bool last = (t == nt - 2);
;             const Src a1 = cA + (size_t)(t + 1) * kstep;
;             const Src a2 = last ? nA : cA + (size_t)(t + 2) * kstep, b2 = last ? nB : cB + (size_t)(t + 2) * kstep;
;             const Src a3 = a2 + kstep, b3 = b2 + kstep;
;             if (last && has_next) H(nxt);
;             if constexpr (SP2) {
;             PG8_TRIP_SP2(PG8_WAIT_V(8));
	s_mov_b32 m0, s39
	ds_read_b128 v[162:165], v231 offset:49152
	ds_read_b128 v[166:169], v231 offset:50176
	ds_read_b128 v[170:173], v231 offset:51200
	ds_read_b128 v[174:177], v231 offset:52224
	ds_read_b128 v[178:181], v231 offset:53248
	ds_read_b128 v[182:185], v231 offset:54272
	ds_read_b128 v[186:189], v231 offset:55296
	ds_read_b128 v[190:193], v231 offset:56320
	buffer_load_dwordx4 v227, s[16:19], s57 offen lds
	s_mov_b32 m0, s40
	s_add_i32 s54, s54, 0x20080
	buffer_load_dwordx4 v229, s[16:19], s57 offen lds
	s_mov_b32 m0, s43
	s_nop 0
	buffer_load_dwordx4 v227, s[16:19], s54 offen lds
	s_mov_b32 m0, s42
	s_nop 0
	buffer_load_dwordx4 v229, s[16:19], s54 offen lds
	s_mov_b32 m0, s41
	s_nop 0
	buffer_load_dwordx4 v199, s[12:15], s21 offen lds
	s_mov_b32 m0, s33
	s_nop 0
	buffer_load_dwordx4 v228, s[12:15], s21 offen lds
	s_waitcnt vmcnt(8)
	s_waitcnt lgkmcnt(0)
	s_barrier
	s_setprio 1
	v_mfma_f32_16x16x32_bf16 v[62:65], v[130:133], v[162:165], v[62:65]
	v_mfma_f32_16x16x32_bf16 v[58:61], v[138:141], v[162:165], v[58:61]
	v_mfma_f32_16x16x32_bf16 v[54:57], v[130:133], v[170:173], v[54:57]
	v_mfma_f32_16x16x32_bf16 v[50:53], v[138:141], v[170:173], v[50:53]
	v_mfma_f32_16x16x32_bf16 v[46:49], v[130:133], v[178:181], v[46:49]
	v_mfma_f32_16x16x32_bf16 v[42:45], v[138:141], v[178:181], v[42:45]
	v_mfma_f32_16x16x32_bf16 v[38:41], v[130:133], v[186:189], v[38:41]
	v_mfma_f32_16x16x32_bf16 v[34:37], v[138:141], v[186:189], v[34:37]
	v_mfma_f32_16x16x32_bf16 v[62:65], v[134:137], v[166:169], v[62:65]
	v_mfma_f32_16x16x32_bf16 v[58:61], v[142:145], v[166:169], v[58:61]
	v_mfma_f32_16x16x32_bf16 v[54:57], v[134:137], v[174:177], v[54:57]
	v_mfma_f32_16x16x32_bf16 v[50:53], v[142:145], v[174:177], v[50:53]
	v_mfma_f32_16x16x32_bf16 v[46:49], v[134:137], v[182:185], v[46:49]
	v_mfma_f32_16x16x32_bf16 v[42:45], v[142:145], v[182:185], v[42:45]
	v_mfma_f32_16x16x32_bf16 v[38:41], v[134:137], v[190:193], v[38:41]
	v_mfma_f32_16x16x32_bf16 v[34:37], v[142:145], v[190:193], v[34:37]
	v_mfma_f32_16x16x32_bf16 v[30:33], v[146:149], v[162:165], v[30:33]
	v_mfma_f32_16x16x32_bf16 v[26:29], v[154:157], v[162:165], v[26:29]
	v_mfma_f32_16x16x32_bf16 v[22:25], v[146:149], v[170:173], v[22:25]
	v_mfma_f32_16x16x32_bf16 v[18:21], v[154:157], v[170:173], v[18:21]
	v_mfma_f32_16x16x32_bf16 v[14:17], v[146:149], v[178:181], v[14:17]
	v_mfma_f32_16x16x32_bf16 v[10:13], v[154:157], v[178:181], v[10:13]
	v_mfma_f32_16x16x32_bf16 v[6:9], v[146:149], v[186:189], v[6:9]
	v_mfma_f32_16x16x32_bf16 v[2:5], v[154:157], v[186:189], v[2:5]
	v_mfma_f32_16x16x32_bf16 v[30:33], v[150:153], v[166:169], v[30:33]
	v_mfma_f32_16x16x32_bf16 v[26:29], v[158:161], v[166:169], v[26:29]
	v_mfma_f32_16x16x32_bf16 v[22:25], v[150:153], v[174:177], v[22:25]
	v_mfma_f32_16x16x32_bf16 v[18:21], v[158:161], v[174:177], v[18:21]
	v_mfma_f32_16x16x32_bf16 v[14:17], v[150:153], v[182:185], v[14:17]
	v_mfma_f32_16x16x32_bf16 v[10:13], v[158:161], v[182:185], v[10:13]
	v_mfma_f32_16x16x32_bf16 v[6:9], v[150:153], v[190:193], v[6:9]
	v_mfma_f32_16x16x32_bf16 v[2:5], v[158:161], v[190:193], v[2:5]
	s_setprio 0
	s_barrier
	s_add_i32 s12, s20, 2
	s_cmp_gt_u32 s20, 5
	s_cbranch_scc1 .LBB0_1032
	s_mov_b32 s20, s12
	s_branch .LBB0_951

; #define PG8_WAIT_V(n) asm volatile("s_waitcnt vmcnt(" #n ")" ::: "memory")
; template <class Epi, bool ALIGN_EPI, bool SP2, class Hook>
; __device__ __forceinline__ void gemm_phase(LAS unsigned char* lds, const Gemm g, const StaticOrder& S, const Epi& E, Acc& acc, const bool fresh, const Hook& H, const int wave_id) {
;     ...
;         for (int t = t0; t < nt; t += 2) {
;             const bool last = (t == nt - 2);
;             const Src a1 = cA + (size_t)(t + 1) * kstep;
;             const Src a2 = last ? nA : cA + (size_t)(t + 2) * kstep, b2 = last ? nB : cB + (size_t)(t + 2) * kstep;
;             const Src a3 = a2 + kstep, b3 = b2 + kstep;
;             if (last && has_next) H(nxt);
;             if constexpr (SP2) {
;             PG8_TRIP_SP2(PG8_WAIT_V(8));
.LBB0_1235:
	v_add_u32_e32 v142, 0x10000, v161
	v_add_u32_e32 v163, 0x14000, v161
	ds_read_b128 v[130:133], v142
	ds_read_b128 v[134:137], v142 offset:1024
	ds_read_b128 v[138:141], v142 offset:2048
	ds_read_b128 v[142:145], v142 offset:3072
	ds_read_b128 v[146:149], v163
	ds_read_b128 v[150:153], v163 offset:1024
	ds_read_b128 v[154:157], v163 offset:2048
	ds_read_b128 v[164:167], v163 offset:3072
	s_add_i32 s16, s2, 0xfffc0080
	s_cmp_eq_u32 s59, 12
	s_cselect_b32 s62, s55, s16
	s_cselect_b32 s17, s31, s9
	s_cselect_b32 s16, s30, s8
	s_cselect_b32 s19, s35, s51
	s_cselect_b32 s18, s34, s50
	s_cselect_b32 s60, s56, s3
	s_cselect_b32 s20, s26, s12
	s_cselect_b32 s21, s27, s13
	s_cselect_b32 s22, s28, s14
	s_cselect_b32 s23, s29, s15
	s_or_b32 s61, s62, 0x80
	s_mov_b32 m0, s45
	ds_read_b128 v[168:171], v162
	ds_read_b128 v[172:175], v162 offset:1024
	ds_read_b128 v[176:179], v162 offset:2048
	ds_read_b128 v[180:183], v162 offset:3072
	ds_read_b128 v[184:187], v162 offset:4096
	ds_read_b128 v[188:191], v162 offset:5120
	ds_read_b128 v[192:195], v162 offset:6144
	ds_read_b128 v[200:203], v162 offset:7168
	buffer_load_dwordx4 v0, s[12:15], s2 offen lds
	s_mov_b32 m0, s46
	s_nop 0
	buffer_load_dwordx4 v159, s[12:15], s2 offen lds
	s_waitcnt vmcnt(8)
	s_waitcnt lgkmcnt(0)
	s_barrier
	s_setprio 1
	v_mfma_f32_16x16x32_bf16 v[126:129], v[130:133], v[168:171], v[126:129]
	v_mfma_f32_16x16x32_bf16 v[122:125], v[138:141], v[168:171], v[122:125]
	v_mfma_f32_16x16x32_bf16 v[110:113], v[130:133], v[176:179], v[110:113]
	v_mfma_f32_16x16x32_bf16 v[106:109], v[138:141], v[176:179], v[106:109]
	v_mfma_f32_16x16x32_bf16 v[94:97], v[130:133], v[184:187], v[94:97]
	v_mfma_f32_16x16x32_bf16 v[90:93], v[138:141], v[184:187], v[90:93]
	v_mfma_f32_16x16x32_bf16 v[78:81], v[130:133], v[192:195], v[78:81]
	v_mfma_f32_16x16x32_bf16 v[74:77], v[138:141], v[192:195], v[74:77]
	v_mfma_f32_16x16x32_bf16 v[126:129], v[134:137], v[172:175], v[126:129]
	v_mfma_f32_16x16x32_bf16 v[122:125], v[142:145], v[172:175], v[122:125]
	v_mfma_f32_16x16x32_bf16 v[110:113], v[134:137], v[180:183], v[110:113]
	v_mfma_f32_16x16x32_bf16 v[106:109], v[142:145], v[180:183], v[106:109]
	v_mfma_f32_16x16x32_bf16 v[94:97], v[134:137], v[188:191], v[94:97]
	v_mfma_f32_16x16x32_bf16 v[90:93], v[142:145], v[188:191], v[90:93]
	v_mfma_f32_16x16x32_bf16 v[78:81], v[134:137], v[200:203], v[78:81]
	v_mfma_f32_16x16x32_bf16 v[74:77], v[142:145], v[200:203], v[74:77]
	v_mfma_f32_16x16x32_bf16 v[118:121], v[146:149], v[168:171], v[118:121]
	v_mfma_f32_16x16x32_bf16 v[114:117], v[154:157], v[168:171], v[114:117]
	v_mfma_f32_16x16x32_bf16 v[102:105], v[146:149], v[176:179], v[102:105]
	v_mfma_f32_16x16x32_bf16 v[98:101], v[154:157], v[176:179], v[98:101]
	v_mfma_f32_16x16x32_bf16 v[86:89], v[146:149], v[184:187], v[86:89]
	v_mfma_f32_16x16x32_bf16 v[82:85], v[154:157], v[184:187], v[82:85]
	v_mfma_f32_16x16x32_bf16 v[70:73], v[146:149], v[192:195], v[70:73]
	v_mfma_f32_16x16x32_bf16 v[66:69], v[154:157], v[192:195], v[66:69]
	v_mfma_f32_16x16x32_bf16 v[118:121], v[150:153], v[172:175], v[118:121]
	v_mfma_f32_16x16x32_bf16 v[114:117], v[164:167], v[172:175], v[114:117]
	v_mfma_f32_16x16x32_bf16 v[102:105], v[150:153], v[180:183], v[102:105]
	v_mfma_f32_16x16x32_bf16 v[98:101], v[164:167], v[180:183], v[98:101]
	v_mfma_f32_16x16x32_bf16 v[86:89], v[150:153], v[188:191], v[86:89]
	v_mfma_f32_16x16x32_bf16 v[82:85], v[164:167], v[188:191], v[82:85]
	v_mfma_f32_16x16x32_bf16 v[70:73], v[150:153], v[200:203], v[70:73]
	v_mfma_f32_16x16x32_bf16 v[66:69], v[164:167], v[200:203], v[66:69]
	s_setprio 0
	s_barrier
	s_mov_b32 m0, s92
	ds_read_b128 v[168:171], v162 offset:16384
	ds_read_b128 v[172:175], v162 offset:17408
	ds_read_b128 v[176:179], v162 offset:18432
	ds_read_b128 v[180:183], v162 offset:19456
	ds_read_b128 v[184:187], v162 offset:20480
	ds_read_b128 v[188:191], v162 offset:21504
	ds_read_b128 v[192:195], v162 offset:22528
	ds_read_b128 v[200:203], v162 offset:23552
	buffer_load_dwordx4 v158, s[16:19], s60 offen lds
	s_mov_b32 m0, s93
	s_add_i32 s63, s60, 0x40000
	buffer_load_dwordx4 v160, s[16:19], s60 offen lds
	s_mov_b32 m0, s94
	s_nop 0
	buffer_load_dwordx4 v158, s[16:19], s63 offen lds
	s_mov_b32 m0, s95
	s_nop 0
	buffer_load_dwordx4 v160, s[16:19], s63 offen lds
	s_mov_b32 m0, s44
	s_nop 0
	buffer_load_dwordx4 v0, s[20:23], s62 offen lds
	s_mov_b32 m0, s36
	s_nop 0
	buffer_load_dwordx4 v159, s[20:23], s62 offen lds
	s_waitcnt vmcnt(8)
	s_waitcnt lgkmcnt(0)
	s_barrier
	s_setprio 1
	v_mfma_f32_16x16x32_bf16 v[62:65], v[130:133], v[168:171], v[62:65]
	v_mfma_f32_16x16x32_bf16 v[58:61], v[138:141], v[168:171], v[58:61]
	v_mfma_f32_16x16x32_bf16 v[46:49], v[130:133], v[176:179], v[46:49]
	v_mfma_f32_16x16x32_bf16 v[42:45], v[138:141], v[176:179], v[42:45]
	v_mfma_f32_16x16x32_bf16 v[30:33], v[130:133], v[184:187], v[30:33]
	v_mfma_f32_16x16x32_bf16 v[26:29], v[138:141], v[184:187], v[26:29]
	v_mfma_f32_16x16x32_bf16 v[14:17], v[130:133], v[192:195], v[14:17]
	v_mfma_f32_16x16x32_bf16 v[10:13], v[138:141], v[192:195], v[10:13]
	v_mfma_f32_16x16x32_bf16 v[62:65], v[134:137], v[172:175], v[62:65]
	v_mfma_f32_16x16x32_bf16 v[58:61], v[142:145], v[172:175], v[58:61]
	v_mfma_f32_16x16x32_bf16 v[46:49], v[134:137], v[180:183], v[46:49]
	v_mfma_f32_16x16x32_bf16 v[42:45], v[142:145], v[180:183], v[42:45]
	v_mfma_f32_16x16x32_bf16 v[30:33], v[134:137], v[188:191], v[30:33]
	v_mfma_f32_16x16x32_bf16 v[26:29], v[142:145], v[188:191], v[26:29]
	v_mfma_f32_16x16x32_bf16 v[14:17], v[134:137], v[200:203], v[14:17]
	v_mfma_f32_16x16x32_bf16 v[10:13], v[142:145], v[200:203], v[10:13]
	v_mfma_f32_16x16x32_bf16 v[54:57], v[146:149], v[168:171], v[54:57]
	v_mfma_f32_16x16x32_bf16 v[50:53], v[154:157], v[168:171], v[50:53]
	v_mfma_f32_16x16x32_bf16 v[38:41], v[146:149], v[176:179], v[38:41]
	v_mfma_f32_16x16x32_bf16 v[34:37], v[154:157], v[176:179], v[34:37]
	v_mfma_f32_16x16x32_bf16 v[22:25], v[146:149], v[184:187], v[22:25]
	v_mfma_f32_16x16x32_bf16 v[18:21], v[154:157], v[184:187], v[18:21]
	v_mfma_f32_16x16x32_bf16 v[6:9], v[146:149], v[192:195], v[6:9]
	v_mfma_f32_16x16x32_bf16 v[2:5], v[154:157], v[192:195], v[2:5]
	v_mfma_f32_16x16x32_bf16 v[54:57], v[150:153], v[172:175], v[54:57]
	v_mfma_f32_16x16x32_bf16 v[50:53], v[164:167], v[172:175], v[50:53]
	v_mfma_f32_16x16x32_bf16 v[38:41], v[150:153], v[180:183], v[38:41]
	v_mfma_f32_16x16x32_bf16 v[34:37], v[164:167], v[180:183], v[34:37]
	v_mfma_f32_16x16x32_bf16 v[22:25], v[150:153], v[188:191], v[22:25]
	v_mfma_f32_16x16x32_bf16 v[18:21], v[164:167], v[188:191], v[18:21]
	v_mfma_f32_16x16x32_bf16 v[6:9], v[150:153], v[200:203], v[6:9]
	v_mfma_f32_16x16x32_bf16 v[2:5], v[164:167], v[200:203], v[2:5]
	s_setprio 0
	s_barrier
; #define PG8_WAIT_V(n) asm volatile("s_waitcnt vmcnt(" #n ")" ::: "memory")
; template <class Epi, bool ALIGN_EPI, bool SP2, class Hook>
; __device__ __forceinline__ void gemm_phase(LAS unsigned char* lds, const Gemm g, const StaticOrder& S, const Epi& E, Acc& acc, const bool fresh, const Hook& H, const int wave_id) {
;     ...
;         for (int t = t0; t < nt; t += 2) {
;             const bool last = (t == nt - 2);
;             const Src a1 = cA + (size_t)(t + 1) * kstep;
;             const Src a2 = last ? nA : cA + (size_t)(t + 2) * kstep, b2 = last ? nB : cB + (size_t)(t + 2) * kstep;
;             const Src a3 = a2 + kstep, b3 = b2 + kstep;
;             if (last && has_next) H(nxt);
;             if constexpr (SP2) {
;             PG8_TRIP_SP2(PG8_WAIT_V(8));
	v_add_u32_e32 v142, 0x18000, v161
	v_add_u32_e32 v163, 0x1c000, v161
	ds_read_b128 v[130:133], v142
	ds_read_b128 v[134:137], v142 offset:1024
	ds_read_b128 v[138:141], v142 offset:2048
	ds_read_b128 v[142:145], v142 offset:3072
	ds_read_b128 v[146:149], v163
	ds_read_b128 v[150:153], v163 offset:1024
	ds_read_b128 v[154:157], v163 offset:2048
	ds_read_b128 v[164:167], v163 offset:3072
	s_add_i32 s62, s62, 0x40000
	s_mov_b32 m0, s37
	ds_read_b128 v[168:171], v162 offset:32768
	ds_read_b128 v[172:175], v162 offset:33792
	ds_read_b128 v[176:179], v162 offset:34816
	ds_read_b128 v[180:183], v162 offset:35840
	ds_read_b128 v[184:187], v162 offset:36864
	ds_read_b128 v[188:191], v162 offset:37888
	ds_read_b128 v[192:195], v162 offset:38912
	ds_read_b128 v[200:203], v162 offset:39936
	buffer_load_dwordx4 v0, s[20:23], s62 offen lds
	s_mov_b32 m0, s38
	s_nop 0
	buffer_load_dwordx4 v159, s[20:23], s62 offen lds
	s_waitcnt vmcnt(8)
	s_waitcnt lgkmcnt(0)
	s_barrier
	s_setprio 1
	v_mfma_f32_16x16x32_bf16 v[126:129], v[130:133], v[168:171], v[126:129]
	v_mfma_f32_16x16x32_bf16 v[122:125], v[138:141], v[168:171], v[122:125]
	v_mfma_f32_16x16x32_bf16 v[110:113], v[130:133], v[176:179], v[110:113]
	v_mfma_f32_16x16x32_bf16 v[106:109], v[138:141], v[176:179], v[106:109]
	v_mfma_f32_16x16x32_bf16 v[94:97], v[130:133], v[184:187], v[94:97]
	v_mfma_f32_16x16x32_bf16 v[90:93], v[138:141], v[184:187], v[90:93]
	v_mfma_f32_16x16x32_bf16 v[78:81], v[130:133], v[192:195], v[78:81]
	v_mfma_f32_16x16x32_bf16 v[74:77], v[138:141], v[192:195], v[74:77]
	v_mfma_f32_16x16x32_bf16 v[126:129], v[134:137], v[172:175], v[126:129]
	v_mfma_f32_16x16x32_bf16 v[122:125], v[142:145], v[172:175], v[122:125]
	v_mfma_f32_16x16x32_bf16 v[110:113], v[134:137], v[180:183], v[110:113]
	v_mfma_f32_16x16x32_bf16 v[106:109], v[142:145], v[180:183], v[106:109]
	v_mfma_f32_16x16x32_bf16 v[94:97], v[134:137], v[188:191], v[94:97]
	v_mfma_f32_16x16x32_bf16 v[90:93], v[142:145], v[188:191], v[90:93]
	v_mfma_f32_16x16x32_bf16 v[78:81], v[134:137], v[200:203], v[78:81]
	v_mfma_f32_16x16x32_bf16 v[74:77], v[142:145], v[200:203], v[74:77]
	v_mfma_f32_16x16x32_bf16 v[118:121], v[146:149], v[168:171], v[118:121]
	v_mfma_f32_16x16x32_bf16 v[114:117], v[154:157], v[168:171], v[114:117]
	v_mfma_f32_16x16x32_bf16 v[102:105], v[146:149], v[176:179], v[102:105]
	v_mfma_f32_16x16x32_bf16 v[98:101], v[154:157], v[176:179], v[98:101]
	v_mfma_f32_16x16x32_bf16 v[86:89], v[146:149], v[184:187], v[86:89]
	v_mfma_f32_16x16x32_bf16 v[82:85], v[154:157], v[184:187], v[82:85]
	v_mfma_f32_16x16x32_bf16 v[70:73], v[146:149], v[192:195], v[70:73]
	v_mfma_f32_16x16x32_bf16 v[66:69], v[154:157], v[192:195], v[66:69]
	v_mfma_f32_16x16x32_bf16 v[118:121], v[150:153], v[172:175], v[118:121]
	v_mfma_f32_16x16x32_bf16 v[114:117], v[164:167], v[172:175], v[114:117]
	v_mfma_f32_16x16x32_bf16 v[102:105], v[150:153], v[180:183], v[102:105]
	v_mfma_f32_16x16x32_bf16 v[98:101], v[164:167], v[180:183], v[98:101]
	v_mfma_f32_16x16x32_bf16 v[86:89], v[150:153], v[188:191], v[86:89]
	v_mfma_f32_16x16x32_bf16 v[82:85], v[164:167], v[188:191], v[82:85]
	v_mfma_f32_16x16x32_bf16 v[70:73], v[150:153], v[200:203], v[70:73]
	v_mfma_f32_16x16x32_bf16 v[66:69], v[164:167], v[200:203], v[66:69]
	s_setprio 0
	s_barrier
	s_mov_b32 m0, s39
	s_or_b32 s62, s60, 0x80
	ds_read_b128 v[168:171], v162 offset:49152
	ds_read_b128 v[172:175], v162 offset:50176
	ds_read_b128 v[176:179], v162 offset:51200
	ds_read_b128 v[180:183], v162 offset:52224
	ds_read_b128 v[184:187], v162 offset:53248
	ds_read_b128 v[188:191], v162 offset:54272
	ds_read_b128 v[192:195], v162 offset:55296
	ds_read_b128 v[200:203], v162 offset:56320
	buffer_load_dwordx4 v158, s[16:19], s62 offen lds
	s_mov_b32 m0, s40
	s_add_i32 s60, s60, 0x40080
	buffer_load_dwordx4 v160, s[16:19], s62 offen lds
	s_mov_b32 m0, s43
	s_nop 0
	buffer_load_dwordx4 v158, s[16:19], s60 offen lds
	s_mov_b32 m0, s42
	s_nop 0
	buffer_load_dwordx4 v160, s[16:19], s60 offen lds
	s_mov_b32 m0, s41
	s_nop 0
	buffer_load_dwordx4 v0, s[20:23], s61 offen lds
	s_mov_b32 m0, s33
	s_nop 0
	buffer_load_dwordx4 v159, s[20:23], s61 offen lds
	s_waitcnt vmcnt(8)
	s_waitcnt lgkmcnt(0)
	s_barrier
	s_setprio 1
	v_mfma_f32_16x16x32_bf16 v[62:65], v[130:133], v[168:171], v[62:65]
	v_mfma_f32_16x16x32_bf16 v[58:61], v[138:141], v[168:171], v[58:61]
	v_mfma_f32_16x16x32_bf16 v[46:49], v[130:133], v[176:179], v[46:49]
	v_mfma_f32_16x16x32_bf16 v[42:45], v[138:141], v[176:179], v[42:45]
	v_mfma_f32_16x16x32_bf16 v[30:33], v[130:133], v[184:187], v[30:33]
	v_mfma_f32_16x16x32_bf16 v[26:29], v[138:141], v[184:187], v[26:29]
	v_mfma_f32_16x16x32_bf16 v[14:17], v[130:133], v[192:195], v[14:17]
	v_mfma_f32_16x16x32_bf16 v[10:13], v[138:141], v[192:195], v[10:13]
	v_mfma_f32_16x16x32_bf16 v[62:65], v[134:137], v[172:175], v[62:65]
	v_mfma_f32_16x16x32_bf16 v[58:61], v[142:145], v[172:175], v[58:61]
	v_mfma_f32_16x16x32_bf16 v[46:49], v[134:137], v[180:183], v[46:49]
	v_mfma_f32_16x16x32_bf16 v[42:45], v[142:145], v[180:183], v[42:45]
	v_mfma_f32_16x16x32_bf16 v[30:33], v[134:137], v[188:191], v[30:33]
	v_mfma_f32_16x16x32_bf16 v[26:29], v[142:145], v[188:191], v[26:29]
	v_mfma_f32_16x16x32_bf16 v[14:17], v[134:137], v[200:203], v[14:17]
	v_mfma_f32_16x16x32_bf16 v[10:13], v[142:145], v[200:203], v[10:13]
	v_mfma_f32_16x16x32_bf16 v[54:57], v[146:149], v[168:171], v[54:57]
	v_mfma_f32_16x16x32_bf16 v[50:53], v[154:157], v[168:171], v[50:53]
	v_mfma_f32_16x16x32_bf16 v[38:41], v[146:149], v[176:179], v[38:41]
	v_mfma_f32_16x16x32_bf16 v[34:37], v[154:157], v[176:179], v[34:37]
	v_mfma_f32_16x16x32_bf16 v[22:25], v[146:149], v[184:187], v[22:25]
	v_mfma_f32_16x16x32_bf16 v[18:21], v[154:157], v[184:187], v[18:21]
	v_mfma_f32_16x16x32_bf16 v[6:9], v[146:149], v[192:195], v[6:9]
	v_mfma_f32_16x16x32_bf16 v[2:5], v[154:157], v[192:195], v[2:5]
	v_mfma_f32_16x16x32_bf16 v[54:57], v[150:153], v[172:175], v[54:57]
	v_mfma_f32_16x16x32_bf16 v[50:53], v[164:167], v[172:175], v[50:53]
	v_mfma_f32_16x16x32_bf16 v[38:41], v[150:153], v[180:183], v[38:41]
	v_mfma_f32_16x16x32_bf16 v[34:37], v[164:167], v[180:183], v[34:37]
	v_mfma_f32_16x16x32_bf16 v[22:25], v[150:153], v[188:191], v[22:25]
	v_mfma_f32_16x16x32_bf16 v[18:21], v[164:167], v[188:191], v[18:21]
	v_mfma_f32_16x16x32_bf16 v[6:9], v[150:153], v[200:203], v[6:9]
	v_mfma_f32_16x16x32_bf16 v[2:5], v[164:167], v[200:203], v[2:5]
	s_setprio 0
	s_barrier
	s_add_i32 s59, s59, 2
	s_addk_i32 s2, 0x100
	s_addk_i32 s3, 0x100
	s_cmp_gt_u32 s59, 13
	s_cbranch_scc0 .LBB0_1235
	v_readlane_b32 s2, v251, 45
	v_readlane_b32 s3, v251, 46
	s_and_b64 vcc, exec, s[2:3]
	s_cbranch_vccz .LBB0_1238
	s_barrier

; #define PG8_WAIT_V(n) asm volatile("s_waitcnt vmcnt(" #n ")" ::: "memory")
; template <class Epi, bool ALIGN_EPI, bool SP2, class Hook>
; __device__ __forceinline__ void gemm_phase(LAS unsigned char* lds, const Gemm g, const StaticOrder& S, const Epi& E, Acc& acc, const bool fresh, const Hook& H, const int wave_id) {
;     ...
;         if constexpr (SP2 && Epi::NSTORE > 0) {
;             const Src a1 = cA + kstep, a2 = cA + 2 * kstep, b2 = cB + 2 * kstep, a3 = a2 + kstep, b3 = b2 + kstep;
;             if constexpr (Epi::NSTORE == 16) PG8_TRIP_SP2(PG8_WAIT_V(24)); else PG8_TRIP_SP2(PG8_WAIT_V(16));
;             t0 = 2;
.LBB0_1452:
	ds_read_b128 v[2:5], v138
	ds_read_b128 v[6:9], v138 offset:1024
	ds_read_b128 v[10:13], v138 offset:2048
	ds_read_b128 v[14:17], v138 offset:3072
	ds_read_b128 v[18:21], v139
	ds_read_b128 v[22:25], v139 offset:1024
	ds_read_b128 v[26:29], v139 offset:2048
	ds_read_b128 v[30:33], v139 offset:3072
	s_or_b32 s3, s50, 0x100
	s_or_b32 s2, s50, 0x180
	s_or_b32 s12, s51, 0x100
	s_or_b32 s13, s50, 0x40080
	s_mov_b32 m0, s45
	ds_read_b128 v[34:37], v137
	ds_read_b128 v[38:41], v137 offset:1024
	ds_read_b128 v[42:45], v137 offset:2048
	ds_read_b128 v[46:49], v137 offset:3072
	ds_read_b128 v[50:53], v137 offset:4096
	ds_read_b128 v[54:57], v137 offset:5120
	ds_read_b128 v[58:61], v137 offset:6144
	ds_read_b128 v[62:65], v137 offset:7168
	buffer_load_dwordx4 v132, s[4:7], s13 offen lds
	s_mov_b32 m0, s46
	s_nop 0
	buffer_load_dwordx4 v134, s[4:7], s13 offen lds
	s_waitcnt vmcnt(16)
	s_waitcnt lgkmcnt(0)
	s_barrier
	s_setprio 1
	v_mfma_f32_16x16x32_bf16 v[90:93], v[2:5], v[58:61], 0
	v_mfma_f32_16x16x32_bf16 v[66:69], v[2:5], v[34:37], 0
	v_mfma_f32_16x16x32_bf16 v[70:73], v[10:13], v[34:37], 0
	v_mfma_f32_16x16x32_bf16 v[74:77], v[2:5], v[42:45], 0
	v_mfma_f32_16x16x32_bf16 v[78:81], v[10:13], v[42:45], 0
	v_mfma_f32_16x16x32_bf16 v[82:85], v[2:5], v[50:53], 0
	v_mfma_f32_16x16x32_bf16 v[86:89], v[10:13], v[50:53], 0
	v_mfma_f32_16x16x32_bf16 v[96:99], v[6:9], v[62:65], v[90:93]
	v_mfma_f32_16x16x32_bf16 v[90:93], v[10:13], v[58:61], 0
	v_mfma_f32_16x16x32_bf16 v[66:69], v[6:9], v[38:41], v[66:69]
	v_mfma_f32_16x16x32_bf16 v[70:73], v[14:17], v[38:41], v[70:73]
	v_mfma_f32_16x16x32_bf16 v[74:77], v[6:9], v[46:49], v[74:77]
	v_mfma_f32_16x16x32_bf16 v[78:81], v[14:17], v[46:49], v[78:81]
	v_mfma_f32_16x16x32_bf16 v[82:85], v[6:9], v[54:57], v[82:85]
	v_mfma_f32_16x16x32_bf16 v[86:89], v[14:17], v[54:57], v[86:89]
	v_mfma_f32_16x16x32_bf16 v[104:107], v[14:17], v[62:65], v[90:93]
	v_mfma_f32_16x16x32_bf16 v[90:93], v[18:21], v[34:37], 0
	v_mfma_f32_16x16x32_bf16 v[34:37], v[26:29], v[34:37], 0
	v_mfma_f32_16x16x32_bf16 v[112:115], v[22:25], v[38:41], v[90:93]
	v_mfma_f32_16x16x32_bf16 v[34:37], v[30:33], v[38:41], v[34:37]
	v_mfma_f32_16x16x32_bf16 v[38:41], v[18:21], v[42:45], 0
	v_mfma_f32_16x16x32_bf16 v[42:45], v[26:29], v[42:45], 0
	v_mfma_f32_16x16x32_bf16 v[38:41], v[22:25], v[46:49], v[38:41]
	v_mfma_f32_16x16x32_bf16 v[42:45], v[30:33], v[46:49], v[42:45]
	v_mfma_f32_16x16x32_bf16 v[46:49], v[18:21], v[50:53], 0
	v_mfma_f32_16x16x32_bf16 v[50:53], v[26:29], v[50:53], 0
	v_mfma_f32_16x16x32_bf16 v[46:49], v[22:25], v[54:57], v[46:49]
	v_mfma_f32_16x16x32_bf16 v[50:53], v[30:33], v[54:57], v[50:53]
	v_mfma_f32_16x16x32_bf16 v[54:57], v[18:21], v[58:61], 0
	v_mfma_f32_16x16x32_bf16 v[58:61], v[26:29], v[58:61], 0
	v_mfma_f32_16x16x32_bf16 v[54:57], v[22:25], v[62:65], v[54:57]
	v_mfma_f32_16x16x32_bf16 v[58:61], v[30:33], v[62:65], v[58:61]
	s_setprio 0
	s_barrier
	s_mov_b32 m0, s92
	ds_read_b128 v[62:65], v137 offset:16384
	ds_read_b128 v[90:93], v137 offset:17408
	ds_read_b128 v[100:103], v137 offset:18432
	ds_read_b128 v[108:111], v137 offset:19456
	ds_read_b128 v[116:119], v137 offset:20480
	ds_read_b128 v[120:123], v137 offset:21504
	ds_read_b128 v[124:127], v137 offset:22528
	ds_read_b128 v[128:131], v137 offset:23552
	buffer_load_dwordx4 v133, s[8:11], s12 offen lds
	s_mov_b32 m0, s93
	s_nop 0
	buffer_load_dwordx4 v135, s[8:11], s12 offen lds
	s_or_b32 s12, s51, 0x40100
	s_mov_b32 m0, s94
	s_nop 0
	buffer_load_dwordx4 v133, s[8:11], s12 offen lds
	s_mov_b32 m0, s95
	s_nop 0
	buffer_load_dwordx4 v135, s[8:11], s12 offen lds
	s_mov_b32 m0, s44
	s_nop 0
	buffer_load_dwordx4 v132, s[4:7], s3 offen lds
	s_mov_b32 m0, s36
	s_nop 0
	buffer_load_dwordx4 v134, s[4:7], s3 offen lds
	s_waitcnt vmcnt(16)
	s_waitcnt lgkmcnt(0)
	s_barrier
	s_setprio 1
	v_mfma_f32_16x16x32_bf16 v[142:145], v[2:5], v[62:65], 0
	v_mfma_f32_16x16x32_bf16 v[150:153], v[2:5], v[100:103], 0
	v_mfma_f32_16x16x32_bf16 v[158:161], v[2:5], v[116:119], 0
	v_mfma_f32_16x16x32_bf16 v[2:5], v[2:5], v[124:127], 0
	v_mfma_f32_16x16x32_bf16 v[142:145], v[6:9], v[90:93], v[142:145]
	v_mfma_f32_16x16x32_bf16 v[150:153], v[6:9], v[108:111], v[150:153]
	v_mfma_f32_16x16x32_bf16 v[158:161], v[6:9], v[120:123], v[158:161]
	v_mfma_f32_16x16x32_bf16 v[2:5], v[6:9], v[128:131], v[2:5]
	v_mfma_f32_16x16x32_bf16 v[6:9], v[10:13], v[124:127], 0
	v_mfma_f32_16x16x32_bf16 v[146:149], v[10:13], v[62:65], 0
	v_mfma_f32_16x16x32_bf16 v[154:157], v[10:13], v[100:103], 0
	v_mfma_f32_16x16x32_bf16 v[162:165], v[10:13], v[116:119], 0
	v_mfma_f32_16x16x32_bf16 v[6:9], v[14:17], v[128:131], v[6:9]
	v_mfma_f32_16x16x32_bf16 v[146:149], v[14:17], v[90:93], v[146:149]
	v_mfma_f32_16x16x32_bf16 v[154:157], v[14:17], v[108:111], v[154:157]
	v_mfma_f32_16x16x32_bf16 v[162:165], v[14:17], v[120:123], v[162:165]
	v_mfma_f32_16x16x32_bf16 v[10:13], v[18:21], v[62:65], 0
	v_mfma_f32_16x16x32_bf16 v[166:169], v[22:25], v[90:93], v[10:13]
	v_mfma_f32_16x16x32_bf16 v[10:13], v[26:29], v[62:65], 0
	v_mfma_f32_16x16x32_bf16 v[170:173], v[30:33], v[90:93], v[10:13]
	v_mfma_f32_16x16x32_bf16 v[10:13], v[18:21], v[100:103], 0
	v_mfma_f32_16x16x32_bf16 v[174:177], v[22:25], v[108:111], v[10:13]
	v_mfma_f32_16x16x32_bf16 v[10:13], v[26:29], v[100:103], 0
	v_mfma_f32_16x16x32_bf16 v[178:181], v[30:33], v[108:111], v[10:13]
	v_mfma_f32_16x16x32_bf16 v[10:13], v[18:21], v[116:119], 0
	v_mfma_f32_16x16x32_bf16 v[182:185], v[22:25], v[120:123], v[10:13]
	v_mfma_f32_16x16x32_bf16 v[10:13], v[26:29], v[116:119], 0
	v_mfma_f32_16x16x32_bf16 v[186:189], v[30:33], v[120:123], v[10:13]
	v_mfma_f32_16x16x32_bf16 v[10:13], v[18:21], v[124:127], 0
	v_mfma_f32_16x16x32_bf16 v[16:19], v[22:25], v[128:131], v[10:13]
	v_mfma_f32_16x16x32_bf16 v[10:13], v[26:29], v[124:127], 0
	v_mfma_f32_16x16x32_bf16 v[190:193], v[30:33], v[128:131], v[10:13]
	s_setprio 0
	s_barrier
; #define PG8_WAIT_V(n) asm volatile("s_waitcnt vmcnt(" #n ")" ::: "memory")
; template <class Epi, bool ALIGN_EPI, bool SP2, class Hook>
; __device__ __forceinline__ void gemm_phase(LAS unsigned char* lds, const Gemm g, const StaticOrder& S, const Epi& E, Acc& acc, const bool fresh, const Hook& H, const int wave_id) {
;     ...
;         if constexpr (SP2 && Epi::NSTORE > 0) {
;             const Src a1 = cA + kstep, a2 = cA + 2 * kstep, b2 = cB + 2 * kstep, a3 = a2 + kstep, b3 = b2 + kstep;
;             if constexpr (Epi::NSTORE == 16) PG8_TRIP_SP2(PG8_WAIT_V(24)); else PG8_TRIP_SP2(PG8_WAIT_V(16));
;             t0 = 2;
	s_nop 4
	ds_read_b128 v[10:13], v140
	ds_read_b128 v[24:27], v140 offset:1024
	ds_read_b128 v[194:197], v140 offset:2048
	ds_read_b128 v[200:203], v140 offset:3072
	ds_read_b128 v[204:207], v141
	ds_read_b128 v[208:211], v141 offset:1024
	ds_read_b128 v[212:215], v141 offset:2048
	ds_read_b128 v[138:141], v141 offset:3072
	s_or_b32 s3, s50, 0x40100
	s_mov_b32 m0, s37
	ds_read_b128 v[20:23], v137 offset:32768
	ds_read_b128 v[28:31], v137 offset:33792
	ds_read_b128 v[216:219], v137 offset:34816
	ds_read_b128 v[220:223], v137 offset:35840
	ds_read_b128 v[228:231], v137 offset:36864
	ds_read_b128 v[232:235], v137 offset:37888
	ds_read_b128 v[236:239], v137 offset:38912
	ds_read_b128 v[240:243], v137 offset:39936
	buffer_load_dwordx4 v132, s[4:7], s3 offen lds
	s_mov_b32 m0, s38
	s_nop 0
	buffer_load_dwordx4 v134, s[4:7], s3 offen lds
	s_waitcnt vmcnt(8)
	s_waitcnt lgkmcnt(0)
	s_barrier
	s_setprio 1
	v_mfma_f32_16x16x32_bf16 v[62:65], v[10:13], v[20:23], v[66:69]
	v_mfma_f32_16x16x32_bf16 v[124:127], v[24:27], v[28:31], v[62:65]
	v_mfma_f32_16x16x32_bf16 v[62:65], v[194:197], v[20:23], v[70:73]
	v_mfma_f32_16x16x32_bf16 v[116:119], v[200:203], v[28:31], v[62:65]
	v_mfma_f32_16x16x32_bf16 v[62:65], v[10:13], v[216:219], v[74:77]
	v_mfma_f32_16x16x32_bf16 v[108:111], v[24:27], v[220:223], v[62:65]
	v_mfma_f32_16x16x32_bf16 v[62:65], v[194:197], v[216:219], v[78:81]
	v_mfma_f32_16x16x32_bf16 v[100:103], v[200:203], v[220:223], v[62:65]
	v_mfma_f32_16x16x32_bf16 v[62:65], v[10:13], v[228:231], v[82:85]
	v_mfma_f32_16x16x32_bf16 v[92:95], v[24:27], v[232:235], v[62:65]
	v_mfma_f32_16x16x32_bf16 v[62:65], v[194:197], v[228:231], v[86:89]
	v_mfma_f32_16x16x32_bf16 v[84:87], v[200:203], v[232:235], v[62:65]
	v_mfma_f32_16x16x32_bf16 v[62:65], v[10:13], v[236:239], v[96:99]
	v_mfma_f32_16x16x32_bf16 v[76:79], v[24:27], v[240:243], v[62:65]
	v_mfma_f32_16x16x32_bf16 v[62:65], v[194:197], v[236:239], v[104:107]
	v_mfma_f32_16x16x32_bf16 v[64:67], v[200:203], v[240:243], v[62:65]
	v_mfma_f32_16x16x32_bf16 v[68:71], v[204:207], v[20:23], v[112:115]
	v_mfma_f32_16x16x32_bf16 v[20:23], v[212:215], v[20:23], v[34:37]
	v_mfma_f32_16x16x32_bf16 v[120:123], v[138:141], v[28:31], v[20:23]
	v_mfma_f32_16x16x32_bf16 v[20:23], v[204:207], v[216:219], v[38:41]
	v_mfma_f32_16x16x32_bf16 v[112:115], v[208:211], v[220:223], v[20:23]
	v_mfma_f32_16x16x32_bf16 v[20:23], v[212:215], v[216:219], v[42:45]
	v_mfma_f32_16x16x32_bf16 v[104:107], v[138:141], v[220:223], v[20:23]
	v_mfma_f32_16x16x32_bf16 v[20:23], v[204:207], v[228:231], v[46:49]
	v_mfma_f32_16x16x32_bf16 v[96:99], v[208:211], v[232:235], v[20:23]
	v_mfma_f32_16x16x32_bf16 v[20:23], v[212:215], v[228:231], v[50:53]
	v_mfma_f32_16x16x32_bf16 v[88:91], v[138:141], v[232:235], v[20:23]
	v_mfma_f32_16x16x32_bf16 v[20:23], v[204:207], v[236:239], v[54:57]
	v_mfma_f32_16x16x32_bf16 v[80:83], v[208:211], v[240:243], v[20:23]
	v_mfma_f32_16x16x32_bf16 v[20:23], v[212:215], v[236:239], v[58:61]
	v_mfma_f32_16x16x32_bf16 v[128:131], v[208:211], v[28:31], v[68:71]
	v_mfma_f32_16x16x32_bf16 v[68:71], v[138:141], v[240:243], v[20:23]
	s_setprio 0
	s_barrier
	s_mov_b32 m0, s39
	s_or_b32 s3, s51, 0x180
	ds_read_b128 v[32:35], v137 offset:49152
	ds_read_b128 v[40:43], v137 offset:50176
	ds_read_b128 v[216:219], v137 offset:51200
	ds_read_b128 v[220:223], v137 offset:52224
	ds_read_b128 v[228:231], v137 offset:53248
	ds_read_b128 v[232:235], v137 offset:54272
	ds_read_b128 v[236:239], v137 offset:55296
	ds_read_b128 v[240:243], v137 offset:56320
	buffer_load_dwordx4 v133, s[8:11], s3 offen lds
	s_mov_b32 m0, s40
	s_nop 0
	buffer_load_dwordx4 v135, s[8:11], s3 offen lds
	s_or_b32 s3, s51, 0x40180
	s_mov_b32 m0, s43
	s_nop 0
	buffer_load_dwordx4 v133, s[8:11], s3 offen lds
	s_mov_b32 m0, s42
	s_nop 0
	buffer_load_dwordx4 v135, s[8:11], s3 offen lds
	s_mov_b32 m0, s41
	s_nop 0
	buffer_load_dwordx4 v132, s[4:7], s2 offen lds
	s_mov_b32 m0, s33
	s_nop 0
	buffer_load_dwordx4 v134, s[4:7], s2 offen lds
	s_waitcnt vmcnt(8)
	s_waitcnt lgkmcnt(0)
	s_barrier
	s_setprio 1
	v_mfma_f32_16x16x32_bf16 v[20:23], v[10:13], v[32:35], v[142:145]
	v_mfma_f32_16x16x32_bf16 v[60:63], v[24:27], v[40:43], v[20:23]
	v_mfma_f32_16x16x32_bf16 v[20:23], v[194:197], v[32:35], v[146:149]
	v_mfma_f32_16x16x32_bf16 v[52:55], v[200:203], v[40:43], v[20:23]
	v_mfma_f32_16x16x32_bf16 v[20:23], v[10:13], v[216:219], v[150:153]
	v_mfma_f32_16x16x32_bf16 v[44:47], v[24:27], v[220:223], v[20:23]
	v_mfma_f32_16x16x32_bf16 v[20:23], v[194:197], v[216:219], v[154:157]
	v_mfma_f32_16x16x32_bf16 v[36:39], v[200:203], v[220:223], v[20:23]
	v_mfma_f32_16x16x32_bf16 v[20:23], v[10:13], v[228:231], v[158:161]
	v_mfma_f32_16x16x32_bf16 v[2:5], v[10:13], v[236:239], v[2:5]
	v_mfma_f32_16x16x32_bf16 v[28:31], v[24:27], v[232:235], v[20:23]
	v_mfma_f32_16x16x32_bf16 v[20:23], v[194:197], v[228:231], v[162:165]
	v_mfma_f32_16x16x32_bf16 v[12:15], v[24:27], v[240:243], v[2:5]
	v_mfma_f32_16x16x32_bf16 v[2:5], v[194:197], v[236:239], v[6:9]
	v_mfma_f32_16x16x32_bf16 v[20:23], v[200:203], v[232:235], v[20:23]
	v_mfma_f32_16x16x32_bf16 v[4:7], v[200:203], v[240:243], v[2:5]
	v_mfma_f32_16x16x32_bf16 v[8:11], v[204:207], v[32:35], v[166:169]
	v_mfma_f32_16x16x32_bf16 v[72:75], v[208:211], v[40:43], v[8:11]
	v_mfma_f32_16x16x32_bf16 v[8:11], v[212:215], v[32:35], v[170:173]
	v_mfma_f32_16x16x32_bf16 v[56:59], v[138:141], v[40:43], v[8:11]
	v_mfma_f32_16x16x32_bf16 v[8:11], v[204:207], v[216:219], v[174:177]
	v_mfma_f32_16x16x32_bf16 v[48:51], v[208:211], v[220:223], v[8:11]
	v_mfma_f32_16x16x32_bf16 v[8:11], v[212:215], v[216:219], v[178:181]
	v_mfma_f32_16x16x32_bf16 v[40:43], v[138:141], v[220:223], v[8:11]
	v_mfma_f32_16x16x32_bf16 v[8:11], v[204:207], v[228:231], v[182:185]
	v_mfma_f32_16x16x32_bf16 v[32:35], v[208:211], v[232:235], v[8:11]
	v_mfma_f32_16x16x32_bf16 v[8:11], v[212:215], v[228:231], v[186:189]
	v_mfma_f32_16x16x32_bf16 v[24:27], v[138:141], v[232:235], v[8:11]
	v_mfma_f32_16x16x32_bf16 v[8:11], v[204:207], v[236:239], v[16:19]
	v_mfma_f32_16x16x32_bf16 v[16:19], v[208:211], v[240:243], v[8:11]
	v_mfma_f32_16x16x32_bf16 v[8:11], v[212:215], v[236:239], v[190:193]
	v_mfma_f32_16x16x32_bf16 v[8:11], v[138:141], v[240:243], v[8:11]
	s_setprio 0
	s_barrier
	s_mov_b64 s[2:3], 0
	v_mov_b64_e32 v[234:235], v[226:227]
	v_mov_b32_e32 v226, v0
	v_mov_b64_e32 v[236:237], v[198:199]
	v_mov_b32_e32 v198, v225

; #define PG8_WAIT_V(n) asm volatile("s_waitcnt vmcnt(" #n ")" ::: "memory")
; template <class Epi, bool ALIGN_EPI, bool SP2, class Hook>
; __device__ __forceinline__ void gemm_phase(LAS unsigned char* lds, const Gemm g, const StaticOrder& S, const Epi& E, Acc& acc, const bool fresh, const Hook& H, const int wave_id) {
;     ...
;         for (int t = t0; t < nt; t += 2) {
;             const bool last = (t == nt - 2);
;             const Src a1 = cA + (size_t)(t + 1) * kstep;
;             const Src a2 = last ? nA : cA + (size_t)(t + 2) * kstep, b2 = last ? nB : cB + (size_t)(t + 2) * kstep;
;             const Src a3 = a2 + kstep, b3 = b2 + kstep;
;             if (last && has_next) H(nxt);
;             if constexpr (SP2) {
;             PG8_TRIP_SP2(PG8_WAIT_V(8));
.LBB0_1461:
	v_add_u32_e32 v138, 0x10000, v136
	v_add_u32_e32 v139, 0x14000, v136
	ds_read_b128 v[140:143], v138
	ds_read_b128 v[144:147], v138 offset:1024
	ds_read_b128 v[148:151], v138 offset:2048
	ds_read_b128 v[152:155], v138 offset:3072
	ds_read_b128 v[156:159], v139
	ds_read_b128 v[160:163], v139 offset:1024
	ds_read_b128 v[164:167], v139 offset:2048
	ds_read_b128 v[168:171], v139 offset:3072
	s_add_i32 s16, s55, 0xfffc0080
	s_cmp_eq_u32 s54, 12
	s_cselect_b32 s59, s50, s16
	s_cselect_b32 s17, s9, s77
	s_cselect_b32 s16, s8, s76
	s_cselect_b32 s19, s11, s29
	s_cselect_b32 s18, s10, s28
	s_cselect_b32 s57, s51, s56
	s_cselect_b32 s20, s4, s12
	s_cselect_b32 s21, s5, s13
	s_cselect_b32 s22, s6, s14
	s_cselect_b32 s23, s7, s15
	s_or_b32 s58, s59, 0x80
	s_mov_b32 m0, s45
	ds_read_b128 v[172:175], v137
	ds_read_b128 v[176:179], v137 offset:1024
	ds_read_b128 v[180:183], v137 offset:2048
	ds_read_b128 v[184:187], v137 offset:3072
	ds_read_b128 v[188:191], v137 offset:4096
	ds_read_b128 v[192:195], v137 offset:5120
	ds_read_b128 v[200:203], v137 offset:6144
	ds_read_b128 v[204:207], v137 offset:7168
	buffer_load_dwordx4 v132, s[12:15], s55 offen lds
	s_mov_b32 m0, s46
	s_nop 0
	buffer_load_dwordx4 v134, s[12:15], s55 offen lds
	s_waitcnt vmcnt(8)
	s_waitcnt lgkmcnt(0)
	s_barrier
	s_setprio 1
	v_mfma_f32_16x16x32_bf16 v[124:127], v[140:143], v[172:175], v[124:127]
	v_mfma_f32_16x16x32_bf16 v[116:119], v[148:151], v[172:175], v[116:119]
	v_mfma_f32_16x16x32_bf16 v[108:111], v[140:143], v[180:183], v[108:111]
	v_mfma_f32_16x16x32_bf16 v[100:103], v[148:151], v[180:183], v[100:103]
	v_mfma_f32_16x16x32_bf16 v[92:95], v[140:143], v[188:191], v[92:95]
	v_mfma_f32_16x16x32_bf16 v[84:87], v[148:151], v[188:191], v[84:87]
	v_mfma_f32_16x16x32_bf16 v[76:79], v[140:143], v[200:203], v[76:79]
	v_mfma_f32_16x16x32_bf16 v[64:67], v[148:151], v[200:203], v[64:67]
	v_mfma_f32_16x16x32_bf16 v[124:127], v[144:147], v[176:179], v[124:127]
	v_mfma_f32_16x16x32_bf16 v[116:119], v[152:155], v[176:179], v[116:119]
	v_mfma_f32_16x16x32_bf16 v[108:111], v[144:147], v[184:187], v[108:111]
	v_mfma_f32_16x16x32_bf16 v[100:103], v[152:155], v[184:187], v[100:103]
	v_mfma_f32_16x16x32_bf16 v[92:95], v[144:147], v[192:195], v[92:95]
	v_mfma_f32_16x16x32_bf16 v[84:87], v[152:155], v[192:195], v[84:87]
	v_mfma_f32_16x16x32_bf16 v[76:79], v[144:147], v[204:207], v[76:79]
	v_mfma_f32_16x16x32_bf16 v[64:67], v[152:155], v[204:207], v[64:67]
	v_mfma_f32_16x16x32_bf16 v[128:131], v[156:159], v[172:175], v[128:131]
	v_mfma_f32_16x16x32_bf16 v[120:123], v[164:167], v[172:175], v[120:123]
	v_mfma_f32_16x16x32_bf16 v[112:115], v[156:159], v[180:183], v[112:115]
	v_mfma_f32_16x16x32_bf16 v[104:107], v[164:167], v[180:183], v[104:107]
	v_mfma_f32_16x16x32_bf16 v[96:99], v[156:159], v[188:191], v[96:99]
	v_mfma_f32_16x16x32_bf16 v[88:91], v[164:167], v[188:191], v[88:91]
	v_mfma_f32_16x16x32_bf16 v[80:83], v[156:159], v[200:203], v[80:83]
	v_mfma_f32_16x16x32_bf16 v[68:71], v[164:167], v[200:203], v[68:71]
	v_mfma_f32_16x16x32_bf16 v[128:131], v[160:163], v[176:179], v[128:131]
	v_mfma_f32_16x16x32_bf16 v[120:123], v[168:171], v[176:179], v[120:123]
	v_mfma_f32_16x16x32_bf16 v[112:115], v[160:163], v[184:187], v[112:115]
	v_mfma_f32_16x16x32_bf16 v[104:107], v[168:171], v[184:187], v[104:107]
	v_mfma_f32_16x16x32_bf16 v[96:99], v[160:163], v[192:195], v[96:99]
	v_mfma_f32_16x16x32_bf16 v[88:91], v[168:171], v[192:195], v[88:91]
	v_mfma_f32_16x16x32_bf16 v[80:83], v[160:163], v[204:207], v[80:83]
	v_mfma_f32_16x16x32_bf16 v[68:71], v[168:171], v[204:207], v[68:71]
	s_setprio 0
	s_barrier
	s_mov_b32 m0, s92
	ds_read_b128 v[172:175], v137 offset:16384
	ds_read_b128 v[176:179], v137 offset:17408
	ds_read_b128 v[180:183], v137 offset:18432
	ds_read_b128 v[184:187], v137 offset:19456
	ds_read_b128 v[188:191], v137 offset:20480
	ds_read_b128 v[192:195], v137 offset:21504
	ds_read_b128 v[200:203], v137 offset:22528
	ds_read_b128 v[204:207], v137 offset:23552
	buffer_load_dwordx4 v133, s[16:19], s57 offen lds
	s_mov_b32 m0, s93
	s_add_i32 s60, s57, 0x40000
	buffer_load_dwordx4 v135, s[16:19], s57 offen lds
	s_mov_b32 m0, s94
	s_nop 0
	buffer_load_dwordx4 v133, s[16:19], s60 offen lds
	s_mov_b32 m0, s95
	s_nop 0
	buffer_load_dwordx4 v135, s[16:19], s60 offen lds
	s_mov_b32 m0, s44
	s_nop 0
	buffer_load_dwordx4 v132, s[20:23], s59 offen lds
	s_mov_b32 m0, s36
	s_nop 0
	buffer_load_dwordx4 v134, s[20:23], s59 offen lds
	s_waitcnt vmcnt(8)
	s_waitcnt lgkmcnt(0)
	s_barrier
	s_setprio 1
	v_mfma_f32_16x16x32_bf16 v[60:63], v[140:143], v[172:175], v[60:63]
	v_mfma_f32_16x16x32_bf16 v[52:55], v[148:151], v[172:175], v[52:55]
	v_mfma_f32_16x16x32_bf16 v[44:47], v[140:143], v[180:183], v[44:47]
	v_mfma_f32_16x16x32_bf16 v[36:39], v[148:151], v[180:183], v[36:39]
	v_mfma_f32_16x16x32_bf16 v[28:31], v[140:143], v[188:191], v[28:31]
	v_mfma_f32_16x16x32_bf16 v[20:23], v[148:151], v[188:191], v[20:23]
	v_mfma_f32_16x16x32_bf16 v[12:15], v[140:143], v[200:203], v[12:15]
	v_mfma_f32_16x16x32_bf16 v[2:5], v[148:151], v[200:203], v[4:7]
	v_mfma_f32_16x16x32_bf16 v[60:63], v[144:147], v[176:179], v[60:63]
	v_mfma_f32_16x16x32_bf16 v[52:55], v[152:155], v[176:179], v[52:55]
	v_mfma_f32_16x16x32_bf16 v[44:47], v[144:147], v[184:187], v[44:47]
	v_mfma_f32_16x16x32_bf16 v[36:39], v[152:155], v[184:187], v[36:39]
	v_mfma_f32_16x16x32_bf16 v[28:31], v[144:147], v[192:195], v[28:31]
	v_mfma_f32_16x16x32_bf16 v[20:23], v[152:155], v[192:195], v[20:23]
	v_mfma_f32_16x16x32_bf16 v[12:15], v[144:147], v[204:207], v[12:15]
	v_mfma_f32_16x16x32_bf16 v[2:5], v[152:155], v[204:207], v[2:5]
	v_mfma_f32_16x16x32_bf16 v[72:75], v[156:159], v[172:175], v[72:75]
	v_mfma_f32_16x16x32_bf16 v[56:59], v[164:167], v[172:175], v[56:59]
	v_mfma_f32_16x16x32_bf16 v[48:51], v[156:159], v[180:183], v[48:51]
	v_mfma_f32_16x16x32_bf16 v[40:43], v[164:167], v[180:183], v[40:43]
	v_mfma_f32_16x16x32_bf16 v[32:35], v[156:159], v[188:191], v[32:35]
	v_mfma_f32_16x16x32_bf16 v[24:27], v[164:167], v[188:191], v[24:27]
	v_mfma_f32_16x16x32_bf16 v[16:19], v[156:159], v[200:203], v[16:19]
	v_mfma_f32_16x16x32_bf16 v[6:9], v[164:167], v[200:203], v[8:11]
	v_mfma_f32_16x16x32_bf16 v[72:75], v[160:163], v[176:179], v[72:75]
	v_mfma_f32_16x16x32_bf16 v[56:59], v[168:171], v[176:179], v[56:59]
	v_mfma_f32_16x16x32_bf16 v[48:51], v[160:163], v[184:187], v[48:51]
	v_mfma_f32_16x16x32_bf16 v[40:43], v[168:171], v[184:187], v[40:43]
	v_mfma_f32_16x16x32_bf16 v[32:35], v[160:163], v[192:195], v[32:35]
	v_mfma_f32_16x16x32_bf16 v[24:27], v[168:171], v[192:195], v[24:27]
	v_mfma_f32_16x16x32_bf16 v[16:19], v[160:163], v[204:207], v[16:19]
	v_mfma_f32_16x16x32_bf16 v[8:11], v[168:171], v[204:207], v[6:9]
	s_setprio 0
	s_barrier
; #define PG8_WAIT_V(n) asm volatile("s_waitcnt vmcnt(" #n ")" ::: "memory")
; template <class Epi, bool ALIGN_EPI, bool SP2, class Hook>
; __device__ __forceinline__ void gemm_phase(LAS unsigned char* lds, const Gemm g, const StaticOrder& S, const Epi& E, Acc& acc, const bool fresh, const Hook& H, const int wave_id) {
;     ...
;         for (int t = t0; t < nt; t += 2) {
;             const bool last = (t == nt - 2);
;             const Src a1 = cA + (size_t)(t + 1) * kstep;
;             const Src a2 = last ? nA : cA + (size_t)(t + 2) * kstep, b2 = last ? nB : cB + (size_t)(t + 2) * kstep;
;             const Src a3 = a2 + kstep, b3 = b2 + kstep;
;             if (last && has_next) H(nxt);
;             if constexpr (SP2) {
;             PG8_TRIP_SP2(PG8_WAIT_V(8));
	v_add_u32_e32 v140, 0x18000, v136
	v_add_u32_e32 v141, 0x1c000, v136
	ds_read_b128 v[142:145], v140
	ds_read_b128 v[146:149], v140 offset:1024
	ds_read_b128 v[150:153], v140 offset:2048
	ds_read_b128 v[154:157], v140 offset:3072
	ds_read_b128 v[158:161], v141
	ds_read_b128 v[162:165], v141 offset:1024
	ds_read_b128 v[166:169], v141 offset:2048
	ds_read_b128 v[170:173], v141 offset:3072
	s_add_i32 s59, s59, 0x40000
	s_mov_b32 m0, s37
	ds_read_b128 v[174:177], v137 offset:32768
	ds_read_b128 v[178:181], v137 offset:33792
	ds_read_b128 v[182:185], v137 offset:34816
	ds_read_b128 v[186:189], v137 offset:35840
	ds_read_b128 v[190:193], v137 offset:36864
	ds_read_b128 v[194:197], v137 offset:37888
	ds_read_b128 v[200:203], v137 offset:38912
	ds_read_b128 v[204:207], v137 offset:39936
	buffer_load_dwordx4 v132, s[20:23], s59 offen lds
	s_mov_b32 m0, s38
	s_nop 0
	buffer_load_dwordx4 v134, s[20:23], s59 offen lds
	s_waitcnt vmcnt(8)
	s_waitcnt lgkmcnt(0)
	s_barrier
	s_setprio 1
	v_mfma_f32_16x16x32_bf16 v[124:127], v[142:145], v[174:177], v[124:127]
	v_mfma_f32_16x16x32_bf16 v[116:119], v[150:153], v[174:177], v[116:119]
	v_mfma_f32_16x16x32_bf16 v[108:111], v[142:145], v[182:185], v[108:111]
	v_mfma_f32_16x16x32_bf16 v[100:103], v[150:153], v[182:185], v[100:103]
	v_mfma_f32_16x16x32_bf16 v[92:95], v[142:145], v[190:193], v[92:95]
	v_mfma_f32_16x16x32_bf16 v[84:87], v[150:153], v[190:193], v[84:87]
	v_mfma_f32_16x16x32_bf16 v[76:79], v[142:145], v[200:203], v[76:79]
	v_mfma_f32_16x16x32_bf16 v[64:67], v[150:153], v[200:203], v[64:67]
	v_mfma_f32_16x16x32_bf16 v[124:127], v[146:149], v[178:181], v[124:127]
	v_mfma_f32_16x16x32_bf16 v[116:119], v[154:157], v[178:181], v[116:119]
	v_mfma_f32_16x16x32_bf16 v[108:111], v[146:149], v[186:189], v[108:111]
	v_mfma_f32_16x16x32_bf16 v[100:103], v[154:157], v[186:189], v[100:103]
	v_mfma_f32_16x16x32_bf16 v[92:95], v[146:149], v[194:197], v[92:95]
	v_mfma_f32_16x16x32_bf16 v[84:87], v[154:157], v[194:197], v[84:87]
	v_mfma_f32_16x16x32_bf16 v[76:79], v[146:149], v[204:207], v[76:79]
	v_mfma_f32_16x16x32_bf16 v[64:67], v[154:157], v[204:207], v[64:67]
	v_mfma_f32_16x16x32_bf16 v[128:131], v[158:161], v[174:177], v[128:131]
	v_mfma_f32_16x16x32_bf16 v[120:123], v[166:169], v[174:177], v[120:123]
	v_mfma_f32_16x16x32_bf16 v[112:115], v[158:161], v[182:185], v[112:115]
	v_mfma_f32_16x16x32_bf16 v[104:107], v[166:169], v[182:185], v[104:107]
	v_mfma_f32_16x16x32_bf16 v[96:99], v[158:161], v[190:193], v[96:99]
	v_mfma_f32_16x16x32_bf16 v[88:91], v[166:169], v[190:193], v[88:91]
	v_mfma_f32_16x16x32_bf16 v[80:83], v[158:161], v[200:203], v[80:83]
	v_mfma_f32_16x16x32_bf16 v[68:71], v[166:169], v[200:203], v[68:71]
	v_mfma_f32_16x16x32_bf16 v[128:131], v[162:165], v[178:181], v[128:131]
	v_mfma_f32_16x16x32_bf16 v[120:123], v[170:173], v[178:181], v[120:123]
	v_mfma_f32_16x16x32_bf16 v[112:115], v[162:165], v[186:189], v[112:115]
	v_mfma_f32_16x16x32_bf16 v[104:107], v[170:173], v[186:189], v[104:107]
	v_mfma_f32_16x16x32_bf16 v[96:99], v[162:165], v[194:197], v[96:99]
	v_mfma_f32_16x16x32_bf16 v[88:91], v[170:173], v[194:197], v[88:91]
	v_mfma_f32_16x16x32_bf16 v[80:83], v[162:165], v[204:207], v[80:83]
	v_mfma_f32_16x16x32_bf16 v[68:71], v[170:173], v[204:207], v[68:71]
	s_setprio 0
	s_barrier
	s_mov_b32 m0, s39
	s_or_b32 s59, s57, 0x80
	ds_read_b128 v[174:177], v137 offset:49152
	ds_read_b128 v[178:181], v137 offset:50176
	ds_read_b128 v[182:185], v137 offset:51200
	ds_read_b128 v[186:189], v137 offset:52224
	ds_read_b128 v[190:193], v137 offset:53248
	ds_read_b128 v[194:197], v137 offset:54272
	ds_read_b128 v[200:203], v137 offset:55296
	ds_read_b128 v[204:207], v137 offset:56320
	buffer_load_dwordx4 v133, s[16:19], s59 offen lds
	s_mov_b32 m0, s40
	s_add_i32 s57, s57, 0x40080
	buffer_load_dwordx4 v135, s[16:19], s59 offen lds
	s_mov_b32 m0, s43
	s_nop 0
	buffer_load_dwordx4 v133, s[16:19], s57 offen lds
	s_mov_b32 m0, s42
	s_nop 0
	buffer_load_dwordx4 v135, s[16:19], s57 offen lds
	s_mov_b32 m0, s41
	s_nop 0
	buffer_load_dwordx4 v132, s[20:23], s58 offen lds
	s_mov_b32 m0, s33
	s_nop 0
	buffer_load_dwordx4 v134, s[20:23], s58 offen lds
	s_waitcnt vmcnt(8)
	s_waitcnt lgkmcnt(0)
	s_barrier
	s_setprio 1
	v_mfma_f32_16x16x32_bf16 v[60:63], v[142:145], v[174:177], v[60:63]
	v_mfma_f32_16x16x32_bf16 v[52:55], v[150:153], v[174:177], v[52:55]
	v_mfma_f32_16x16x32_bf16 v[44:47], v[142:145], v[182:185], v[44:47]
	v_mfma_f32_16x16x32_bf16 v[36:39], v[150:153], v[182:185], v[36:39]
	v_mfma_f32_16x16x32_bf16 v[28:31], v[142:145], v[190:193], v[28:31]
	v_mfma_f32_16x16x32_bf16 v[20:23], v[150:153], v[190:193], v[20:23]
	v_mfma_f32_16x16x32_bf16 v[12:15], v[142:145], v[200:203], v[12:15]
	v_mfma_f32_16x16x32_bf16 v[2:5], v[150:153], v[200:203], v[2:5]
	v_mfma_f32_16x16x32_bf16 v[60:63], v[146:149], v[178:181], v[60:63]
	v_mfma_f32_16x16x32_bf16 v[52:55], v[154:157], v[178:181], v[52:55]
	v_mfma_f32_16x16x32_bf16 v[44:47], v[146:149], v[186:189], v[44:47]
	v_mfma_f32_16x16x32_bf16 v[36:39], v[154:157], v[186:189], v[36:39]
	v_mfma_f32_16x16x32_bf16 v[28:31], v[146:149], v[194:197], v[28:31]
	v_mfma_f32_16x16x32_bf16 v[20:23], v[154:157], v[194:197], v[20:23]
	v_mfma_f32_16x16x32_bf16 v[12:15], v[146:149], v[204:207], v[12:15]
	v_mfma_f32_16x16x32_bf16 v[4:7], v[154:157], v[204:207], v[2:5]
	v_mfma_f32_16x16x32_bf16 v[72:75], v[158:161], v[174:177], v[72:75]
	v_mfma_f32_16x16x32_bf16 v[56:59], v[166:169], v[174:177], v[56:59]
	v_mfma_f32_16x16x32_bf16 v[48:51], v[158:161], v[182:185], v[48:51]
	v_mfma_f32_16x16x32_bf16 v[40:43], v[166:169], v[182:185], v[40:43]
	v_mfma_f32_16x16x32_bf16 v[32:35], v[158:161], v[190:193], v[32:35]
	v_mfma_f32_16x16x32_bf16 v[24:27], v[166:169], v[190:193], v[24:27]
	v_mfma_f32_16x16x32_bf16 v[16:19], v[158:161], v[200:203], v[16:19]
	v_mfma_f32_16x16x32_bf16 v[8:11], v[166:169], v[200:203], v[8:11]
	v_mfma_f32_16x16x32_bf16 v[72:75], v[162:165], v[178:181], v[72:75]
	v_mfma_f32_16x16x32_bf16 v[56:59], v[170:173], v[178:181], v[56:59]
	v_mfma_f32_16x16x32_bf16 v[48:51], v[162:165], v[186:189], v[48:51]
	v_mfma_f32_16x16x32_bf16 v[40:43], v[170:173], v[186:189], v[40:43]
	v_mfma_f32_16x16x32_bf16 v[32:35], v[162:165], v[194:197], v[32:35]
	v_mfma_f32_16x16x32_bf16 v[24:27], v[170:173], v[194:197], v[24:27]
	v_mfma_f32_16x16x32_bf16 v[16:19], v[162:165], v[204:207], v[16:19]
	v_mfma_f32_16x16x32_bf16 v[8:11], v[170:173], v[204:207], v[8:11]
	s_setprio 0
	s_barrier
	s_add_i32 s54, s54, 2
	s_addk_i32 s55, 0x100
	s_addk_i32 s56, 0x100
	s_cmp_gt_u32 s54, 13
	s_cbranch_scc0 .LBB0_1461
	v_readlane_b32 s12, v251, 45
	v_readlane_b32 s13, v251, 46
	s_and_b64 vcc, exec, s[12:13]
	s_cbranch_vccz .LBB0_1464
	s_barrier

; #define PG8_WAIT_V(n) asm volatile("s_waitcnt vmcnt(" #n ")" ::: "memory")
; template <class Epi, bool ALIGN_EPI, bool SP2, class Hook>
; __device__ __forceinline__ void gemm_phase(LAS unsigned char* lds, const Gemm g, const StaticOrder& S, const Epi& E, Acc& acc, const bool fresh, const Hook& H, const int wave_id) {
;     ...
;         for (int t = t0; t < nt; t += 2) {
;             const bool last = (t == nt - 2);
;             const Src a1 = cA + (size_t)(t + 1) * kstep;
;             const Src a2 = last ? nA : cA + (size_t)(t + 2) * kstep, b2 = last ? nB : cB + (size_t)(t + 2) * kstep;
;             const Src a3 = a2 + kstep, b3 = b2 + kstep;
;             if (last && has_next) H(nxt);
;             if constexpr (SP2) {
;             PG8_TRIP_SP2(PG8_WAIT_V(8));
.LBB0_1572:
	v_add_u32_e32 v142, 0x10000, v161
	v_add_u32_e32 v163, 0x14000, v161
	ds_read_b128 v[130:133], v142
	ds_read_b128 v[134:137], v142 offset:1024
	ds_read_b128 v[138:141], v142 offset:2048
	ds_read_b128 v[142:145], v142 offset:3072
	ds_read_b128 v[146:149], v163
	ds_read_b128 v[150:153], v163 offset:1024
	ds_read_b128 v[154:157], v163 offset:2048
	ds_read_b128 v[164:167], v163 offset:3072
	s_add_i32 s16, s2, 0xfff40080
	s_cmp_eq_u32 s61, 40
	s_cselect_b32 s64, s57, s16
	s_cselect_b32 s17, s35, s9
	s_cselect_b32 s16, s34, s8
	s_cselect_b32 s19, s51, s53
	s_cselect_b32 s18, s50, s52
	s_cselect_b32 s62, s58, s3
	s_cselect_b32 s20, s10, s12
	s_cselect_b32 s21, s11, s13
	s_cselect_b32 s22, s30, s14
	s_cselect_b32 s23, s31, s15
	s_or_b32 s63, s64, 0x80
	s_mov_b32 m0, s45
	ds_read_b128 v[168:171], v162
	ds_read_b128 v[172:175], v162 offset:1024
	ds_read_b128 v[176:179], v162 offset:2048
	ds_read_b128 v[180:183], v162 offset:3072
	ds_read_b128 v[184:187], v162 offset:4096
	ds_read_b128 v[188:191], v162 offset:5120
	ds_read_b128 v[192:195], v162 offset:6144
	ds_read_b128 v[200:203], v162 offset:7168
	buffer_load_dwordx4 v0, s[12:15], s2 offen lds
	s_mov_b32 m0, s46
	s_nop 0
	buffer_load_dwordx4 v159, s[12:15], s2 offen lds
	s_waitcnt vmcnt(8)
	s_waitcnt lgkmcnt(0)
	s_barrier
	s_setprio 1
	v_mfma_f32_16x16x32_bf16 v[126:129], v[130:133], v[168:171], v[126:129]
	v_mfma_f32_16x16x32_bf16 v[122:125], v[138:141], v[168:171], v[122:125]
	v_mfma_f32_16x16x32_bf16 v[110:113], v[130:133], v[176:179], v[110:113]
	v_mfma_f32_16x16x32_bf16 v[106:109], v[138:141], v[176:179], v[106:109]
	v_mfma_f32_16x16x32_bf16 v[94:97], v[130:133], v[184:187], v[94:97]
	v_mfma_f32_16x16x32_bf16 v[90:93], v[138:141], v[184:187], v[90:93]
	v_mfma_f32_16x16x32_bf16 v[78:81], v[130:133], v[192:195], v[78:81]
	v_mfma_f32_16x16x32_bf16 v[74:77], v[138:141], v[192:195], v[74:77]
	v_mfma_f32_16x16x32_bf16 v[126:129], v[134:137], v[172:175], v[126:129]
	v_mfma_f32_16x16x32_bf16 v[122:125], v[142:145], v[172:175], v[122:125]
	v_mfma_f32_16x16x32_bf16 v[110:113], v[134:137], v[180:183], v[110:113]
	v_mfma_f32_16x16x32_bf16 v[106:109], v[142:145], v[180:183], v[106:109]
	v_mfma_f32_16x16x32_bf16 v[94:97], v[134:137], v[188:191], v[94:97]
	v_mfma_f32_16x16x32_bf16 v[90:93], v[142:145], v[188:191], v[90:93]
	v_mfma_f32_16x16x32_bf16 v[78:81], v[134:137], v[200:203], v[78:81]
	v_mfma_f32_16x16x32_bf16 v[74:77], v[142:145], v[200:203], v[74:77]
	v_mfma_f32_16x16x32_bf16 v[118:121], v[146:149], v[168:171], v[118:121]
	v_mfma_f32_16x16x32_bf16 v[114:117], v[154:157], v[168:171], v[114:117]
	v_mfma_f32_16x16x32_bf16 v[102:105], v[146:149], v[176:179], v[102:105]
	v_mfma_f32_16x16x32_bf16 v[98:101], v[154:157], v[176:179], v[98:101]
	v_mfma_f32_16x16x32_bf16 v[86:89], v[146:149], v[184:187], v[86:89]
	v_mfma_f32_16x16x32_bf16 v[82:85], v[154:157], v[184:187], v[82:85]
	v_mfma_f32_16x16x32_bf16 v[70:73], v[146:149], v[192:195], v[70:73]
	v_mfma_f32_16x16x32_bf16 v[66:69], v[154:157], v[192:195], v[66:69]
	v_mfma_f32_16x16x32_bf16 v[118:121], v[150:153], v[172:175], v[118:121]
	v_mfma_f32_16x16x32_bf16 v[114:117], v[164:167], v[172:175], v[114:117]
	v_mfma_f32_16x16x32_bf16 v[102:105], v[150:153], v[180:183], v[102:105]
	v_mfma_f32_16x16x32_bf16 v[98:101], v[164:167], v[180:183], v[98:101]
	v_mfma_f32_16x16x32_bf16 v[86:89], v[150:153], v[188:191], v[86:89]
	v_mfma_f32_16x16x32_bf16 v[82:85], v[164:167], v[188:191], v[82:85]
	v_mfma_f32_16x16x32_bf16 v[70:73], v[150:153], v[200:203], v[70:73]
	v_mfma_f32_16x16x32_bf16 v[66:69], v[164:167], v[200:203], v[66:69]
	s_setprio 0
	s_barrier
	s_mov_b32 m0, s92
	ds_read_b128 v[168:171], v162 offset:16384
	ds_read_b128 v[172:175], v162 offset:17408
	ds_read_b128 v[176:179], v162 offset:18432
	ds_read_b128 v[180:183], v162 offset:19456
	ds_read_b128 v[184:187], v162 offset:20480
	ds_read_b128 v[188:191], v162 offset:21504
	ds_read_b128 v[192:195], v162 offset:22528
	ds_read_b128 v[200:203], v162 offset:23552
	buffer_load_dwordx4 v158, s[16:19], s62 offen lds
	s_mov_b32 m0, s93
	s_add_i32 s65, s62, 0xb0000
	buffer_load_dwordx4 v160, s[16:19], s62 offen lds
	s_mov_b32 m0, s94
	s_nop 0
	buffer_load_dwordx4 v158, s[16:19], s65 offen lds
	s_mov_b32 m0, s95
	s_nop 0
	buffer_load_dwordx4 v160, s[16:19], s65 offen lds
	s_mov_b32 m0, s44
	s_nop 0
	buffer_load_dwordx4 v0, s[20:23], s64 offen lds
	s_mov_b32 m0, s36
	s_nop 0
	buffer_load_dwordx4 v159, s[20:23], s64 offen lds
	s_waitcnt vmcnt(8)
	s_waitcnt lgkmcnt(0)
	s_barrier
	s_setprio 1
	v_mfma_f32_16x16x32_bf16 v[62:65], v[130:133], v[168:171], v[62:65]
	v_mfma_f32_16x16x32_bf16 v[58:61], v[138:141], v[168:171], v[58:61]
	v_mfma_f32_16x16x32_bf16 v[46:49], v[130:133], v[176:179], v[46:49]
	v_mfma_f32_16x16x32_bf16 v[42:45], v[138:141], v[176:179], v[42:45]
	v_mfma_f32_16x16x32_bf16 v[30:33], v[130:133], v[184:187], v[30:33]
	v_mfma_f32_16x16x32_bf16 v[26:29], v[138:141], v[184:187], v[26:29]
	v_mfma_f32_16x16x32_bf16 v[14:17], v[130:133], v[192:195], v[14:17]
	v_mfma_f32_16x16x32_bf16 v[10:13], v[138:141], v[192:195], v[10:13]
	v_mfma_f32_16x16x32_bf16 v[62:65], v[134:137], v[172:175], v[62:65]
	v_mfma_f32_16x16x32_bf16 v[58:61], v[142:145], v[172:175], v[58:61]
	v_mfma_f32_16x16x32_bf16 v[46:49], v[134:137], v[180:183], v[46:49]
	v_mfma_f32_16x16x32_bf16 v[42:45], v[142:145], v[180:183], v[42:45]
	v_mfma_f32_16x16x32_bf16 v[30:33], v[134:137], v[188:191], v[30:33]
	v_mfma_f32_16x16x32_bf16 v[26:29], v[142:145], v[188:191], v[26:29]
	v_mfma_f32_16x16x32_bf16 v[14:17], v[134:137], v[200:203], v[14:17]
	v_mfma_f32_16x16x32_bf16 v[10:13], v[142:145], v[200:203], v[10:13]
	v_mfma_f32_16x16x32_bf16 v[54:57], v[146:149], v[168:171], v[54:57]
	v_mfma_f32_16x16x32_bf16 v[50:53], v[154:157], v[168:171], v[50:53]
	v_mfma_f32_16x16x32_bf16 v[38:41], v[146:149], v[176:179], v[38:41]
	v_mfma_f32_16x16x32_bf16 v[34:37], v[154:157], v[176:179], v[34:37]
	v_mfma_f32_16x16x32_bf16 v[22:25], v[146:149], v[184:187], v[22:25]
	v_mfma_f32_16x16x32_bf16 v[18:21], v[154:157], v[184:187], v[18:21]
	v_mfma_f32_16x16x32_bf16 v[6:9], v[146:149], v[192:195], v[6:9]
	v_mfma_f32_16x16x32_bf16 v[2:5], v[154:157], v[192:195], v[2:5]
	v_mfma_f32_16x16x32_bf16 v[54:57], v[150:153], v[172:175], v[54:57]
	v_mfma_f32_16x16x32_bf16 v[50:53], v[164:167], v[172:175], v[50:53]
	v_mfma_f32_16x16x32_bf16 v[38:41], v[150:153], v[180:183], v[38:41]
	v_mfma_f32_16x16x32_bf16 v[34:37], v[164:167], v[180:183], v[34:37]
	v_mfma_f32_16x16x32_bf16 v[22:25], v[150:153], v[188:191], v[22:25]
	v_mfma_f32_16x16x32_bf16 v[18:21], v[164:167], v[188:191], v[18:21]
	v_mfma_f32_16x16x32_bf16 v[6:9], v[150:153], v[200:203], v[6:9]
	v_mfma_f32_16x16x32_bf16 v[2:5], v[164:167], v[200:203], v[2:5]
	s_setprio 0
	s_barrier
; #define PG8_WAIT_V(n) asm volatile("s_waitcnt vmcnt(" #n ")" ::: "memory")
; template <class Epi, bool ALIGN_EPI, bool SP2, class Hook>
; __device__ __forceinline__ void gemm_phase(LAS unsigned char* lds, const Gemm g, const StaticOrder& S, const Epi& E, Acc& acc, const bool fresh, const Hook& H, const int wave_id) {
;     ...
;         for (int t = t0; t < nt; t += 2) {
;             const bool last = (t == nt - 2);
;             const Src a1 = cA + (size_t)(t + 1) * kstep;
;             const Src a2 = last ? nA : cA + (size_t)(t + 2) * kstep, b2 = last ? nB : cB + (size_t)(t + 2) * kstep;
;             const Src a3 = a2 + kstep, b3 = b2 + kstep;
;             if (last && has_next) H(nxt);
;             if constexpr (SP2) {
;             PG8_TRIP_SP2(PG8_WAIT_V(8));
	v_add_u32_e32 v142, 0x18000, v161
	v_add_u32_e32 v163, 0x1c000, v161
	ds_read_b128 v[130:133], v142
	ds_read_b128 v[134:137], v142 offset:1024
	ds_read_b128 v[138:141], v142 offset:2048
	ds_read_b128 v[142:145], v142 offset:3072
	ds_read_b128 v[146:149], v163
	ds_read_b128 v[150:153], v163 offset:1024
	ds_read_b128 v[154:157], v163 offset:2048
	ds_read_b128 v[164:167], v163 offset:3072
	s_add_i32 s64, s64, 0xc0000
	s_mov_b32 m0, s37
	ds_read_b128 v[168:171], v162 offset:32768
	ds_read_b128 v[172:175], v162 offset:33792
	ds_read_b128 v[176:179], v162 offset:34816
	ds_read_b128 v[180:183], v162 offset:35840
	ds_read_b128 v[184:187], v162 offset:36864
	ds_read_b128 v[188:191], v162 offset:37888
	ds_read_b128 v[192:195], v162 offset:38912
	ds_read_b128 v[200:203], v162 offset:39936
	buffer_load_dwordx4 v0, s[20:23], s64 offen lds
	s_mov_b32 m0, s38
	s_nop 0
	buffer_load_dwordx4 v159, s[20:23], s64 offen lds
	s_waitcnt vmcnt(8)
	s_waitcnt lgkmcnt(0)
	s_barrier
	s_setprio 1
	v_mfma_f32_16x16x32_bf16 v[126:129], v[130:133], v[168:171], v[126:129]
	v_mfma_f32_16x16x32_bf16 v[122:125], v[138:141], v[168:171], v[122:125]
	v_mfma_f32_16x16x32_bf16 v[110:113], v[130:133], v[176:179], v[110:113]
	v_mfma_f32_16x16x32_bf16 v[106:109], v[138:141], v[176:179], v[106:109]
	v_mfma_f32_16x16x32_bf16 v[94:97], v[130:133], v[184:187], v[94:97]
	v_mfma_f32_16x16x32_bf16 v[90:93], v[138:141], v[184:187], v[90:93]
	v_mfma_f32_16x16x32_bf16 v[78:81], v[130:133], v[192:195], v[78:81]
	v_mfma_f32_16x16x32_bf16 v[74:77], v[138:141], v[192:195], v[74:77]
	v_mfma_f32_16x16x32_bf16 v[126:129], v[134:137], v[172:175], v[126:129]
	v_mfma_f32_16x16x32_bf16 v[122:125], v[142:145], v[172:175], v[122:125]
	v_mfma_f32_16x16x32_bf16 v[110:113], v[134:137], v[180:183], v[110:113]
	v_mfma_f32_16x16x32_bf16 v[106:109], v[142:145], v[180:183], v[106:109]
	v_mfma_f32_16x16x32_bf16 v[94:97], v[134:137], v[188:191], v[94:97]
	v_mfma_f32_16x16x32_bf16 v[90:93], v[142:145], v[188:191], v[90:93]
	v_mfma_f32_16x16x32_bf16 v[78:81], v[134:137], v[200:203], v[78:81]
	v_mfma_f32_16x16x32_bf16 v[74:77], v[142:145], v[200:203], v[74:77]
	v_mfma_f32_16x16x32_bf16 v[118:121], v[146:149], v[168:171], v[118:121]
	v_mfma_f32_16x16x32_bf16 v[114:117], v[154:157], v[168:171], v[114:117]
	v_mfma_f32_16x16x32_bf16 v[102:105], v[146:149], v[176:179], v[102:105]
	v_mfma_f32_16x16x32_bf16 v[98:101], v[154:157], v[176:179], v[98:101]
	v_mfma_f32_16x16x32_bf16 v[86:89], v[146:149], v[184:187], v[86:89]
	v_mfma_f32_16x16x32_bf16 v[82:85], v[154:157], v[184:187], v[82:85]
	v_mfma_f32_16x16x32_bf16 v[70:73], v[146:149], v[192:195], v[70:73]
	v_mfma_f32_16x16x32_bf16 v[66:69], v[154:157], v[192:195], v[66:69]
	v_mfma_f32_16x16x32_bf16 v[118:121], v[150:153], v[172:175], v[118:121]
	v_mfma_f32_16x16x32_bf16 v[114:117], v[164:167], v[172:175], v[114:117]
	v_mfma_f32_16x16x32_bf16 v[102:105], v[150:153], v[180:183], v[102:105]
	v_mfma_f32_16x16x32_bf16 v[98:101], v[164:167], v[180:183], v[98:101]
	v_mfma_f32_16x16x32_bf16 v[86:89], v[150:153], v[188:191], v[86:89]
	v_mfma_f32_16x16x32_bf16 v[82:85], v[164:167], v[188:191], v[82:85]
	v_mfma_f32_16x16x32_bf16 v[70:73], v[150:153], v[200:203], v[70:73]
	v_mfma_f32_16x16x32_bf16 v[66:69], v[164:167], v[200:203], v[66:69]
	s_setprio 0
	s_barrier
	s_mov_b32 m0, s39
	s_or_b32 s64, s62, 0x80
	ds_read_b128 v[168:171], v162 offset:49152
	ds_read_b128 v[172:175], v162 offset:50176
	ds_read_b128 v[176:179], v162 offset:51200
	ds_read_b128 v[180:183], v162 offset:52224
	ds_read_b128 v[184:187], v162 offset:53248
	ds_read_b128 v[188:191], v162 offset:54272
	ds_read_b128 v[192:195], v162 offset:55296
	ds_read_b128 v[200:203], v162 offset:56320
	buffer_load_dwordx4 v158, s[16:19], s64 offen lds
	s_mov_b32 m0, s40
	s_add_i32 s62, s62, 0xb0080
	buffer_load_dwordx4 v160, s[16:19], s64 offen lds
	s_mov_b32 m0, s43
	s_nop 0
	buffer_load_dwordx4 v158, s[16:19], s62 offen lds
	s_mov_b32 m0, s42
	s_nop 0
	buffer_load_dwordx4 v160, s[16:19], s62 offen lds
	s_mov_b32 m0, s41
	s_nop 0
	buffer_load_dwordx4 v0, s[20:23], s63 offen lds
	s_mov_b32 m0, s33
	s_nop 0
	buffer_load_dwordx4 v159, s[20:23], s63 offen lds
	s_waitcnt vmcnt(8)
	s_waitcnt lgkmcnt(0)
	s_barrier
	s_setprio 1
	v_mfma_f32_16x16x32_bf16 v[62:65], v[130:133], v[168:171], v[62:65]
	v_mfma_f32_16x16x32_bf16 v[58:61], v[138:141], v[168:171], v[58:61]
	v_mfma_f32_16x16x32_bf16 v[46:49], v[130:133], v[176:179], v[46:49]
	v_mfma_f32_16x16x32_bf16 v[42:45], v[138:141], v[176:179], v[42:45]
	v_mfma_f32_16x16x32_bf16 v[30:33], v[130:133], v[184:187], v[30:33]
	v_mfma_f32_16x16x32_bf16 v[26:29], v[138:141], v[184:187], v[26:29]
	v_mfma_f32_16x16x32_bf16 v[14:17], v[130:133], v[192:195], v[14:17]
	v_mfma_f32_16x16x32_bf16 v[10:13], v[138:141], v[192:195], v[10:13]
	v_mfma_f32_16x16x32_bf16 v[62:65], v[134:137], v[172:175], v[62:65]
	v_mfma_f32_16x16x32_bf16 v[58:61], v[142:145], v[172:175], v[58:61]
	v_mfma_f32_16x16x32_bf16 v[46:49], v[134:137], v[180:183], v[46:49]
	v_mfma_f32_16x16x32_bf16 v[42:45], v[142:145], v[180:183], v[42:45]
	v_mfma_f32_16x16x32_bf16 v[30:33], v[134:137], v[188:191], v[30:33]
	v_mfma_f32_16x16x32_bf16 v[26:29], v[142:145], v[188:191], v[26:29]
	v_mfma_f32_16x16x32_bf16 v[14:17], v[134:137], v[200:203], v[14:17]
	v_mfma_f32_16x16x32_bf16 v[10:13], v[142:145], v[200:203], v[10:13]
	v_mfma_f32_16x16x32_bf16 v[54:57], v[146:149], v[168:171], v[54:57]
	v_mfma_f32_16x16x32_bf16 v[50:53], v[154:157], v[168:171], v[50:53]
	v_mfma_f32_16x16x32_bf16 v[38:41], v[146:149], v[176:179], v[38:41]
	v_mfma_f32_16x16x32_bf16 v[34:37], v[154:157], v[176:179], v[34:37]
	v_mfma_f32_16x16x32_bf16 v[22:25], v[146:149], v[184:187], v[22:25]
	v_mfma_f32_16x16x32_bf16 v[18:21], v[154:157], v[184:187], v[18:21]
	v_mfma_f32_16x16x32_bf16 v[6:9], v[146:149], v[192:195], v[6:9]
	v_mfma_f32_16x16x32_bf16 v[2:5], v[154:157], v[192:195], v[2:5]
	v_mfma_f32_16x16x32_bf16 v[54:57], v[150:153], v[172:175], v[54:57]
	v_mfma_f32_16x16x32_bf16 v[50:53], v[164:167], v[172:175], v[50:53]
	v_mfma_f32_16x16x32_bf16 v[38:41], v[150:153], v[180:183], v[38:41]
	v_mfma_f32_16x16x32_bf16 v[34:37], v[164:167], v[180:183], v[34:37]
	v_mfma_f32_16x16x32_bf16 v[22:25], v[150:153], v[188:191], v[22:25]
	v_mfma_f32_16x16x32_bf16 v[18:21], v[164:167], v[188:191], v[18:21]
	v_mfma_f32_16x16x32_bf16 v[6:9], v[150:153], v[200:203], v[6:9]
	v_mfma_f32_16x16x32_bf16 v[2:5], v[164:167], v[200:203], v[2:5]
	s_setprio 0
	s_barrier
	s_add_i32 s61, s61, 2
	s_addk_i32 s2, 0x100
	s_addk_i32 s3, 0x100
	s_cmp_gt_u32 s61, 41
	s_cbranch_scc0 .LBB0_1572
	v_readlane_b32 s2, v251, 45
	v_readlane_b32 s3, v251, 46
	s_and_b64 vcc, exec, s[2:3]
	s_cbranch_vccz .LBB0_1575
	s_barrier

; #define PG8_WAIT_V(n) asm volatile("s_waitcnt vmcnt(" #n ")" ::: "memory")
; template <class Epi, bool ALIGN_EPI, bool SP2, class Hook>
; __device__ __forceinline__ void gemm_phase(LAS unsigned char* lds, const Gemm g, const StaticOrder& S, const Epi& E, Acc& acc, const bool fresh, const Hook& H, const int wave_id) {
;     ...
;         for (int t = t0; t < nt; t += 2) {
;             const bool last = (t == nt - 2);
;             const Src a1 = cA + (size_t)(t + 1) * kstep;
;             const Src a2 = last ? nA : cA + (size_t)(t + 2) * kstep, b2 = last ? nB : cB + (size_t)(t + 2) * kstep;
;             const Src a3 = a2 + kstep, b3 = b2 + kstep;
;             if (last && has_next) H(nxt);
;             if constexpr (SP2) {
;             PG8_TRIP_SP2(PG8_WAIT_V(8));
.LBB0_1614:
	v_add_u32_e32 v0, 0x10000, v172
	ds_read_b128 v[130:133], v0
	ds_read_b128 v[134:137], v0 offset:1024
	ds_read_b128 v[138:141], v0 offset:2048
	ds_read_b128 v[142:145], v0 offset:3072
	v_add_u32_e32 v0, 0x14000, v172
	ds_read_b128 v[146:149], v0
	ds_read_b128 v[150:153], v0 offset:1024
	ds_read_b128 v[154:157], v0 offset:2048
	ds_read_b128 v[158:161], v0 offset:3072
	s_add_i32 s12, s2, 0xfff40080
	s_cmp_eq_u32 s59, 40
	s_cselect_b32 s62, s55, s12
	s_cselect_b32 s13, s31, s77
	s_cselect_b32 s12, s30, s76
	s_cselect_b32 s15, s35, s51
	s_cselect_b32 s14, s34, s50
	s_cselect_b32 s60, s56, s3
	s_cselect_b32 s16, s20, s8
	s_cselect_b32 s17, s21, s9
	s_cselect_b32 s18, s22, s10
	s_cselect_b32 s19, s23, s11
	s_or_b32 s61, s62, 0x80
	s_mov_b32 m0, s45
	ds_read_b128 v[162:165], v173
	ds_read_b128 v[174:177], v173 offset:1024
	ds_read_b128 v[178:181], v173 offset:2048
	ds_read_b128 v[182:185], v173 offset:3072
	ds_read_b128 v[186:189], v173 offset:4096
	ds_read_b128 v[190:193], v173 offset:5120
	ds_read_b128 v[194:197], v173 offset:6144
	ds_read_b128 v[200:203], v173 offset:7168
	buffer_load_dwordx4 v168, s[8:11], s2 offen lds
	s_mov_b32 m0, s46
	s_nop 0
	buffer_load_dwordx4 v170, s[8:11], s2 offen lds
	s_waitcnt vmcnt(8)
	s_waitcnt lgkmcnt(0)
	s_barrier
	s_setprio 1
	v_mfma_f32_16x16x32_bf16 v[126:129], v[130:133], v[162:165], v[126:129]
	v_mfma_f32_16x16x32_bf16 v[122:125], v[138:141], v[162:165], v[122:125]
	v_mfma_f32_16x16x32_bf16 v[110:113], v[130:133], v[178:181], v[110:113]
	v_mfma_f32_16x16x32_bf16 v[106:109], v[138:141], v[178:181], v[106:109]
	v_mfma_f32_16x16x32_bf16 v[94:97], v[130:133], v[186:189], v[94:97]
	v_mfma_f32_16x16x32_bf16 v[90:93], v[138:141], v[186:189], v[90:93]
	v_mfma_f32_16x16x32_bf16 v[78:81], v[130:133], v[194:197], v[78:81]
	v_mfma_f32_16x16x32_bf16 v[74:77], v[138:141], v[194:197], v[74:77]
	v_mfma_f32_16x16x32_bf16 v[126:129], v[134:137], v[174:177], v[126:129]
	v_mfma_f32_16x16x32_bf16 v[122:125], v[142:145], v[174:177], v[122:125]
	v_mfma_f32_16x16x32_bf16 v[110:113], v[134:137], v[182:185], v[110:113]
	v_mfma_f32_16x16x32_bf16 v[106:109], v[142:145], v[182:185], v[106:109]
	v_mfma_f32_16x16x32_bf16 v[94:97], v[134:137], v[190:193], v[94:97]
	v_mfma_f32_16x16x32_bf16 v[90:93], v[142:145], v[190:193], v[90:93]
	v_mfma_f32_16x16x32_bf16 v[78:81], v[134:137], v[200:203], v[78:81]
	v_mfma_f32_16x16x32_bf16 v[74:77], v[142:145], v[200:203], v[74:77]
	v_mfma_f32_16x16x32_bf16 v[118:121], v[146:149], v[162:165], v[118:121]
	v_mfma_f32_16x16x32_bf16 v[114:117], v[154:157], v[162:165], v[114:117]
	v_mfma_f32_16x16x32_bf16 v[102:105], v[146:149], v[178:181], v[102:105]
	v_mfma_f32_16x16x32_bf16 v[98:101], v[154:157], v[178:181], v[98:101]
	v_mfma_f32_16x16x32_bf16 v[86:89], v[146:149], v[186:189], v[86:89]
	v_mfma_f32_16x16x32_bf16 v[82:85], v[154:157], v[186:189], v[82:85]
	v_mfma_f32_16x16x32_bf16 v[70:73], v[146:149], v[194:197], v[70:73]
	v_mfma_f32_16x16x32_bf16 v[66:69], v[154:157], v[194:197], v[66:69]
	v_mfma_f32_16x16x32_bf16 v[118:121], v[150:153], v[174:177], v[118:121]
	v_mfma_f32_16x16x32_bf16 v[114:117], v[158:161], v[174:177], v[114:117]
	v_mfma_f32_16x16x32_bf16 v[102:105], v[150:153], v[182:185], v[102:105]
	v_mfma_f32_16x16x32_bf16 v[98:101], v[158:161], v[182:185], v[98:101]
	v_mfma_f32_16x16x32_bf16 v[86:89], v[150:153], v[190:193], v[86:89]
	v_mfma_f32_16x16x32_bf16 v[82:85], v[158:161], v[190:193], v[82:85]
	v_mfma_f32_16x16x32_bf16 v[70:73], v[150:153], v[200:203], v[70:73]
	v_mfma_f32_16x16x32_bf16 v[66:69], v[158:161], v[200:203], v[66:69]
	s_setprio 0
	s_barrier
	s_mov_b32 m0, s92
	ds_read_b128 v[162:165], v173 offset:16384
	ds_read_b128 v[174:177], v173 offset:17408
	ds_read_b128 v[178:181], v173 offset:18432
	ds_read_b128 v[182:185], v173 offset:19456
	ds_read_b128 v[186:189], v173 offset:20480
	ds_read_b128 v[190:193], v173 offset:21504
	ds_read_b128 v[194:197], v173 offset:22528
	ds_read_b128 v[200:203], v173 offset:23552
	buffer_load_dwordx4 v169, s[12:15], s60 offen lds
	s_mov_b32 m0, s93
	s_add_i32 s63, s60, 0xb0000
	buffer_load_dwordx4 v171, s[12:15], s60 offen lds
	s_mov_b32 m0, s94
	s_nop 0
	buffer_load_dwordx4 v169, s[12:15], s63 offen lds
	s_mov_b32 m0, s95
	s_nop 0
	buffer_load_dwordx4 v171, s[12:15], s63 offen lds
	s_mov_b32 m0, s44
	s_nop 0
	buffer_load_dwordx4 v168, s[16:19], s62 offen lds
	s_mov_b32 m0, s36
	s_nop 0
	buffer_load_dwordx4 v170, s[16:19], s62 offen lds
	s_waitcnt vmcnt(8)
	s_waitcnt lgkmcnt(0)
	s_barrier
	s_setprio 1
	v_mfma_f32_16x16x32_bf16 v[62:65], v[130:133], v[162:165], v[62:65]
	v_mfma_f32_16x16x32_bf16 v[58:61], v[138:141], v[162:165], v[58:61]
	v_mfma_f32_16x16x32_bf16 v[46:49], v[130:133], v[178:181], v[46:49]
	v_mfma_f32_16x16x32_bf16 v[42:45], v[138:141], v[178:181], v[42:45]
	v_mfma_f32_16x16x32_bf16 v[30:33], v[130:133], v[186:189], v[30:33]
	v_mfma_f32_16x16x32_bf16 v[26:29], v[138:141], v[186:189], v[26:29]
	v_mfma_f32_16x16x32_bf16 v[14:17], v[130:133], v[194:197], v[14:17]
	v_mfma_f32_16x16x32_bf16 v[10:13], v[138:141], v[194:197], v[10:13]
	v_mfma_f32_16x16x32_bf16 v[62:65], v[134:137], v[174:177], v[62:65]
	v_mfma_f32_16x16x32_bf16 v[58:61], v[142:145], v[174:177], v[58:61]
	v_mfma_f32_16x16x32_bf16 v[46:49], v[134:137], v[182:185], v[46:49]
	v_mfma_f32_16x16x32_bf16 v[42:45], v[142:145], v[182:185], v[42:45]
	v_mfma_f32_16x16x32_bf16 v[30:33], v[134:137], v[190:193], v[30:33]
	v_mfma_f32_16x16x32_bf16 v[26:29], v[142:145], v[190:193], v[26:29]
	v_mfma_f32_16x16x32_bf16 v[14:17], v[134:137], v[200:203], v[14:17]
	v_mfma_f32_16x16x32_bf16 v[10:13], v[142:145], v[200:203], v[10:13]
	v_mfma_f32_16x16x32_bf16 v[54:57], v[146:149], v[162:165], v[54:57]
	v_mfma_f32_16x16x32_bf16 v[50:53], v[154:157], v[162:165], v[50:53]
	v_mfma_f32_16x16x32_bf16 v[38:41], v[146:149], v[178:181], v[38:41]
	v_mfma_f32_16x16x32_bf16 v[34:37], v[154:157], v[178:181], v[34:37]
	v_mfma_f32_16x16x32_bf16 v[22:25], v[146:149], v[186:189], v[22:25]
	v_mfma_f32_16x16x32_bf16 v[18:21], v[154:157], v[186:189], v[18:21]
	v_mfma_f32_16x16x32_bf16 v[6:9], v[146:149], v[194:197], v[6:9]
	v_mfma_f32_16x16x32_bf16 v[2:5], v[154:157], v[194:197], v[2:5]
	v_mfma_f32_16x16x32_bf16 v[54:57], v[150:153], v[174:177], v[54:57]
	v_mfma_f32_16x16x32_bf16 v[50:53], v[158:161], v[174:177], v[50:53]
	v_mfma_f32_16x16x32_bf16 v[38:41], v[150:153], v[182:185], v[38:41]
	v_mfma_f32_16x16x32_bf16 v[34:37], v[158:161], v[182:185], v[34:37]
	v_mfma_f32_16x16x32_bf16 v[22:25], v[150:153], v[190:193], v[22:25]
	v_mfma_f32_16x16x32_bf16 v[18:21], v[158:161], v[190:193], v[18:21]
	v_mfma_f32_16x16x32_bf16 v[6:9], v[150:153], v[200:203], v[6:9]
	v_mfma_f32_16x16x32_bf16 v[2:5], v[158:161], v[200:203], v[2:5]
	s_setprio 0
	s_barrier
; #define PG8_WAIT_V(n) asm volatile("s_waitcnt vmcnt(" #n ")" ::: "memory")
; template <class Epi, bool ALIGN_EPI, bool SP2, class Hook>
; __device__ __forceinline__ void gemm_phase(LAS unsigned char* lds, const Gemm g, const StaticOrder& S, const Epi& E, Acc& acc, const bool fresh, const Hook& H, const int wave_id) {
;     ...
;         for (int t = t0; t < nt; t += 2) {
;             const bool last = (t == nt - 2);
;             const Src a1 = cA + (size_t)(t + 1) * kstep;
;             const Src a2 = last ? nA : cA + (size_t)(t + 2) * kstep, b2 = last ? nB : cB + (size_t)(t + 2) * kstep;
;             const Src a3 = a2 + kstep, b3 = b2 + kstep;
;             if (last && has_next) H(nxt);
;             if constexpr (SP2) {
;             PG8_TRIP_SP2(PG8_WAIT_V(8));
	v_add_u32_e32 v0, 0x18000, v172
	ds_read_b128 v[130:133], v0
	ds_read_b128 v[134:137], v0 offset:1024
	ds_read_b128 v[138:141], v0 offset:2048
	ds_read_b128 v[142:145], v0 offset:3072
	v_add_u32_e32 v0, 0x1c000, v172
	ds_read_b128 v[146:149], v0
	ds_read_b128 v[150:153], v0 offset:1024
	ds_read_b128 v[154:157], v0 offset:2048
	ds_read_b128 v[158:161], v0 offset:3072
	s_add_i32 s62, s62, 0xc0000
	s_mov_b32 m0, s37
	ds_read_b128 v[162:165], v173 offset:32768
	ds_read_b128 v[174:177], v173 offset:33792
	ds_read_b128 v[178:181], v173 offset:34816
	ds_read_b128 v[182:185], v173 offset:35840
	ds_read_b128 v[186:189], v173 offset:36864
	ds_read_b128 v[190:193], v173 offset:37888
	ds_read_b128 v[194:197], v173 offset:38912
	ds_read_b128 v[200:203], v173 offset:39936
	buffer_load_dwordx4 v168, s[16:19], s62 offen lds
	s_mov_b32 m0, s38
	s_nop 0
	buffer_load_dwordx4 v170, s[16:19], s62 offen lds
	s_waitcnt vmcnt(8)
	s_waitcnt lgkmcnt(0)
	s_barrier
	s_setprio 1
	v_mfma_f32_16x16x32_bf16 v[126:129], v[130:133], v[162:165], v[126:129]
	v_mfma_f32_16x16x32_bf16 v[122:125], v[138:141], v[162:165], v[122:125]
	v_mfma_f32_16x16x32_bf16 v[110:113], v[130:133], v[178:181], v[110:113]
	v_mfma_f32_16x16x32_bf16 v[106:109], v[138:141], v[178:181], v[106:109]
	v_mfma_f32_16x16x32_bf16 v[94:97], v[130:133], v[186:189], v[94:97]
	v_mfma_f32_16x16x32_bf16 v[90:93], v[138:141], v[186:189], v[90:93]
	v_mfma_f32_16x16x32_bf16 v[78:81], v[130:133], v[194:197], v[78:81]
	v_mfma_f32_16x16x32_bf16 v[74:77], v[138:141], v[194:197], v[74:77]
	v_mfma_f32_16x16x32_bf16 v[126:129], v[134:137], v[174:177], v[126:129]
	v_mfma_f32_16x16x32_bf16 v[122:125], v[142:145], v[174:177], v[122:125]
	v_mfma_f32_16x16x32_bf16 v[110:113], v[134:137], v[182:185], v[110:113]
	v_mfma_f32_16x16x32_bf16 v[106:109], v[142:145], v[182:185], v[106:109]
	v_mfma_f32_16x16x32_bf16 v[94:97], v[134:137], v[190:193], v[94:97]
	v_mfma_f32_16x16x32_bf16 v[90:93], v[142:145], v[190:193], v[90:93]
	v_mfma_f32_16x16x32_bf16 v[78:81], v[134:137], v[200:203], v[78:81]
	v_mfma_f32_16x16x32_bf16 v[74:77], v[142:145], v[200:203], v[74:77]
	v_mfma_f32_16x16x32_bf16 v[118:121], v[146:149], v[162:165], v[118:121]
	v_mfma_f32_16x16x32_bf16 v[114:117], v[154:157], v[162:165], v[114:117]
	v_mfma_f32_16x16x32_bf16 v[102:105], v[146:149], v[178:181], v[102:105]
	v_mfma_f32_16x16x32_bf16 v[98:101], v[154:157], v[178:181], v[98:101]
	v_mfma_f32_16x16x32_bf16 v[86:89], v[146:149], v[186:189], v[86:89]
	v_mfma_f32_16x16x32_bf16 v[82:85], v[154:157], v[186:189], v[82:85]
	v_mfma_f32_16x16x32_bf16 v[70:73], v[146:149], v[194:197], v[70:73]
	v_mfma_f32_16x16x32_bf16 v[66:69], v[154:157], v[194:197], v[66:69]
	v_mfma_f32_16x16x32_bf16 v[118:121], v[150:153], v[174:177], v[118:121]
	v_mfma_f32_16x16x32_bf16 v[114:117], v[158:161], v[174:177], v[114:117]
	v_mfma_f32_16x16x32_bf16 v[102:105], v[150:153], v[182:185], v[102:105]
	v_mfma_f32_16x16x32_bf16 v[98:101], v[158:161], v[182:185], v[98:101]
	v_mfma_f32_16x16x32_bf16 v[86:89], v[150:153], v[190:193], v[86:89]
	v_mfma_f32_16x16x32_bf16 v[82:85], v[158:161], v[190:193], v[82:85]
	v_mfma_f32_16x16x32_bf16 v[70:73], v[150:153], v[200:203], v[70:73]
	v_mfma_f32_16x16x32_bf16 v[66:69], v[158:161], v[200:203], v[66:69]
	s_setprio 0
	s_barrier
	s_mov_b32 m0, s39
	s_or_b32 s62, s60, 0x80
	ds_read_b128 v[162:165], v173 offset:49152
	ds_read_b128 v[174:177], v173 offset:50176
	ds_read_b128 v[178:181], v173 offset:51200
	ds_read_b128 v[182:185], v173 offset:52224
	ds_read_b128 v[186:189], v173 offset:53248
	ds_read_b128 v[190:193], v173 offset:54272
	ds_read_b128 v[194:197], v173 offset:55296
	ds_read_b128 v[200:203], v173 offset:56320
	buffer_load_dwordx4 v169, s[12:15], s62 offen lds
	s_mov_b32 m0, s40
	s_add_i32 s60, s60, 0xb0080
	buffer_load_dwordx4 v171, s[12:15], s62 offen lds
	s_mov_b32 m0, s43
	s_nop 0
	buffer_load_dwordx4 v169, s[12:15], s60 offen lds
	s_mov_b32 m0, s42
	s_nop 0
	buffer_load_dwordx4 v171, s[12:15], s60 offen lds
	s_mov_b32 m0, s41
	s_nop 0
	buffer_load_dwordx4 v168, s[16:19], s61 offen lds
	s_mov_b32 m0, s33
	s_nop 0
	buffer_load_dwordx4 v170, s[16:19], s61 offen lds
	s_waitcnt vmcnt(8)
	s_waitcnt lgkmcnt(0)
	s_barrier
	s_setprio 1
	v_mfma_f32_16x16x32_bf16 v[62:65], v[130:133], v[162:165], v[62:65]
	v_mfma_f32_16x16x32_bf16 v[58:61], v[138:141], v[162:165], v[58:61]
	v_mfma_f32_16x16x32_bf16 v[46:49], v[130:133], v[178:181], v[46:49]
	v_mfma_f32_16x16x32_bf16 v[42:45], v[138:141], v[178:181], v[42:45]
	v_mfma_f32_16x16x32_bf16 v[30:33], v[130:133], v[186:189], v[30:33]
	v_mfma_f32_16x16x32_bf16 v[26:29], v[138:141], v[186:189], v[26:29]
	v_mfma_f32_16x16x32_bf16 v[14:17], v[130:133], v[194:197], v[14:17]
	v_mfma_f32_16x16x32_bf16 v[10:13], v[138:141], v[194:197], v[10:13]
	v_mfma_f32_16x16x32_bf16 v[62:65], v[134:137], v[174:177], v[62:65]
	v_mfma_f32_16x16x32_bf16 v[58:61], v[142:145], v[174:177], v[58:61]
	v_mfma_f32_16x16x32_bf16 v[46:49], v[134:137], v[182:185], v[46:49]
	v_mfma_f32_16x16x32_bf16 v[42:45], v[142:145], v[182:185], v[42:45]
	v_mfma_f32_16x16x32_bf16 v[30:33], v[134:137], v[190:193], v[30:33]
	v_mfma_f32_16x16x32_bf16 v[26:29], v[142:145], v[190:193], v[26:29]
	v_mfma_f32_16x16x32_bf16 v[14:17], v[134:137], v[200:203], v[14:17]
	v_mfma_f32_16x16x32_bf16 v[10:13], v[142:145], v[200:203], v[10:13]
	v_mfma_f32_16x16x32_bf16 v[54:57], v[146:149], v[162:165], v[54:57]
	v_mfma_f32_16x16x32_bf16 v[50:53], v[154:157], v[162:165], v[50:53]
	v_mfma_f32_16x16x32_bf16 v[38:41], v[146:149], v[178:181], v[38:41]
	v_mfma_f32_16x16x32_bf16 v[34:37], v[154:157], v[178:181], v[34:37]
	v_mfma_f32_16x16x32_bf16 v[22:25], v[146:149], v[186:189], v[22:25]
	v_mfma_f32_16x16x32_bf16 v[18:21], v[154:157], v[186:189], v[18:21]
	v_mfma_f32_16x16x32_bf16 v[6:9], v[146:149], v[194:197], v[6:9]
	v_mfma_f32_16x16x32_bf16 v[2:5], v[154:157], v[194:197], v[2:5]
	v_mfma_f32_16x16x32_bf16 v[54:57], v[150:153], v[174:177], v[54:57]
	v_mfma_f32_16x16x32_bf16 v[50:53], v[158:161], v[174:177], v[50:53]
	v_mfma_f32_16x16x32_bf16 v[38:41], v[150:153], v[182:185], v[38:41]
	v_mfma_f32_16x16x32_bf16 v[34:37], v[158:161], v[182:185], v[34:37]
	v_mfma_f32_16x16x32_bf16 v[22:25], v[150:153], v[190:193], v[22:25]
	v_mfma_f32_16x16x32_bf16 v[18:21], v[158:161], v[190:193], v[18:21]
	v_mfma_f32_16x16x32_bf16 v[6:9], v[150:153], v[200:203], v[6:9]
	v_mfma_f32_16x16x32_bf16 v[2:5], v[158:161], v[200:203], v[2:5]
	s_setprio 0
	s_barrier
	s_add_i32 s59, s59, 2
	s_addk_i32 s2, 0x100
	s_addk_i32 s3, 0x100
	s_cmp_gt_u32 s59, 41
	s_cbranch_scc0 .LBB0_1614
	v_readlane_b32 s2, v251, 45
	v_readlane_b32 s3, v251, 46
	s_and_b64 vcc, exec, s[2:3]
	s_cbranch_vccz .LBB0_1617
	s_barrier
